# GEMM super-phases: s_setprio 1 moved above the barrier that opens each MFMA block and s_setprio 0 below the barrier that closes it (28+28 sites), taking both off the MFMA critical path
# baseline (speedup 1.0000x reference)
; #define PG8_STAGE(bufoff, gbase, voff) do { _Pragma("unroll") for (int _i = 0; _i < 2; ++_i) \
;         __builtin_amdgcn_global_load_lds((const unsigned*)((const char*)(gbase) + (voff)[_i]), (PG8_LAS unsigned*)(lds + (bufoff) + ldsw + _i * 8192), 16, 0, 0); } while (0)
; #define PG8_LDA(dst, b, h) do { _Pragma("unroll") for (int m = 0; m < 4; ++m) _Pragma("unroll") for (int k = 0; k < 2; ++k) dst[m][k] = *(const PG8_LAS bf16x8*)(lds + PG8_SA(b, h) + aoff + m * 2048 + k * 1024); } while (0)
; #define PG8_LDB(dst, b, h) do { _Pragma("unroll") for (int n = 0; n < 2; ++n) _Pragma("unroll") for (int k = 0; k < 2; ++k) dst[n][k] = *(const PG8_LAS bf16x8*)(lds + PG8_SB(b, h) + boff + n * 2048 + k * 1024); } while (0)
; #define PG8_MMA(ai, bj, At, Bt) do { __builtin_amdgcn_s_setprio(1); _Pragma("unroll") for (int m = 0; m < 4; ++m) _Pragma("unroll") for (int n = 0; n < 2; ++n) _Pragma("unroll") for (int k = 0; k < 2; ++k) \
;         acc[ai][bj][m][n] = __builtin_amdgcn_mfma_f32_16x16x32_bf16(Bt[n][k], At[m][k], acc[ai][bj][m][n], 0, 0, 0); __builtin_amdgcn_s_setprio(0); } while (0)
; #define PG8_WAIT_V(n) asm volatile("s_waitcnt vmcnt(" #n ")" ::: "memory")
; #define PG8_WAIT_L(n) asm volatile("s_waitcnt lgkmcnt(" #n ")" ::: "memory")
; template <class Epi, class Sched, bool ALIGN_EPI = false, bool SP2 = false>
; __device__ __forceinline__ void gemm_phase(PG8_LAS unsigned char* lds, const Gemm g, const Sched& S, const Epi& E) {
;     ...
;             const bool last = (t == nt - 2);
;             const char* a1 = cA + (size_t)(t + 1) * kstep;
;             const char* a2 = last ? nA : cA + (size_t)(t + 2) * kstep; const char* b2 = last ? nB : cB + (size_t)(t + 2) * kstep;
;             const char* a3 = a2 + kstep; const char* b3 = b2 + kstep;
;             if (last && has_next) S.a_ready(nxt);
;             if constexpr (SP2) {
;             PG8_LDB(B0, 0, 0); PG8_LDB(B1, 0, 1); PG8_SCHED; PG8_LDA(At, 0, 0); PG8_STAGE(PG8_SA(1, 1), a1 + hstep, voffA);
;             PG8_WAIT_V(8); PG8_WAIT_L(0); PG8_BAR; PG8_MMA(0, 0, At, B0); PG8_MMA(0, 1, At, B1); PG8_BAR; PG8_SCHED;
;             PG8_LDA(At, 0, 1); PG8_STAGE(PG8_SB(0, 0), b2, voffB); PG8_STAGE(PG8_SB(0, 1), b2 + hstep, voffB); PG8_STAGE(PG8_SA(0, 0), a2, voffA);
;             PG8_WAIT_V(8); PG8_WAIT_L(0); PG8_BAR; PG8_MMA(1, 0, At, B0); PG8_MMA(1, 1, At, B1); PG8_BAR; PG8_SCHED;
.LBB0_301:
	s_add_u32 s26, s24, 0xfffc0080
	s_addc_u32 s27, s25, -1
	s_add_i32 s48, 0, 0x10000
	s_cmp_eq_u32 s47, 12
	s_cselect_b32 s29, s13, s27
	s_cselect_b32 s28, s21, s26
	v_add_u32_e32 v154, s48, v156
	s_cselect_b32 s27, s11, s46
	s_cselect_b32 s26, s44, s45
	s_add_i32 s50, 0, 0x14000
	ds_read_b128 v[94:97], v154
	ds_read_b128 v[134:137], v154 offset:1024
	ds_read_b128 v[158:161], v154 offset:2048
	ds_read_b128 v[162:165], v154 offset:3072
	v_add_u32_e32 v154, s50, v156
	ds_read_b128 v[166:169], v154
	ds_read_b128 v[170:173], v154 offset:1024
	ds_read_b128 v[174:177], v154 offset:2048
	ds_read_b128 v[186:189], v154 offset:3072
	v_lshl_add_u64 v[154:155], s[24:25], 0, v[150:151]
	s_add_i32 m0, s23, 0xc000
	ds_read_b128 v[190:193], v157
	ds_read_b128 v[194:197], v157 offset:1024
	ds_read_b128 v[198:201], v157 offset:2048
	ds_read_b128 v[202:205], v157 offset:3072
	ds_read_b128 v[206:209], v157 offset:4096
	ds_read_b128 v[210:213], v157 offset:5120
	ds_read_b128 v[214:217], v157 offset:6144
	ds_read_b128 v[218:221], v157 offset:7168
	global_load_lds_dwordx4 v[154:155], off
	v_lshl_add_u64 v[154:155], s[24:25], 0, v[152:153]
	s_add_i32 m0, s23, 0xe000
	s_nop 0
	global_load_lds_dwordx4 v[154:155], off
	s_waitcnt vmcnt(8)
	s_waitcnt lgkmcnt(0)
	s_setprio 1
	s_barrier
	v_mfma_f32_16x16x32_bf16 v[130:133], v[94:97], v[190:193], v[130:133]
	v_mfma_f32_16x16x32_bf16 v[126:129], v[158:161], v[190:193], v[126:129]
	v_mfma_f32_16x16x32_bf16 v[114:117], v[94:97], v[198:201], v[114:117]
	v_mfma_f32_16x16x32_bf16 v[110:113], v[158:161], v[198:201], v[110:113]
	v_mfma_f32_16x16x32_bf16 v[98:101], v[94:97], v[206:209], v[98:101]
	v_mfma_f32_16x16x32_bf16 v[90:93], v[158:161], v[206:209], v[90:93]
	v_mfma_f32_16x16x32_bf16 v[78:81], v[94:97], v[214:217], v[78:81]
	v_mfma_f32_16x16x32_bf16 v[74:77], v[158:161], v[214:217], v[74:77]
	v_mfma_f32_16x16x32_bf16 v[130:133], v[134:137], v[194:197], v[130:133]
	v_mfma_f32_16x16x32_bf16 v[126:129], v[162:165], v[194:197], v[126:129]
	v_mfma_f32_16x16x32_bf16 v[114:117], v[134:137], v[202:205], v[114:117]
	v_mfma_f32_16x16x32_bf16 v[110:113], v[162:165], v[202:205], v[110:113]
	v_mfma_f32_16x16x32_bf16 v[98:101], v[134:137], v[210:213], v[98:101]
	v_mfma_f32_16x16x32_bf16 v[90:93], v[162:165], v[210:213], v[90:93]
	v_mfma_f32_16x16x32_bf16 v[78:81], v[134:137], v[218:221], v[78:81]
	v_mfma_f32_16x16x32_bf16 v[74:77], v[162:165], v[218:221], v[74:77]
	s_setprio 0
	s_setprio 1
	v_mfma_f32_16x16x32_bf16 v[122:125], v[166:169], v[190:193], v[122:125]
	v_mfma_f32_16x16x32_bf16 v[118:121], v[174:177], v[190:193], v[118:121]
	v_mfma_f32_16x16x32_bf16 v[106:109], v[166:169], v[198:201], v[106:109]
	v_mfma_f32_16x16x32_bf16 v[102:105], v[174:177], v[198:201], v[102:105]
	v_mfma_f32_16x16x32_bf16 v[86:89], v[166:169], v[206:209], v[86:89]
	v_mfma_f32_16x16x32_bf16 v[82:85], v[174:177], v[206:209], v[82:85]
	v_mfma_f32_16x16x32_bf16 v[70:73], v[166:169], v[214:217], v[70:73]
	v_mfma_f32_16x16x32_bf16 v[66:69], v[174:177], v[214:217], v[66:69]
	v_mfma_f32_16x16x32_bf16 v[122:125], v[170:173], v[194:197], v[122:125]
	v_mfma_f32_16x16x32_bf16 v[118:121], v[186:189], v[194:197], v[118:121]
	v_mfma_f32_16x16x32_bf16 v[106:109], v[170:173], v[202:205], v[106:109]
	v_mfma_f32_16x16x32_bf16 v[102:105], v[186:189], v[202:205], v[102:105]
	v_mfma_f32_16x16x32_bf16 v[86:89], v[170:173], v[210:213], v[86:89]
	v_mfma_f32_16x16x32_bf16 v[82:85], v[186:189], v[210:213], v[82:85]
	v_mfma_f32_16x16x32_bf16 v[70:73], v[170:173], v[218:221], v[70:73]
	v_mfma_f32_16x16x32_bf16 v[66:69], v[186:189], v[218:221], v[66:69]
	s_barrier
	s_setprio 0
	s_add_i32 s48, s48, s35
	v_lshl_add_u64 v[154:155], s[26:27], 0, v[142:143]
	s_mov_b32 m0, s48
	ds_read_b128 v[190:193], v157 offset:16384
	ds_read_b128 v[194:197], v157 offset:17408
	ds_read_b128 v[198:201], v157 offset:18432
	ds_read_b128 v[202:205], v157 offset:19456
	ds_read_b128 v[206:209], v157 offset:20480
	ds_read_b128 v[210:213], v157 offset:21504
	ds_read_b128 v[214:217], v157 offset:22528
	ds_read_b128 v[218:221], v157 offset:23552
	global_load_lds_dwordx4 v[154:155], off
	s_add_i32 m0, s48, 0x2000
	s_add_u32 s48, s26, 0x40000
	v_lshl_add_u64 v[180:181], s[26:27], 0, v[138:139]
	s_addc_u32 s49, s27, 0
	s_add_i32 s50, s50, s35
	global_load_lds_dwordx4 v[180:181], off
	v_lshl_add_u64 v[182:183], s[48:49], 0, v[142:143]
	s_mov_b32 m0, s50
	v_lshl_add_u64 v[222:223], s[28:29], 0, v[140:141]
	global_load_lds_dwordx4 v[182:183], off
	v_lshl_add_u64 v[182:183], s[48:49], 0, v[138:139]
	s_add_i32 m0, s50, 0x2000
	s_nop 0
	global_load_lds_dwordx4 v[182:183], off
	v_lshl_add_u64 v[182:183], s[28:29], 0, v[144:145]
	s_mov_b32 m0, s23
	s_nop 0
	global_load_lds_dwordx4 v[182:183], off
	s_mov_b32 m0, s37
	s_nop 0
	global_load_lds_dwordx4 v[222:223], off
	s_waitcnt vmcnt(8)
	s_waitcnt lgkmcnt(0)
	s_setprio 1
	s_barrier
; #define PG8_STAGE(bufoff, gbase, voff) do { _Pragma("unroll") for (int _i = 0; _i < 2; ++_i) \
;         __builtin_amdgcn_global_load_lds((const unsigned*)((const char*)(gbase) + (voff)[_i]), (PG8_LAS unsigned*)(lds + (bufoff) + ldsw + _i * 8192), 16, 0, 0); } while (0)
; #define PG8_LDA(dst, b, h) do { _Pragma("unroll") for (int m = 0; m < 4; ++m) _Pragma("unroll") for (int k = 0; k < 2; ++k) dst[m][k] = *(const PG8_LAS bf16x8*)(lds + PG8_SA(b, h) + aoff + m * 2048 + k * 1024); } while (0)
; #define PG8_LDB(dst, b, h) do { _Pragma("unroll") for (int n = 0; n < 2; ++n) _Pragma("unroll") for (int k = 0; k < 2; ++k) dst[n][k] = *(const PG8_LAS bf16x8*)(lds + PG8_SB(b, h) + boff + n * 2048 + k * 1024); } while (0)
; #define PG8_MMA(ai, bj, At, Bt) do { __builtin_amdgcn_s_setprio(1); _Pragma("unroll") for (int m = 0; m < 4; ++m) _Pragma("unroll") for (int n = 0; n < 2; ++n) _Pragma("unroll") for (int k = 0; k < 2; ++k) \
;         acc[ai][bj][m][n] = __builtin_amdgcn_mfma_f32_16x16x32_bf16(Bt[n][k], At[m][k], acc[ai][bj][m][n], 0, 0, 0); __builtin_amdgcn_s_setprio(0); } while (0)
; #define PG8_WAIT_V(n) asm volatile("s_waitcnt vmcnt(" #n ")" ::: "memory")
; #define PG8_WAIT_L(n) asm volatile("s_waitcnt lgkmcnt(" #n ")" ::: "memory")
; #define PG8_BAR __builtin_amdgcn_s_barrier()
; #define PG8_SCHED __builtin_amdgcn_sched_barrier(0)
; template <class Epi, class Sched, bool ALIGN_EPI = false, bool SP2 = false>
; __device__ __forceinline__ void gemm_phase(PG8_LAS unsigned char* lds, const Gemm g, const Sched& S, const Epi& E) {
;     ...
;             PG8_WAIT_V(8); PG8_WAIT_L(0); PG8_BAR; PG8_MMA(1, 0, At, B0); PG8_MMA(1, 1, At, B1); PG8_BAR; PG8_SCHED;
;             PG8_LDB(B0, 1, 0); PG8_LDB(B1, 1, 1); PG8_SCHED; PG8_LDA(At, 1, 0); PG8_STAGE(PG8_SA(0, 1), a2 + hstep, voffA);
;             PG8_WAIT_V(8); PG8_WAIT_L(0); PG8_BAR; PG8_MMA(0, 0, At, B0); PG8_MMA(0, 1, At, B1); PG8_BAR; PG8_SCHED;
;             PG8_LDA(At, 1, 1); PG8_STAGE(PG8_SB(1, 0), b3, voffB); PG8_STAGE(PG8_SB(1, 1), b3 + hstep, voffB); PG8_STAGE(PG8_SA(1, 0), a3, voffA);
;             PG8_WAIT_V(8); PG8_WAIT_L(0); PG8_BAR; PG8_MMA(1, 0, At, B0); PG8_MMA(1, 1, At, B1); PG8_BAR; PG8_SCHED;
	v_mfma_f32_16x16x32_bf16 v[62:65], v[94:97], v[190:193], v[62:65]
	v_mfma_f32_16x16x32_bf16 v[58:61], v[158:161], v[190:193], v[58:61]
	v_mfma_f32_16x16x32_bf16 v[50:53], v[94:97], v[198:201], v[50:53]
	v_mfma_f32_16x16x32_bf16 v[42:45], v[158:161], v[198:201], v[42:45]
	v_mfma_f32_16x16x32_bf16 v[34:37], v[94:97], v[206:209], v[34:37]
	v_mfma_f32_16x16x32_bf16 v[26:29], v[158:161], v[206:209], v[26:29]
	v_mfma_f32_16x16x32_bf16 v[18:21], v[94:97], v[214:217], v[18:21]
	v_mfma_f32_16x16x32_bf16 v[10:13], v[158:161], v[214:217], v[10:13]
	v_mfma_f32_16x16x32_bf16 v[62:65], v[134:137], v[194:197], v[62:65]
	v_mfma_f32_16x16x32_bf16 v[58:61], v[162:165], v[194:197], v[58:61]
	v_mfma_f32_16x16x32_bf16 v[50:53], v[134:137], v[202:205], v[50:53]
	v_mfma_f32_16x16x32_bf16 v[42:45], v[162:165], v[202:205], v[42:45]
	v_mfma_f32_16x16x32_bf16 v[34:37], v[134:137], v[210:213], v[34:37]
	v_mfma_f32_16x16x32_bf16 v[26:29], v[162:165], v[210:213], v[26:29]
	v_mfma_f32_16x16x32_bf16 v[18:21], v[134:137], v[218:221], v[18:21]
	v_mfma_f32_16x16x32_bf16 v[10:13], v[162:165], v[218:221], v[10:13]
	s_setprio 0
	s_setprio 1
	v_mfma_f32_16x16x32_bf16 v[54:57], v[166:169], v[190:193], v[54:57]
	v_mfma_f32_16x16x32_bf16 v[46:49], v[174:177], v[190:193], v[46:49]
	v_mfma_f32_16x16x32_bf16 v[38:41], v[166:169], v[198:201], v[38:41]
	v_mfma_f32_16x16x32_bf16 v[30:33], v[174:177], v[198:201], v[30:33]
	v_mfma_f32_16x16x32_bf16 v[22:25], v[166:169], v[206:209], v[22:25]
	v_mfma_f32_16x16x32_bf16 v[14:17], v[174:177], v[206:209], v[14:17]
	v_mfma_f32_16x16x32_bf16 v[6:9], v[166:169], v[214:217], v[6:9]
	v_mfma_f32_16x16x32_bf16 v[2:5], v[174:177], v[214:217], v[2:5]
	v_mfma_f32_16x16x32_bf16 v[54:57], v[170:173], v[194:197], v[54:57]
	v_mfma_f32_16x16x32_bf16 v[46:49], v[186:189], v[194:197], v[46:49]
	v_mfma_f32_16x16x32_bf16 v[38:41], v[170:173], v[202:205], v[38:41]
	v_mfma_f32_16x16x32_bf16 v[30:33], v[186:189], v[202:205], v[30:33]
	v_mfma_f32_16x16x32_bf16 v[22:25], v[170:173], v[210:213], v[22:25]
	v_mfma_f32_16x16x32_bf16 v[14:17], v[186:189], v[210:213], v[14:17]
	v_mfma_f32_16x16x32_bf16 v[6:9], v[170:173], v[218:221], v[6:9]
	v_mfma_f32_16x16x32_bf16 v[2:5], v[186:189], v[218:221], v[2:5]
	s_barrier
	s_setprio 0
	s_add_i32 s48, 0, 0x18000
	s_add_i32 s49, 0, 0x1c000
	v_add_u32_e32 v162, s48, v156
	v_add_u32_e32 v179, s49, v156
	ds_read_b128 v[94:97], v162
	ds_read_b128 v[134:137], v162 offset:1024
	ds_read_b128 v[158:161], v162 offset:2048
	ds_read_b128 v[162:165], v162 offset:3072
	ds_read_b128 v[166:169], v179
	ds_read_b128 v[170:173], v179 offset:1024
	ds_read_b128 v[174:177], v179 offset:2048
	ds_read_b128 v[186:189], v179 offset:3072
	s_add_u32 s28, s28, 0x40000
	s_addc_u32 s29, s29, 0
	s_mov_b32 m0, s38
	v_lshl_add_u64 v[240:241], s[28:29], 0, v[144:145]
	ds_read_b128 v[190:193], v157 offset:32768
	ds_read_b128 v[194:197], v157 offset:33792
	ds_read_b128 v[198:201], v157 offset:34816
	ds_read_b128 v[202:205], v157 offset:35840
	ds_read_b128 v[206:209], v157 offset:36864
	ds_read_b128 v[210:213], v157 offset:37888
	ds_read_b128 v[214:217], v157 offset:38912
	ds_read_b128 v[218:221], v157 offset:39936
	global_load_lds_dwordx4 v[240:241], off
	v_lshl_add_u64 v[240:241], s[28:29], 0, v[140:141]
	s_mov_b32 m0, s39
	s_nop 0
	global_load_lds_dwordx4 v[240:241], off
	s_waitcnt vmcnt(8)
	s_waitcnt lgkmcnt(0)
	s_setprio 1
	s_barrier
	v_mfma_f32_16x16x32_bf16 v[130:133], v[94:97], v[190:193], v[130:133]
	v_mfma_f32_16x16x32_bf16 v[126:129], v[158:161], v[190:193], v[126:129]
	v_mfma_f32_16x16x32_bf16 v[114:117], v[94:97], v[198:201], v[114:117]
	v_mfma_f32_16x16x32_bf16 v[110:113], v[158:161], v[198:201], v[110:113]
	v_mfma_f32_16x16x32_bf16 v[98:101], v[94:97], v[206:209], v[98:101]
	v_mfma_f32_16x16x32_bf16 v[90:93], v[158:161], v[206:209], v[90:93]
	v_mfma_f32_16x16x32_bf16 v[78:81], v[94:97], v[214:217], v[78:81]
	v_mfma_f32_16x16x32_bf16 v[74:77], v[158:161], v[214:217], v[74:77]
	v_mfma_f32_16x16x32_bf16 v[130:133], v[134:137], v[194:197], v[130:133]
	v_mfma_f32_16x16x32_bf16 v[126:129], v[162:165], v[194:197], v[126:129]
	v_mfma_f32_16x16x32_bf16 v[114:117], v[134:137], v[202:205], v[114:117]
	v_mfma_f32_16x16x32_bf16 v[110:113], v[162:165], v[202:205], v[110:113]
	v_mfma_f32_16x16x32_bf16 v[98:101], v[134:137], v[210:213], v[98:101]
	v_mfma_f32_16x16x32_bf16 v[90:93], v[162:165], v[210:213], v[90:93]
	v_mfma_f32_16x16x32_bf16 v[78:81], v[134:137], v[218:221], v[78:81]
	v_mfma_f32_16x16x32_bf16 v[74:77], v[162:165], v[218:221], v[74:77]
	s_setprio 0
	s_setprio 1
	v_mfma_f32_16x16x32_bf16 v[122:125], v[166:169], v[190:193], v[122:125]
	v_mfma_f32_16x16x32_bf16 v[118:121], v[174:177], v[190:193], v[118:121]
	v_mfma_f32_16x16x32_bf16 v[106:109], v[166:169], v[198:201], v[106:109]
	v_mfma_f32_16x16x32_bf16 v[102:105], v[174:177], v[198:201], v[102:105]
	v_mfma_f32_16x16x32_bf16 v[86:89], v[166:169], v[206:209], v[86:89]
	v_mfma_f32_16x16x32_bf16 v[82:85], v[174:177], v[206:209], v[82:85]
	v_mfma_f32_16x16x32_bf16 v[70:73], v[166:169], v[214:217], v[70:73]
	v_mfma_f32_16x16x32_bf16 v[66:69], v[174:177], v[214:217], v[66:69]
	v_mfma_f32_16x16x32_bf16 v[122:125], v[170:173], v[194:197], v[122:125]
	v_mfma_f32_16x16x32_bf16 v[118:121], v[186:189], v[194:197], v[118:121]
	v_mfma_f32_16x16x32_bf16 v[106:109], v[170:173], v[202:205], v[106:109]
	v_mfma_f32_16x16x32_bf16 v[102:105], v[186:189], v[202:205], v[102:105]
	v_mfma_f32_16x16x32_bf16 v[86:89], v[170:173], v[210:213], v[86:89]
	v_mfma_f32_16x16x32_bf16 v[82:85], v[186:189], v[210:213], v[82:85]
	v_mfma_f32_16x16x32_bf16 v[70:73], v[170:173], v[218:221], v[70:73]
	v_mfma_f32_16x16x32_bf16 v[66:69], v[186:189], v[218:221], v[66:69]
	s_barrier
; #define PG8_STAGE(bufoff, gbase, voff) do { _Pragma("unroll") for (int _i = 0; _i < 2; ++_i) \
;         __builtin_amdgcn_global_load_lds((const unsigned*)((const char*)(gbase) + (voff)[_i]), (PG8_LAS unsigned*)(lds + (bufoff) + ldsw + _i * 8192), 16, 0, 0); } while (0)
; #define PG8_LDA(dst, b, h) do { _Pragma("unroll") for (int m = 0; m < 4; ++m) _Pragma("unroll") for (int k = 0; k < 2; ++k) dst[m][k] = *(const PG8_LAS bf16x8*)(lds + PG8_SA(b, h) + aoff + m * 2048 + k * 1024); } while (0)
; #define PG8_MMA(ai, bj, At, Bt) do { __builtin_amdgcn_s_setprio(1); _Pragma("unroll") for (int m = 0; m < 4; ++m) _Pragma("unroll") for (int n = 0; n < 2; ++n) _Pragma("unroll") for (int k = 0; k < 2; ++k) \
;         acc[ai][bj][m][n] = __builtin_amdgcn_mfma_f32_16x16x32_bf16(Bt[n][k], At[m][k], acc[ai][bj][m][n], 0, 0, 0); __builtin_amdgcn_s_setprio(0); } while (0)
; #define PG8_WAIT_V(n) asm volatile("s_waitcnt vmcnt(" #n ")" ::: "memory")
; #define PG8_WAIT_L(n) asm volatile("s_waitcnt lgkmcnt(" #n ")" ::: "memory")
; #define PG8_BAR __builtin_amdgcn_s_barrier()
; #define PG8_SCHED __builtin_amdgcn_sched_barrier(0)
; template <class Epi, class Sched, bool ALIGN_EPI = false, bool SP2 = false>
; __device__ __forceinline__ void gemm_phase(PG8_LAS unsigned char* lds, const Gemm g, const Sched& S, const Epi& E) {
;     ...
;             PG8_WAIT_V(8); PG8_WAIT_L(0); PG8_BAR; PG8_MMA(0, 0, At, B0); PG8_MMA(0, 1, At, B1); PG8_BAR; PG8_SCHED;
;             PG8_LDA(At, 1, 1); PG8_STAGE(PG8_SB(1, 0), b3, voffB); PG8_STAGE(PG8_SB(1, 1), b3 + hstep, voffB); PG8_STAGE(PG8_SA(1, 0), a3, voffA);
;             PG8_WAIT_V(8); PG8_WAIT_L(0); PG8_BAR; PG8_MMA(1, 0, At, B0); PG8_MMA(1, 1, At, B1); PG8_BAR; PG8_SCHED;
	s_setprio 0
	s_add_i32 s28, s48, s35
	v_lshl_add_u64 v[154:155], v[154:155], 0, s[80:81]
	s_mov_b32 m0, s28
	ds_read_b128 v[190:193], v157 offset:49152
	ds_read_b128 v[194:197], v157 offset:50176
	ds_read_b128 v[198:201], v157 offset:51200
	ds_read_b128 v[202:205], v157 offset:52224
	ds_read_b128 v[206:209], v157 offset:53248
	ds_read_b128 v[210:213], v157 offset:54272
	ds_read_b128 v[214:217], v157 offset:55296
	ds_read_b128 v[218:221], v157 offset:56320
	global_load_lds_dwordx4 v[154:155], off
	s_add_i32 m0, s28, 0x2000
	s_add_u32 s26, s26, 0x40080
	v_lshl_add_u64 v[154:155], v[180:181], 0, s[80:81]
	s_addc_u32 s27, s27, 0
	s_add_i32 s28, s49, s35
	global_load_lds_dwordx4 v[154:155], off
	v_lshl_add_u64 v[154:155], s[26:27], 0, v[142:143]
	s_mov_b32 m0, s28
	s_nop 0
	global_load_lds_dwordx4 v[154:155], off
	v_lshl_add_u64 v[154:155], s[26:27], 0, v[138:139]
	s_add_i32 m0, s28, 0x2000
	s_nop 0
	global_load_lds_dwordx4 v[154:155], off
	v_lshl_add_u64 v[154:155], v[182:183], 0, s[80:81]
	s_mov_b32 m0, s40
	s_nop 0
	global_load_lds_dwordx4 v[154:155], off
	v_lshl_add_u64 v[154:155], v[222:223], 0, s[80:81]
	s_mov_b32 m0, s41
	s_nop 0
	global_load_lds_dwordx4 v[154:155], off
	s_waitcnt vmcnt(8)
	s_waitcnt lgkmcnt(0)
	s_setprio 1
	s_barrier
	v_mfma_f32_16x16x32_bf16 v[62:65], v[94:97], v[190:193], v[62:65]
	v_mfma_f32_16x16x32_bf16 v[58:61], v[158:161], v[190:193], v[58:61]
	v_mfma_f32_16x16x32_bf16 v[50:53], v[94:97], v[198:201], v[50:53]
	v_mfma_f32_16x16x32_bf16 v[42:45], v[158:161], v[198:201], v[42:45]
	v_mfma_f32_16x16x32_bf16 v[34:37], v[94:97], v[206:209], v[34:37]
	v_mfma_f32_16x16x32_bf16 v[26:29], v[158:161], v[206:209], v[26:29]
	v_mfma_f32_16x16x32_bf16 v[18:21], v[94:97], v[214:217], v[18:21]
	v_mfma_f32_16x16x32_bf16 v[10:13], v[158:161], v[214:217], v[10:13]
	v_mfma_f32_16x16x32_bf16 v[62:65], v[134:137], v[194:197], v[62:65]
	v_mfma_f32_16x16x32_bf16 v[58:61], v[162:165], v[194:197], v[58:61]
	v_mfma_f32_16x16x32_bf16 v[50:53], v[134:137], v[202:205], v[50:53]
	v_mfma_f32_16x16x32_bf16 v[42:45], v[162:165], v[202:205], v[42:45]
	v_mfma_f32_16x16x32_bf16 v[34:37], v[134:137], v[210:213], v[34:37]
	v_mfma_f32_16x16x32_bf16 v[26:29], v[162:165], v[210:213], v[26:29]
	v_mfma_f32_16x16x32_bf16 v[18:21], v[134:137], v[218:221], v[18:21]
	v_mfma_f32_16x16x32_bf16 v[10:13], v[162:165], v[218:221], v[10:13]
	s_setprio 0
	s_setprio 1
	v_mfma_f32_16x16x32_bf16 v[54:57], v[166:169], v[190:193], v[54:57]
	v_mfma_f32_16x16x32_bf16 v[46:49], v[174:177], v[190:193], v[46:49]
	v_mfma_f32_16x16x32_bf16 v[38:41], v[166:169], v[198:201], v[38:41]
	v_mfma_f32_16x16x32_bf16 v[30:33], v[174:177], v[198:201], v[30:33]
	v_mfma_f32_16x16x32_bf16 v[22:25], v[166:169], v[206:209], v[22:25]
	v_mfma_f32_16x16x32_bf16 v[14:17], v[174:177], v[206:209], v[14:17]
	v_mfma_f32_16x16x32_bf16 v[6:9], v[166:169], v[214:217], v[6:9]
	v_mfma_f32_16x16x32_bf16 v[2:5], v[174:177], v[214:217], v[2:5]
	v_mfma_f32_16x16x32_bf16 v[54:57], v[170:173], v[194:197], v[54:57]
	v_mfma_f32_16x16x32_bf16 v[46:49], v[186:189], v[194:197], v[46:49]
	v_mfma_f32_16x16x32_bf16 v[38:41], v[170:173], v[202:205], v[38:41]
	v_mfma_f32_16x16x32_bf16 v[30:33], v[186:189], v[202:205], v[30:33]
	v_mfma_f32_16x16x32_bf16 v[22:25], v[170:173], v[210:213], v[22:25]
	v_mfma_f32_16x16x32_bf16 v[14:17], v[186:189], v[210:213], v[14:17]
	v_mfma_f32_16x16x32_bf16 v[6:9], v[170:173], v[218:221], v[6:9]
	v_mfma_f32_16x16x32_bf16 v[2:5], v[186:189], v[218:221], v[2:5]
	s_barrier
	s_setprio 0
	s_add_i32 s47, s47, 2
	s_add_u32 s24, s24, 0x100
	s_addc_u32 s25, s25, 0
	s_add_u32 s45, s45, 0x100
	s_addc_u32 s46, s46, 0
	s_cmp_gt_u32 s47, 13
	s_cbranch_scc0 .LBB0_301
	s_and_b64 vcc, exec, s[8:9]
	s_cbranch_vccz .LBB0_304
	s_barrier

; #define PG8_STAGE(bufoff, gbase, voff) do { _Pragma("unroll") for (int _i = 0; _i < 2; ++_i) \
;         __builtin_amdgcn_global_load_lds((const unsigned*)((const char*)(gbase) + (voff)[_i]), (PG8_LAS unsigned*)(lds + (bufoff) + ldsw + _i * 8192), 16, 0, 0); } while (0)
; #define PG8_LDA(dst, b, h) do { _Pragma("unroll") for (int m = 0; m < 4; ++m) _Pragma("unroll") for (int k = 0; k < 2; ++k) dst[m][k] = *(const PG8_LAS bf16x8*)(lds + PG8_SA(b, h) + aoff + m * 2048 + k * 1024); } while (0)
; #define PG8_LDB(dst, b, h) do { _Pragma("unroll") for (int n = 0; n < 2; ++n) _Pragma("unroll") for (int k = 0; k < 2; ++k) dst[n][k] = *(const PG8_LAS bf16x8*)(lds + PG8_SB(b, h) + boff + n * 2048 + k * 1024); } while (0)
; #define PG8_MMA(ai, bj, At, Bt) do { __builtin_amdgcn_s_setprio(1); _Pragma("unroll") for (int m = 0; m < 4; ++m) _Pragma("unroll") for (int n = 0; n < 2; ++n) _Pragma("unroll") for (int k = 0; k < 2; ++k) \
;         acc[ai][bj][m][n] = __builtin_amdgcn_mfma_f32_16x16x32_bf16(Bt[n][k], At[m][k], acc[ai][bj][m][n], 0, 0, 0); __builtin_amdgcn_s_setprio(0); } while (0)
; #define PG8_WAIT_V(n) asm volatile("s_waitcnt vmcnt(" #n ")" ::: "memory")
; #define PG8_WAIT_L(n) asm volatile("s_waitcnt lgkmcnt(" #n ")" ::: "memory")
; template <class Epi, class Sched, bool ALIGN_EPI = false, bool SP2 = false>
; __device__ __forceinline__ void gemm_phase(PG8_LAS unsigned char* lds, const Gemm g, const Sched& S, const Epi& E) {
;     ...
;             const bool last = (t == nt - 2);
;             const char* a1 = cA + (size_t)(t + 1) * kstep;
;             const char* a2 = last ? nA : cA + (size_t)(t + 2) * kstep; const char* b2 = last ? nB : cB + (size_t)(t + 2) * kstep;
;             const char* a3 = a2 + kstep; const char* b3 = b2 + kstep;
;             if (last && has_next) S.a_ready(nxt);
;             if constexpr (SP2) {
;             PG8_LDB(B0, 0, 0); PG8_LDB(B1, 0, 1); PG8_SCHED; PG8_LDA(At, 0, 0); PG8_STAGE(PG8_SA(1, 1), a1 + hstep, voffA);
;             PG8_WAIT_V(8); PG8_WAIT_L(0); PG8_BAR; PG8_MMA(0, 0, At, B0); PG8_MMA(0, 1, At, B1); PG8_BAR; PG8_SCHED;
;             PG8_LDA(At, 0, 1); PG8_STAGE(PG8_SB(0, 0), b2, voffB); PG8_STAGE(PG8_SB(0, 1), b2 + hstep, voffB); PG8_STAGE(PG8_SA(0, 0), a2, voffA);
;             PG8_WAIT_V(8); PG8_WAIT_L(0); PG8_BAR; PG8_MMA(1, 0, At, B0); PG8_MMA(1, 1, At, B1); PG8_BAR; PG8_SCHED;
.LBB0_318:
	s_add_u32 s26, s24, 0xfffc0080
	s_addc_u32 s27, s25, -1
	s_add_i32 s48, 0, 0x10000
	s_cmp_eq_u32 s47, 12
	s_cselect_b32 s29, s13, s27
	s_cselect_b32 s28, s21, s26
	v_add_u32_e32 v154, s48, v156
	s_cselect_b32 s27, s11, s46
	s_cselect_b32 s26, s44, s45
	s_add_i32 s50, 0, 0x14000
	ds_read_b128 v[94:97], v154
	ds_read_b128 v[134:137], v154 offset:1024
	ds_read_b128 v[158:161], v154 offset:2048
	ds_read_b128 v[162:165], v154 offset:3072
	v_add_u32_e32 v154, s50, v156
	ds_read_b128 v[166:169], v154
	ds_read_b128 v[170:173], v154 offset:1024
	ds_read_b128 v[174:177], v154 offset:2048
	ds_read_b128 v[186:189], v154 offset:3072
	v_lshl_add_u64 v[154:155], s[24:25], 0, v[150:151]
	s_add_i32 m0, s23, 0xc000
	ds_read_b128 v[190:193], v157
	ds_read_b128 v[194:197], v157 offset:1024
	ds_read_b128 v[198:201], v157 offset:2048
	ds_read_b128 v[202:205], v157 offset:3072
	ds_read_b128 v[206:209], v157 offset:4096
	ds_read_b128 v[210:213], v157 offset:5120
	ds_read_b128 v[214:217], v157 offset:6144
	ds_read_b128 v[218:221], v157 offset:7168
	global_load_lds_dwordx4 v[154:155], off
	v_lshl_add_u64 v[154:155], s[24:25], 0, v[152:153]
	s_add_i32 m0, s23, 0xe000
	s_nop 0
	global_load_lds_dwordx4 v[154:155], off
	s_waitcnt vmcnt(8)
	s_waitcnt lgkmcnt(0)
	s_setprio 1
	s_barrier
	v_mfma_f32_16x16x32_bf16 v[130:133], v[94:97], v[190:193], v[130:133]
	v_mfma_f32_16x16x32_bf16 v[126:129], v[158:161], v[190:193], v[126:129]
	v_mfma_f32_16x16x32_bf16 v[114:117], v[94:97], v[198:201], v[114:117]
	v_mfma_f32_16x16x32_bf16 v[110:113], v[158:161], v[198:201], v[110:113]
	v_mfma_f32_16x16x32_bf16 v[98:101], v[94:97], v[206:209], v[98:101]
	v_mfma_f32_16x16x32_bf16 v[90:93], v[158:161], v[206:209], v[90:93]
	v_mfma_f32_16x16x32_bf16 v[78:81], v[94:97], v[214:217], v[78:81]
	v_mfma_f32_16x16x32_bf16 v[74:77], v[158:161], v[214:217], v[74:77]
	v_mfma_f32_16x16x32_bf16 v[130:133], v[134:137], v[194:197], v[130:133]
	v_mfma_f32_16x16x32_bf16 v[126:129], v[162:165], v[194:197], v[126:129]
	v_mfma_f32_16x16x32_bf16 v[114:117], v[134:137], v[202:205], v[114:117]
	v_mfma_f32_16x16x32_bf16 v[110:113], v[162:165], v[202:205], v[110:113]
	v_mfma_f32_16x16x32_bf16 v[98:101], v[134:137], v[210:213], v[98:101]
	v_mfma_f32_16x16x32_bf16 v[90:93], v[162:165], v[210:213], v[90:93]
	v_mfma_f32_16x16x32_bf16 v[78:81], v[134:137], v[218:221], v[78:81]
	v_mfma_f32_16x16x32_bf16 v[74:77], v[162:165], v[218:221], v[74:77]
	s_setprio 0
	s_setprio 1
	v_mfma_f32_16x16x32_bf16 v[122:125], v[166:169], v[190:193], v[122:125]
	v_mfma_f32_16x16x32_bf16 v[118:121], v[174:177], v[190:193], v[118:121]
	v_mfma_f32_16x16x32_bf16 v[106:109], v[166:169], v[198:201], v[106:109]
	v_mfma_f32_16x16x32_bf16 v[102:105], v[174:177], v[198:201], v[102:105]
	v_mfma_f32_16x16x32_bf16 v[86:89], v[166:169], v[206:209], v[86:89]
	v_mfma_f32_16x16x32_bf16 v[82:85], v[174:177], v[206:209], v[82:85]
	v_mfma_f32_16x16x32_bf16 v[70:73], v[166:169], v[214:217], v[70:73]
	v_mfma_f32_16x16x32_bf16 v[66:69], v[174:177], v[214:217], v[66:69]
	v_mfma_f32_16x16x32_bf16 v[122:125], v[170:173], v[194:197], v[122:125]
	v_mfma_f32_16x16x32_bf16 v[118:121], v[186:189], v[194:197], v[118:121]
	v_mfma_f32_16x16x32_bf16 v[106:109], v[170:173], v[202:205], v[106:109]
	v_mfma_f32_16x16x32_bf16 v[102:105], v[186:189], v[202:205], v[102:105]
	v_mfma_f32_16x16x32_bf16 v[86:89], v[170:173], v[210:213], v[86:89]
	v_mfma_f32_16x16x32_bf16 v[82:85], v[186:189], v[210:213], v[82:85]
	v_mfma_f32_16x16x32_bf16 v[70:73], v[170:173], v[218:221], v[70:73]
	v_mfma_f32_16x16x32_bf16 v[66:69], v[186:189], v[218:221], v[66:69]
	s_barrier
	s_setprio 0
	s_add_i32 s48, s48, s35
	v_lshl_add_u64 v[154:155], s[26:27], 0, v[142:143]
	s_mov_b32 m0, s48
	ds_read_b128 v[190:193], v157 offset:16384
	ds_read_b128 v[194:197], v157 offset:17408
	ds_read_b128 v[198:201], v157 offset:18432
	ds_read_b128 v[202:205], v157 offset:19456
	ds_read_b128 v[206:209], v157 offset:20480
	ds_read_b128 v[210:213], v157 offset:21504
	ds_read_b128 v[214:217], v157 offset:22528
	ds_read_b128 v[218:221], v157 offset:23552
	global_load_lds_dwordx4 v[154:155], off
	s_add_i32 m0, s48, 0x2000
	s_add_u32 s48, s26, 0x40000
	v_lshl_add_u64 v[180:181], s[26:27], 0, v[138:139]
	s_addc_u32 s49, s27, 0
	s_add_i32 s50, s50, s35
	global_load_lds_dwordx4 v[180:181], off
	v_lshl_add_u64 v[182:183], s[48:49], 0, v[142:143]
	s_mov_b32 m0, s50
	v_lshl_add_u64 v[222:223], s[28:29], 0, v[140:141]
	global_load_lds_dwordx4 v[182:183], off
	v_lshl_add_u64 v[182:183], s[48:49], 0, v[138:139]
	s_add_i32 m0, s50, 0x2000
	s_nop 0
	global_load_lds_dwordx4 v[182:183], off
	v_lshl_add_u64 v[182:183], s[28:29], 0, v[144:145]
	s_mov_b32 m0, s23
	s_nop 0
	global_load_lds_dwordx4 v[182:183], off
	s_mov_b32 m0, s37
	s_nop 0
	global_load_lds_dwordx4 v[222:223], off
	s_waitcnt vmcnt(8)
	s_waitcnt lgkmcnt(0)
	s_setprio 1
	s_barrier
; #define PG8_STAGE(bufoff, gbase, voff) do { _Pragma("unroll") for (int _i = 0; _i < 2; ++_i) \
;         __builtin_amdgcn_global_load_lds((const unsigned*)((const char*)(gbase) + (voff)[_i]), (PG8_LAS unsigned*)(lds + (bufoff) + ldsw + _i * 8192), 16, 0, 0); } while (0)
; #define PG8_LDA(dst, b, h) do { _Pragma("unroll") for (int m = 0; m < 4; ++m) _Pragma("unroll") for (int k = 0; k < 2; ++k) dst[m][k] = *(const PG8_LAS bf16x8*)(lds + PG8_SA(b, h) + aoff + m * 2048 + k * 1024); } while (0)
; #define PG8_LDB(dst, b, h) do { _Pragma("unroll") for (int n = 0; n < 2; ++n) _Pragma("unroll") for (int k = 0; k < 2; ++k) dst[n][k] = *(const PG8_LAS bf16x8*)(lds + PG8_SB(b, h) + boff + n * 2048 + k * 1024); } while (0)
; #define PG8_MMA(ai, bj, At, Bt) do { __builtin_amdgcn_s_setprio(1); _Pragma("unroll") for (int m = 0; m < 4; ++m) _Pragma("unroll") for (int n = 0; n < 2; ++n) _Pragma("unroll") for (int k = 0; k < 2; ++k) \
;         acc[ai][bj][m][n] = __builtin_amdgcn_mfma_f32_16x16x32_bf16(Bt[n][k], At[m][k], acc[ai][bj][m][n], 0, 0, 0); __builtin_amdgcn_s_setprio(0); } while (0)
; #define PG8_WAIT_V(n) asm volatile("s_waitcnt vmcnt(" #n ")" ::: "memory")
; #define PG8_WAIT_L(n) asm volatile("s_waitcnt lgkmcnt(" #n ")" ::: "memory")
; #define PG8_BAR __builtin_amdgcn_s_barrier()
; #define PG8_SCHED __builtin_amdgcn_sched_barrier(0)
; template <class Epi, class Sched, bool ALIGN_EPI = false, bool SP2 = false>
; __device__ __forceinline__ void gemm_phase(PG8_LAS unsigned char* lds, const Gemm g, const Sched& S, const Epi& E) {
;     ...
;             PG8_WAIT_V(8); PG8_WAIT_L(0); PG8_BAR; PG8_MMA(1, 0, At, B0); PG8_MMA(1, 1, At, B1); PG8_BAR; PG8_SCHED;
;             PG8_LDB(B0, 1, 0); PG8_LDB(B1, 1, 1); PG8_SCHED; PG8_LDA(At, 1, 0); PG8_STAGE(PG8_SA(0, 1), a2 + hstep, voffA);
;             PG8_WAIT_V(8); PG8_WAIT_L(0); PG8_BAR; PG8_MMA(0, 0, At, B0); PG8_MMA(0, 1, At, B1); PG8_BAR; PG8_SCHED;
;             PG8_LDA(At, 1, 1); PG8_STAGE(PG8_SB(1, 0), b3, voffB); PG8_STAGE(PG8_SB(1, 1), b3 + hstep, voffB); PG8_STAGE(PG8_SA(1, 0), a3, voffA);
;             PG8_WAIT_V(8); PG8_WAIT_L(0); PG8_BAR; PG8_MMA(1, 0, At, B0); PG8_MMA(1, 1, At, B1); PG8_BAR; PG8_SCHED;
	v_mfma_f32_16x16x32_bf16 v[62:65], v[94:97], v[190:193], v[62:65]
	v_mfma_f32_16x16x32_bf16 v[58:61], v[158:161], v[190:193], v[58:61]
	v_mfma_f32_16x16x32_bf16 v[50:53], v[94:97], v[198:201], v[50:53]
	v_mfma_f32_16x16x32_bf16 v[42:45], v[158:161], v[198:201], v[42:45]
	v_mfma_f32_16x16x32_bf16 v[34:37], v[94:97], v[206:209], v[34:37]
	v_mfma_f32_16x16x32_bf16 v[26:29], v[158:161], v[206:209], v[26:29]
	v_mfma_f32_16x16x32_bf16 v[18:21], v[94:97], v[214:217], v[18:21]
	v_mfma_f32_16x16x32_bf16 v[10:13], v[158:161], v[214:217], v[10:13]
	v_mfma_f32_16x16x32_bf16 v[62:65], v[134:137], v[194:197], v[62:65]
	v_mfma_f32_16x16x32_bf16 v[58:61], v[162:165], v[194:197], v[58:61]
	v_mfma_f32_16x16x32_bf16 v[50:53], v[134:137], v[202:205], v[50:53]
	v_mfma_f32_16x16x32_bf16 v[42:45], v[162:165], v[202:205], v[42:45]
	v_mfma_f32_16x16x32_bf16 v[34:37], v[134:137], v[210:213], v[34:37]
	v_mfma_f32_16x16x32_bf16 v[26:29], v[162:165], v[210:213], v[26:29]
	v_mfma_f32_16x16x32_bf16 v[18:21], v[134:137], v[218:221], v[18:21]
	v_mfma_f32_16x16x32_bf16 v[10:13], v[162:165], v[218:221], v[10:13]
	s_setprio 0
	s_setprio 1
	v_mfma_f32_16x16x32_bf16 v[54:57], v[166:169], v[190:193], v[54:57]
	v_mfma_f32_16x16x32_bf16 v[46:49], v[174:177], v[190:193], v[46:49]
	v_mfma_f32_16x16x32_bf16 v[38:41], v[166:169], v[198:201], v[38:41]
	v_mfma_f32_16x16x32_bf16 v[30:33], v[174:177], v[198:201], v[30:33]
	v_mfma_f32_16x16x32_bf16 v[22:25], v[166:169], v[206:209], v[22:25]
	v_mfma_f32_16x16x32_bf16 v[14:17], v[174:177], v[206:209], v[14:17]
	v_mfma_f32_16x16x32_bf16 v[6:9], v[166:169], v[214:217], v[6:9]
	v_mfma_f32_16x16x32_bf16 v[2:5], v[174:177], v[214:217], v[2:5]
	v_mfma_f32_16x16x32_bf16 v[54:57], v[170:173], v[194:197], v[54:57]
	v_mfma_f32_16x16x32_bf16 v[46:49], v[186:189], v[194:197], v[46:49]
	v_mfma_f32_16x16x32_bf16 v[38:41], v[170:173], v[202:205], v[38:41]
	v_mfma_f32_16x16x32_bf16 v[30:33], v[186:189], v[202:205], v[30:33]
	v_mfma_f32_16x16x32_bf16 v[22:25], v[170:173], v[210:213], v[22:25]
	v_mfma_f32_16x16x32_bf16 v[14:17], v[186:189], v[210:213], v[14:17]
	v_mfma_f32_16x16x32_bf16 v[6:9], v[170:173], v[218:221], v[6:9]
	v_mfma_f32_16x16x32_bf16 v[2:5], v[186:189], v[218:221], v[2:5]
	s_barrier
	s_setprio 0
	s_add_i32 s48, 0, 0x18000
	s_add_i32 s49, 0, 0x1c000
	v_add_u32_e32 v162, s48, v156
	v_add_u32_e32 v179, s49, v156
	ds_read_b128 v[94:97], v162
	ds_read_b128 v[134:137], v162 offset:1024
	ds_read_b128 v[158:161], v162 offset:2048
	ds_read_b128 v[162:165], v162 offset:3072
	ds_read_b128 v[166:169], v179
	ds_read_b128 v[170:173], v179 offset:1024
	ds_read_b128 v[174:177], v179 offset:2048
	ds_read_b128 v[186:189], v179 offset:3072
	s_add_u32 s28, s28, 0x40000
	s_addc_u32 s29, s29, 0
	s_mov_b32 m0, s38
	v_lshl_add_u64 v[240:241], s[28:29], 0, v[144:145]
	ds_read_b128 v[190:193], v157 offset:32768
	ds_read_b128 v[194:197], v157 offset:33792
	ds_read_b128 v[198:201], v157 offset:34816
	ds_read_b128 v[202:205], v157 offset:35840
	ds_read_b128 v[206:209], v157 offset:36864
	ds_read_b128 v[210:213], v157 offset:37888
	ds_read_b128 v[214:217], v157 offset:38912
	ds_read_b128 v[218:221], v157 offset:39936
	global_load_lds_dwordx4 v[240:241], off
	v_lshl_add_u64 v[240:241], s[28:29], 0, v[140:141]
	s_mov_b32 m0, s39
	s_nop 0
	global_load_lds_dwordx4 v[240:241], off
	s_waitcnt vmcnt(8)
	s_waitcnt lgkmcnt(0)
	s_setprio 1
	s_barrier
	v_mfma_f32_16x16x32_bf16 v[130:133], v[94:97], v[190:193], v[130:133]
	v_mfma_f32_16x16x32_bf16 v[126:129], v[158:161], v[190:193], v[126:129]
	v_mfma_f32_16x16x32_bf16 v[114:117], v[94:97], v[198:201], v[114:117]
	v_mfma_f32_16x16x32_bf16 v[110:113], v[158:161], v[198:201], v[110:113]
	v_mfma_f32_16x16x32_bf16 v[98:101], v[94:97], v[206:209], v[98:101]
	v_mfma_f32_16x16x32_bf16 v[90:93], v[158:161], v[206:209], v[90:93]
	v_mfma_f32_16x16x32_bf16 v[78:81], v[94:97], v[214:217], v[78:81]
	v_mfma_f32_16x16x32_bf16 v[74:77], v[158:161], v[214:217], v[74:77]
	v_mfma_f32_16x16x32_bf16 v[130:133], v[134:137], v[194:197], v[130:133]
	v_mfma_f32_16x16x32_bf16 v[126:129], v[162:165], v[194:197], v[126:129]
	v_mfma_f32_16x16x32_bf16 v[114:117], v[134:137], v[202:205], v[114:117]
	v_mfma_f32_16x16x32_bf16 v[110:113], v[162:165], v[202:205], v[110:113]
	v_mfma_f32_16x16x32_bf16 v[98:101], v[134:137], v[210:213], v[98:101]
	v_mfma_f32_16x16x32_bf16 v[90:93], v[162:165], v[210:213], v[90:93]
	v_mfma_f32_16x16x32_bf16 v[78:81], v[134:137], v[218:221], v[78:81]
	v_mfma_f32_16x16x32_bf16 v[74:77], v[162:165], v[218:221], v[74:77]
	s_setprio 0
	s_setprio 1
	v_mfma_f32_16x16x32_bf16 v[122:125], v[166:169], v[190:193], v[122:125]
	v_mfma_f32_16x16x32_bf16 v[118:121], v[174:177], v[190:193], v[118:121]
	v_mfma_f32_16x16x32_bf16 v[106:109], v[166:169], v[198:201], v[106:109]
	v_mfma_f32_16x16x32_bf16 v[102:105], v[174:177], v[198:201], v[102:105]
	v_mfma_f32_16x16x32_bf16 v[86:89], v[166:169], v[206:209], v[86:89]
	v_mfma_f32_16x16x32_bf16 v[82:85], v[174:177], v[206:209], v[82:85]
	v_mfma_f32_16x16x32_bf16 v[70:73], v[166:169], v[214:217], v[70:73]
	v_mfma_f32_16x16x32_bf16 v[66:69], v[174:177], v[214:217], v[66:69]
	v_mfma_f32_16x16x32_bf16 v[122:125], v[170:173], v[194:197], v[122:125]
	v_mfma_f32_16x16x32_bf16 v[118:121], v[186:189], v[194:197], v[118:121]
	v_mfma_f32_16x16x32_bf16 v[106:109], v[170:173], v[202:205], v[106:109]
	v_mfma_f32_16x16x32_bf16 v[102:105], v[186:189], v[202:205], v[102:105]
	v_mfma_f32_16x16x32_bf16 v[86:89], v[170:173], v[210:213], v[86:89]
	v_mfma_f32_16x16x32_bf16 v[82:85], v[186:189], v[210:213], v[82:85]
	v_mfma_f32_16x16x32_bf16 v[70:73], v[170:173], v[218:221], v[70:73]
	v_mfma_f32_16x16x32_bf16 v[66:69], v[186:189], v[218:221], v[66:69]
	s_barrier
; #define PG8_STAGE(bufoff, gbase, voff) do { _Pragma("unroll") for (int _i = 0; _i < 2; ++_i) \
;         __builtin_amdgcn_global_load_lds((const unsigned*)((const char*)(gbase) + (voff)[_i]), (PG8_LAS unsigned*)(lds + (bufoff) + ldsw + _i * 8192), 16, 0, 0); } while (0)
; #define PG8_LDA(dst, b, h) do { _Pragma("unroll") for (int m = 0; m < 4; ++m) _Pragma("unroll") for (int k = 0; k < 2; ++k) dst[m][k] = *(const PG8_LAS bf16x8*)(lds + PG8_SA(b, h) + aoff + m * 2048 + k * 1024); } while (0)
; #define PG8_MMA(ai, bj, At, Bt) do { __builtin_amdgcn_s_setprio(1); _Pragma("unroll") for (int m = 0; m < 4; ++m) _Pragma("unroll") for (int n = 0; n < 2; ++n) _Pragma("unroll") for (int k = 0; k < 2; ++k) \
;         acc[ai][bj][m][n] = __builtin_amdgcn_mfma_f32_16x16x32_bf16(Bt[n][k], At[m][k], acc[ai][bj][m][n], 0, 0, 0); __builtin_amdgcn_s_setprio(0); } while (0)
; #define PG8_WAIT_V(n) asm volatile("s_waitcnt vmcnt(" #n ")" ::: "memory")
; #define PG8_WAIT_L(n) asm volatile("s_waitcnt lgkmcnt(" #n ")" ::: "memory")
; #define PG8_BAR __builtin_amdgcn_s_barrier()
; #define PG8_SCHED __builtin_amdgcn_sched_barrier(0)
; template <class Epi, class Sched, bool ALIGN_EPI = false, bool SP2 = false>
; __device__ __forceinline__ void gemm_phase(PG8_LAS unsigned char* lds, const Gemm g, const Sched& S, const Epi& E) {
;     ...
;             PG8_WAIT_V(8); PG8_WAIT_L(0); PG8_BAR; PG8_MMA(0, 0, At, B0); PG8_MMA(0, 1, At, B1); PG8_BAR; PG8_SCHED;
;             PG8_LDA(At, 1, 1); PG8_STAGE(PG8_SB(1, 0), b3, voffB); PG8_STAGE(PG8_SB(1, 1), b3 + hstep, voffB); PG8_STAGE(PG8_SA(1, 0), a3, voffA);
;             PG8_WAIT_V(8); PG8_WAIT_L(0); PG8_BAR; PG8_MMA(1, 0, At, B0); PG8_MMA(1, 1, At, B1); PG8_BAR; PG8_SCHED;
	s_setprio 0
	s_add_i32 s28, s48, s35
	v_lshl_add_u64 v[154:155], v[154:155], 0, s[80:81]
	s_mov_b32 m0, s28
	ds_read_b128 v[190:193], v157 offset:49152
	ds_read_b128 v[194:197], v157 offset:50176
	ds_read_b128 v[198:201], v157 offset:51200
	ds_read_b128 v[202:205], v157 offset:52224
	ds_read_b128 v[206:209], v157 offset:53248
	ds_read_b128 v[210:213], v157 offset:54272
	ds_read_b128 v[214:217], v157 offset:55296
	ds_read_b128 v[218:221], v157 offset:56320
	global_load_lds_dwordx4 v[154:155], off
	s_add_i32 m0, s28, 0x2000
	s_add_u32 s26, s26, 0x40080
	v_lshl_add_u64 v[154:155], v[180:181], 0, s[80:81]
	s_addc_u32 s27, s27, 0
	s_add_i32 s28, s49, s35
	global_load_lds_dwordx4 v[154:155], off
	v_lshl_add_u64 v[154:155], s[26:27], 0, v[142:143]
	s_mov_b32 m0, s28
	s_nop 0
	global_load_lds_dwordx4 v[154:155], off
	v_lshl_add_u64 v[154:155], s[26:27], 0, v[138:139]
	s_add_i32 m0, s28, 0x2000
	s_nop 0
	global_load_lds_dwordx4 v[154:155], off
	v_lshl_add_u64 v[154:155], v[182:183], 0, s[80:81]
	s_mov_b32 m0, s40
	s_nop 0
	global_load_lds_dwordx4 v[154:155], off
	v_lshl_add_u64 v[154:155], v[222:223], 0, s[80:81]
	s_mov_b32 m0, s41
	s_nop 0
	global_load_lds_dwordx4 v[154:155], off
	s_waitcnt vmcnt(8)
	s_waitcnt lgkmcnt(0)
	s_setprio 1
	s_barrier
	v_mfma_f32_16x16x32_bf16 v[62:65], v[94:97], v[190:193], v[62:65]
	v_mfma_f32_16x16x32_bf16 v[58:61], v[158:161], v[190:193], v[58:61]
	v_mfma_f32_16x16x32_bf16 v[50:53], v[94:97], v[198:201], v[50:53]
	v_mfma_f32_16x16x32_bf16 v[42:45], v[158:161], v[198:201], v[42:45]
	v_mfma_f32_16x16x32_bf16 v[34:37], v[94:97], v[206:209], v[34:37]
	v_mfma_f32_16x16x32_bf16 v[26:29], v[158:161], v[206:209], v[26:29]
	v_mfma_f32_16x16x32_bf16 v[18:21], v[94:97], v[214:217], v[18:21]
	v_mfma_f32_16x16x32_bf16 v[10:13], v[158:161], v[214:217], v[10:13]
	v_mfma_f32_16x16x32_bf16 v[62:65], v[134:137], v[194:197], v[62:65]
	v_mfma_f32_16x16x32_bf16 v[58:61], v[162:165], v[194:197], v[58:61]
	v_mfma_f32_16x16x32_bf16 v[50:53], v[134:137], v[202:205], v[50:53]
	v_mfma_f32_16x16x32_bf16 v[42:45], v[162:165], v[202:205], v[42:45]
	v_mfma_f32_16x16x32_bf16 v[34:37], v[134:137], v[210:213], v[34:37]
	v_mfma_f32_16x16x32_bf16 v[26:29], v[162:165], v[210:213], v[26:29]
	v_mfma_f32_16x16x32_bf16 v[18:21], v[134:137], v[218:221], v[18:21]
	v_mfma_f32_16x16x32_bf16 v[10:13], v[162:165], v[218:221], v[10:13]
	s_setprio 0
	s_setprio 1
	v_mfma_f32_16x16x32_bf16 v[54:57], v[166:169], v[190:193], v[54:57]
	v_mfma_f32_16x16x32_bf16 v[46:49], v[174:177], v[190:193], v[46:49]
	v_mfma_f32_16x16x32_bf16 v[38:41], v[166:169], v[198:201], v[38:41]
	v_mfma_f32_16x16x32_bf16 v[30:33], v[174:177], v[198:201], v[30:33]
	v_mfma_f32_16x16x32_bf16 v[22:25], v[166:169], v[206:209], v[22:25]
	v_mfma_f32_16x16x32_bf16 v[14:17], v[174:177], v[206:209], v[14:17]
	v_mfma_f32_16x16x32_bf16 v[6:9], v[166:169], v[214:217], v[6:9]
	v_mfma_f32_16x16x32_bf16 v[2:5], v[174:177], v[214:217], v[2:5]
	v_mfma_f32_16x16x32_bf16 v[54:57], v[170:173], v[194:197], v[54:57]
	v_mfma_f32_16x16x32_bf16 v[46:49], v[186:189], v[194:197], v[46:49]
	v_mfma_f32_16x16x32_bf16 v[38:41], v[170:173], v[202:205], v[38:41]
	v_mfma_f32_16x16x32_bf16 v[30:33], v[186:189], v[202:205], v[30:33]
	v_mfma_f32_16x16x32_bf16 v[22:25], v[170:173], v[210:213], v[22:25]
	v_mfma_f32_16x16x32_bf16 v[14:17], v[186:189], v[210:213], v[14:17]
	v_mfma_f32_16x16x32_bf16 v[6:9], v[170:173], v[218:221], v[6:9]
	v_mfma_f32_16x16x32_bf16 v[2:5], v[186:189], v[218:221], v[2:5]
	s_barrier
	s_setprio 0
	s_add_i32 s47, s47, 2
	s_add_u32 s24, s24, 0x100
	s_addc_u32 s25, s25, 0
	s_add_u32 s45, s45, 0x100
	s_addc_u32 s46, s46, 0
	s_cmp_gt_u32 s47, 13
	s_cbranch_scc0 .LBB0_318
	s_and_b64 vcc, exec, s[6:7]
	s_cbranch_vccz .LBB0_321
	s_barrier

; #define PG8_STAGE(bufoff, gbase, voff) do { _Pragma("unroll") for (int _i = 0; _i < 2; ++_i) \
;         __builtin_amdgcn_global_load_lds((const unsigned*)((const char*)(gbase) + (voff)[_i]), (PG8_LAS unsigned*)(lds + (bufoff) + ldsw + _i * 8192), 16, 0, 0); } while (0)
; #define PG8_LDA(dst, b, h) do { _Pragma("unroll") for (int m = 0; m < 4; ++m) _Pragma("unroll") for (int k = 0; k < 2; ++k) dst[m][k] = *(const PG8_LAS bf16x8*)(lds + PG8_SA(b, h) + aoff + m * 2048 + k * 1024); } while (0)
; #define PG8_LDB(dst, b, h) do { _Pragma("unroll") for (int n = 0; n < 2; ++n) _Pragma("unroll") for (int k = 0; k < 2; ++k) dst[n][k] = *(const PG8_LAS bf16x8*)(lds + PG8_SB(b, h) + boff + n * 2048 + k * 1024); } while (0)
; #define PG8_MMA(ai, bj, At, Bt) do { __builtin_amdgcn_s_setprio(1); _Pragma("unroll") for (int m = 0; m < 4; ++m) _Pragma("unroll") for (int n = 0; n < 2; ++n) _Pragma("unroll") for (int k = 0; k < 2; ++k) \
;         acc[ai][bj][m][n] = __builtin_amdgcn_mfma_f32_16x16x32_bf16(Bt[n][k], At[m][k], acc[ai][bj][m][n], 0, 0, 0); __builtin_amdgcn_s_setprio(0); } while (0)
; #define PG8_WAIT_V(n) asm volatile("s_waitcnt vmcnt(" #n ")" ::: "memory")
; #define PG8_WAIT_L(n) asm volatile("s_waitcnt lgkmcnt(" #n ")" ::: "memory")
; template <class Epi, class Sched, bool ALIGN_EPI = false, bool SP2 = false>
; __device__ __forceinline__ void gemm_phase(PG8_LAS unsigned char* lds, const Gemm g, const Sched& S, const Epi& E) {
;     ...
;             const bool last = (t == nt - 2);
;             const char* a1 = cA + (size_t)(t + 1) * kstep;
;             const char* a2 = last ? nA : cA + (size_t)(t + 2) * kstep; const char* b2 = last ? nB : cB + (size_t)(t + 2) * kstep;
;             const char* a3 = a2 + kstep; const char* b3 = b2 + kstep;
;             if (last && has_next) S.a_ready(nxt);
;             if constexpr (SP2) {
;             PG8_LDB(B0, 0, 0); PG8_LDB(B1, 0, 1); PG8_SCHED; PG8_LDA(At, 0, 0); PG8_STAGE(PG8_SA(1, 1), a1 + hstep, voffA);
;             PG8_WAIT_V(8); PG8_WAIT_L(0); PG8_BAR; PG8_MMA(0, 0, At, B0); PG8_MMA(0, 1, At, B1); PG8_BAR; PG8_SCHED;
;             PG8_LDA(At, 0, 1); PG8_STAGE(PG8_SB(0, 0), b2, voffB); PG8_STAGE(PG8_SB(0, 1), b2 + hstep, voffB); PG8_STAGE(PG8_SA(0, 0), a2, voffA);
;             PG8_WAIT_V(8); PG8_WAIT_L(0); PG8_BAR; PG8_MMA(1, 0, At, B0); PG8_MMA(1, 1, At, B1); PG8_BAR; PG8_SCHED;
.LBB0_1062:
	s_add_u32 s36, s34, 0xfffc0080
	s_addc_u32 s37, s35, -1
	s_add_i32 s59, 0, 0x10000
	s_cmp_eq_u32 s58, 12
	s_cselect_b32 s39, s23, s37
	s_cselect_b32 s38, s29, s36
	s_cselect_b32 s37, s21, s57
	s_cselect_b32 s36, s31, s56
	s_add_i32 s62, 0, 0x14000
	v_add_u32_e32 v142, s59, v179
	v_add_u32_e32 v170, s62, v179
	ds_read_b128 v[130:133], v142
	ds_read_b128 v[134:137], v142 offset:1024
	ds_read_b128 v[138:141], v142 offset:2048
	ds_read_b128 v[142:145], v142 offset:3072
	ds_read_b128 v[146:149], v170
	ds_read_b128 v[150:153], v170 offset:1024
	ds_read_b128 v[166:169], v170 offset:2048
	ds_read_b128 v[170:173], v170 offset:3072
	v_lshl_add_u64 v[212:213], s[34:35], 0, v[162:163]
	s_add_i32 m0, s46, 0xc000
	ds_read_b128 v[174:177], v187
	ds_read_b128 v[180:183], v187 offset:1024
	ds_read_b128 v[188:191], v187 offset:2048
	ds_read_b128 v[192:195], v187 offset:3072
	ds_read_b128 v[196:199], v187 offset:4096
	ds_read_b128 v[200:203], v187 offset:5120
	ds_read_b128 v[204:207], v187 offset:6144
	ds_read_b128 v[208:211], v187 offset:7168
	global_load_lds_dwordx4 v[212:213], off
	v_lshl_add_u64 v[212:213], s[34:35], 0, v[164:165]
	s_add_i32 m0, s46, 0xe000
	s_nop 0
	global_load_lds_dwordx4 v[212:213], off
	s_waitcnt vmcnt(8)
	s_waitcnt lgkmcnt(0)
	s_setprio 1
	s_barrier
	v_mfma_f32_16x16x32_bf16 v[126:129], v[130:133], v[174:177], v[126:129]
	v_mfma_f32_16x16x32_bf16 v[122:125], v[138:141], v[174:177], v[122:125]
	v_mfma_f32_16x16x32_bf16 v[110:113], v[130:133], v[188:191], v[110:113]
	v_mfma_f32_16x16x32_bf16 v[106:109], v[138:141], v[188:191], v[106:109]
	v_mfma_f32_16x16x32_bf16 v[94:97], v[130:133], v[196:199], v[94:97]
	v_mfma_f32_16x16x32_bf16 v[90:93], v[138:141], v[196:199], v[90:93]
	v_mfma_f32_16x16x32_bf16 v[78:81], v[130:133], v[204:207], v[78:81]
	v_mfma_f32_16x16x32_bf16 v[74:77], v[138:141], v[204:207], v[74:77]
	v_mfma_f32_16x16x32_bf16 v[126:129], v[134:137], v[180:183], v[126:129]
	v_mfma_f32_16x16x32_bf16 v[122:125], v[142:145], v[180:183], v[122:125]
	v_mfma_f32_16x16x32_bf16 v[110:113], v[134:137], v[192:195], v[110:113]
	v_mfma_f32_16x16x32_bf16 v[106:109], v[142:145], v[192:195], v[106:109]
	v_mfma_f32_16x16x32_bf16 v[94:97], v[134:137], v[200:203], v[94:97]
	v_mfma_f32_16x16x32_bf16 v[90:93], v[142:145], v[200:203], v[90:93]
	v_mfma_f32_16x16x32_bf16 v[78:81], v[134:137], v[208:211], v[78:81]
	v_mfma_f32_16x16x32_bf16 v[74:77], v[142:145], v[208:211], v[74:77]
	s_setprio 0
	s_setprio 1
	v_mfma_f32_16x16x32_bf16 v[118:121], v[146:149], v[174:177], v[118:121]
	v_mfma_f32_16x16x32_bf16 v[114:117], v[166:169], v[174:177], v[114:117]
	v_mfma_f32_16x16x32_bf16 v[102:105], v[146:149], v[188:191], v[102:105]
	v_mfma_f32_16x16x32_bf16 v[98:101], v[166:169], v[188:191], v[98:101]
	v_mfma_f32_16x16x32_bf16 v[86:89], v[146:149], v[196:199], v[86:89]
	v_mfma_f32_16x16x32_bf16 v[82:85], v[166:169], v[196:199], v[82:85]
	v_mfma_f32_16x16x32_bf16 v[70:73], v[146:149], v[204:207], v[70:73]
	v_mfma_f32_16x16x32_bf16 v[66:69], v[166:169], v[204:207], v[66:69]
	v_mfma_f32_16x16x32_bf16 v[118:121], v[150:153], v[180:183], v[118:121]
	v_mfma_f32_16x16x32_bf16 v[114:117], v[170:173], v[180:183], v[114:117]
	v_mfma_f32_16x16x32_bf16 v[102:105], v[150:153], v[192:195], v[102:105]
	v_mfma_f32_16x16x32_bf16 v[98:101], v[170:173], v[192:195], v[98:101]
	v_mfma_f32_16x16x32_bf16 v[86:89], v[150:153], v[200:203], v[86:89]
	v_mfma_f32_16x16x32_bf16 v[82:85], v[170:173], v[200:203], v[82:85]
	v_mfma_f32_16x16x32_bf16 v[70:73], v[150:153], v[208:211], v[70:73]
	v_mfma_f32_16x16x32_bf16 v[66:69], v[170:173], v[208:211], v[66:69]
	s_barrier
	s_setprio 0
	s_add_i32 s59, s59, s33
	v_lshl_add_u64 v[212:213], s[36:37], 0, v[156:157]
	s_mov_b32 m0, s59
	ds_read_b128 v[174:177], v187 offset:16384
	ds_read_b128 v[180:183], v187 offset:17408
	ds_read_b128 v[188:191], v187 offset:18432
	ds_read_b128 v[192:195], v187 offset:19456
	ds_read_b128 v[196:199], v187 offset:20480
	ds_read_b128 v[200:203], v187 offset:21504
	ds_read_b128 v[204:207], v187 offset:22528
	ds_read_b128 v[208:211], v187 offset:23552
	global_load_lds_dwordx4 v[212:213], off
	s_add_i32 m0, s59, 0x2000
	s_add_u32 s60, s36, 0x40000
	v_lshl_add_u64 v[214:215], s[36:37], 0, v[160:161]
	s_addc_u32 s61, s37, 0
	s_add_i32 s59, s62, s33
	global_load_lds_dwordx4 v[214:215], off
	v_lshl_add_u64 v[216:217], s[60:61], 0, v[156:157]
	s_mov_b32 m0, s59
	v_lshl_add_u64 v[218:219], s[38:39], 0, v[158:159]
	global_load_lds_dwordx4 v[216:217], off
	v_lshl_add_u64 v[216:217], s[60:61], 0, v[160:161]
	s_add_i32 m0, s59, 0x2000
	s_nop 0
	global_load_lds_dwordx4 v[216:217], off
	v_lshl_add_u64 v[216:217], s[38:39], 0, v[154:155]
	s_mov_b32 m0, s46
	s_nop 0
	global_load_lds_dwordx4 v[216:217], off
	s_mov_b32 m0, s47
	s_nop 0
	global_load_lds_dwordx4 v[218:219], off
	s_waitcnt vmcnt(8)
	s_waitcnt lgkmcnt(0)
	s_setprio 1
	s_barrier
; #define PG8_STAGE(bufoff, gbase, voff) do { _Pragma("unroll") for (int _i = 0; _i < 2; ++_i) \
;         __builtin_amdgcn_global_load_lds((const unsigned*)((const char*)(gbase) + (voff)[_i]), (PG8_LAS unsigned*)(lds + (bufoff) + ldsw + _i * 8192), 16, 0, 0); } while (0)
; #define PG8_LDA(dst, b, h) do { _Pragma("unroll") for (int m = 0; m < 4; ++m) _Pragma("unroll") for (int k = 0; k < 2; ++k) dst[m][k] = *(const PG8_LAS bf16x8*)(lds + PG8_SA(b, h) + aoff + m * 2048 + k * 1024); } while (0)
; #define PG8_LDB(dst, b, h) do { _Pragma("unroll") for (int n = 0; n < 2; ++n) _Pragma("unroll") for (int k = 0; k < 2; ++k) dst[n][k] = *(const PG8_LAS bf16x8*)(lds + PG8_SB(b, h) + boff + n * 2048 + k * 1024); } while (0)
; #define PG8_MMA(ai, bj, At, Bt) do { __builtin_amdgcn_s_setprio(1); _Pragma("unroll") for (int m = 0; m < 4; ++m) _Pragma("unroll") for (int n = 0; n < 2; ++n) _Pragma("unroll") for (int k = 0; k < 2; ++k) \
;         acc[ai][bj][m][n] = __builtin_amdgcn_mfma_f32_16x16x32_bf16(Bt[n][k], At[m][k], acc[ai][bj][m][n], 0, 0, 0); __builtin_amdgcn_s_setprio(0); } while (0)
; #define PG8_WAIT_V(n) asm volatile("s_waitcnt vmcnt(" #n ")" ::: "memory")
; #define PG8_WAIT_L(n) asm volatile("s_waitcnt lgkmcnt(" #n ")" ::: "memory")
; #define PG8_BAR __builtin_amdgcn_s_barrier()
; #define PG8_SCHED __builtin_amdgcn_sched_barrier(0)
; template <class Epi, class Sched, bool ALIGN_EPI = false, bool SP2 = false>
; __device__ __forceinline__ void gemm_phase(PG8_LAS unsigned char* lds, const Gemm g, const Sched& S, const Epi& E) {
;     ...
;             PG8_WAIT_V(8); PG8_WAIT_L(0); PG8_BAR; PG8_MMA(1, 0, At, B0); PG8_MMA(1, 1, At, B1); PG8_BAR; PG8_SCHED;
;             PG8_LDB(B0, 1, 0); PG8_LDB(B1, 1, 1); PG8_SCHED; PG8_LDA(At, 1, 0); PG8_STAGE(PG8_SA(0, 1), a2 + hstep, voffA);
;             PG8_WAIT_V(8); PG8_WAIT_L(0); PG8_BAR; PG8_MMA(0, 0, At, B0); PG8_MMA(0, 1, At, B1); PG8_BAR; PG8_SCHED;
;             PG8_LDA(At, 1, 1); PG8_STAGE(PG8_SB(1, 0), b3, voffB); PG8_STAGE(PG8_SB(1, 1), b3 + hstep, voffB); PG8_STAGE(PG8_SA(1, 0), a3, voffA);
;             PG8_WAIT_V(8); PG8_WAIT_L(0); PG8_BAR; PG8_MMA(1, 0, At, B0); PG8_MMA(1, 1, At, B1); PG8_BAR; PG8_SCHED;
	v_mfma_f32_16x16x32_bf16 v[62:65], v[130:133], v[174:177], v[62:65]
	v_mfma_f32_16x16x32_bf16 v[58:61], v[138:141], v[174:177], v[58:61]
	v_mfma_f32_16x16x32_bf16 v[46:49], v[130:133], v[188:191], v[46:49]
	v_mfma_f32_16x16x32_bf16 v[42:45], v[138:141], v[188:191], v[42:45]
	v_mfma_f32_16x16x32_bf16 v[30:33], v[130:133], v[196:199], v[30:33]
	v_mfma_f32_16x16x32_bf16 v[26:29], v[138:141], v[196:199], v[26:29]
	v_mfma_f32_16x16x32_bf16 v[14:17], v[130:133], v[204:207], v[14:17]
	v_mfma_f32_16x16x32_bf16 v[10:13], v[138:141], v[204:207], v[10:13]
	v_mfma_f32_16x16x32_bf16 v[62:65], v[134:137], v[180:183], v[62:65]
	v_mfma_f32_16x16x32_bf16 v[58:61], v[142:145], v[180:183], v[58:61]
	v_mfma_f32_16x16x32_bf16 v[46:49], v[134:137], v[192:195], v[46:49]
	v_mfma_f32_16x16x32_bf16 v[42:45], v[142:145], v[192:195], v[42:45]
	v_mfma_f32_16x16x32_bf16 v[30:33], v[134:137], v[200:203], v[30:33]
	v_mfma_f32_16x16x32_bf16 v[26:29], v[142:145], v[200:203], v[26:29]
	v_mfma_f32_16x16x32_bf16 v[14:17], v[134:137], v[208:211], v[14:17]
	v_mfma_f32_16x16x32_bf16 v[10:13], v[142:145], v[208:211], v[10:13]
	s_setprio 0
	s_setprio 1
	v_mfma_f32_16x16x32_bf16 v[54:57], v[146:149], v[174:177], v[54:57]
	v_mfma_f32_16x16x32_bf16 v[50:53], v[166:169], v[174:177], v[50:53]
	v_mfma_f32_16x16x32_bf16 v[38:41], v[146:149], v[188:191], v[38:41]
	v_mfma_f32_16x16x32_bf16 v[34:37], v[166:169], v[188:191], v[34:37]
	v_mfma_f32_16x16x32_bf16 v[22:25], v[146:149], v[196:199], v[22:25]
	v_mfma_f32_16x16x32_bf16 v[18:21], v[166:169], v[196:199], v[18:21]
	v_mfma_f32_16x16x32_bf16 v[6:9], v[146:149], v[204:207], v[6:9]
	v_mfma_f32_16x16x32_bf16 v[2:5], v[166:169], v[204:207], v[2:5]
	v_mfma_f32_16x16x32_bf16 v[54:57], v[150:153], v[180:183], v[54:57]
	v_mfma_f32_16x16x32_bf16 v[50:53], v[170:173], v[180:183], v[50:53]
	v_mfma_f32_16x16x32_bf16 v[38:41], v[150:153], v[192:195], v[38:41]
	v_mfma_f32_16x16x32_bf16 v[34:37], v[170:173], v[192:195], v[34:37]
	v_mfma_f32_16x16x32_bf16 v[22:25], v[150:153], v[200:203], v[22:25]
	v_mfma_f32_16x16x32_bf16 v[18:21], v[170:173], v[200:203], v[18:21]
	v_mfma_f32_16x16x32_bf16 v[6:9], v[150:153], v[208:211], v[6:9]
	v_mfma_f32_16x16x32_bf16 v[2:5], v[170:173], v[208:211], v[2:5]
	s_barrier
	s_setprio 0
	s_add_i32 s59, 0, 0x18000
	s_add_i32 s60, 0, 0x1c000
	v_add_u32_e32 v142, s59, v179
	v_add_u32_e32 v170, s60, v179
	ds_read_b128 v[130:133], v142
	ds_read_b128 v[134:137], v142 offset:1024
	ds_read_b128 v[138:141], v142 offset:2048
	ds_read_b128 v[142:145], v142 offset:3072
	ds_read_b128 v[146:149], v170
	ds_read_b128 v[150:153], v170 offset:1024
	ds_read_b128 v[166:169], v170 offset:2048
	ds_read_b128 v[170:173], v170 offset:3072
	s_add_u32 s38, s38, 0x40000
	s_addc_u32 s39, s39, 0
	s_mov_b32 m0, s48
	v_lshl_add_u64 v[220:221], s[38:39], 0, v[154:155]
	ds_read_b128 v[174:177], v187 offset:32768
	ds_read_b128 v[180:183], v187 offset:33792
	ds_read_b128 v[188:191], v187 offset:34816
	ds_read_b128 v[192:195], v187 offset:35840
	ds_read_b128 v[196:199], v187 offset:36864
	ds_read_b128 v[200:203], v187 offset:37888
	ds_read_b128 v[204:207], v187 offset:38912
	ds_read_b128 v[208:211], v187 offset:39936
	global_load_lds_dwordx4 v[220:221], off
	v_lshl_add_u64 v[220:221], s[38:39], 0, v[158:159]
	s_mov_b32 m0, s49
	s_nop 0
	global_load_lds_dwordx4 v[220:221], off
	s_waitcnt vmcnt(8)
	s_waitcnt lgkmcnt(0)
	s_setprio 1
	s_barrier
	v_mfma_f32_16x16x32_bf16 v[126:129], v[130:133], v[174:177], v[126:129]
	v_mfma_f32_16x16x32_bf16 v[122:125], v[138:141], v[174:177], v[122:125]
	v_mfma_f32_16x16x32_bf16 v[110:113], v[130:133], v[188:191], v[110:113]
	v_mfma_f32_16x16x32_bf16 v[106:109], v[138:141], v[188:191], v[106:109]
	v_mfma_f32_16x16x32_bf16 v[94:97], v[130:133], v[196:199], v[94:97]
	v_mfma_f32_16x16x32_bf16 v[90:93], v[138:141], v[196:199], v[90:93]
	v_mfma_f32_16x16x32_bf16 v[78:81], v[130:133], v[204:207], v[78:81]
	v_mfma_f32_16x16x32_bf16 v[74:77], v[138:141], v[204:207], v[74:77]
	v_mfma_f32_16x16x32_bf16 v[126:129], v[134:137], v[180:183], v[126:129]
	v_mfma_f32_16x16x32_bf16 v[122:125], v[142:145], v[180:183], v[122:125]
	v_mfma_f32_16x16x32_bf16 v[110:113], v[134:137], v[192:195], v[110:113]
	v_mfma_f32_16x16x32_bf16 v[106:109], v[142:145], v[192:195], v[106:109]
	v_mfma_f32_16x16x32_bf16 v[94:97], v[134:137], v[200:203], v[94:97]
	v_mfma_f32_16x16x32_bf16 v[90:93], v[142:145], v[200:203], v[90:93]
	v_mfma_f32_16x16x32_bf16 v[78:81], v[134:137], v[208:211], v[78:81]
	v_mfma_f32_16x16x32_bf16 v[74:77], v[142:145], v[208:211], v[74:77]
	s_setprio 0
	s_setprio 1
	v_mfma_f32_16x16x32_bf16 v[118:121], v[146:149], v[174:177], v[118:121]
	v_mfma_f32_16x16x32_bf16 v[114:117], v[166:169], v[174:177], v[114:117]
	v_mfma_f32_16x16x32_bf16 v[102:105], v[146:149], v[188:191], v[102:105]
	v_mfma_f32_16x16x32_bf16 v[98:101], v[166:169], v[188:191], v[98:101]
	v_mfma_f32_16x16x32_bf16 v[86:89], v[146:149], v[196:199], v[86:89]
	v_mfma_f32_16x16x32_bf16 v[82:85], v[166:169], v[196:199], v[82:85]
	v_mfma_f32_16x16x32_bf16 v[70:73], v[146:149], v[204:207], v[70:73]
	v_mfma_f32_16x16x32_bf16 v[66:69], v[166:169], v[204:207], v[66:69]
	v_mfma_f32_16x16x32_bf16 v[118:121], v[150:153], v[180:183], v[118:121]
	v_mfma_f32_16x16x32_bf16 v[114:117], v[170:173], v[180:183], v[114:117]
	v_mfma_f32_16x16x32_bf16 v[102:105], v[150:153], v[192:195], v[102:105]
	v_mfma_f32_16x16x32_bf16 v[98:101], v[170:173], v[192:195], v[98:101]
	v_mfma_f32_16x16x32_bf16 v[86:89], v[150:153], v[200:203], v[86:89]
	v_mfma_f32_16x16x32_bf16 v[82:85], v[170:173], v[200:203], v[82:85]
	v_mfma_f32_16x16x32_bf16 v[70:73], v[150:153], v[208:211], v[70:73]
	v_mfma_f32_16x16x32_bf16 v[66:69], v[170:173], v[208:211], v[66:69]
	s_barrier
; #define PG8_STAGE(bufoff, gbase, voff) do { _Pragma("unroll") for (int _i = 0; _i < 2; ++_i) \
;         __builtin_amdgcn_global_load_lds((const unsigned*)((const char*)(gbase) + (voff)[_i]), (PG8_LAS unsigned*)(lds + (bufoff) + ldsw + _i * 8192), 16, 0, 0); } while (0)
; #define PG8_LDA(dst, b, h) do { _Pragma("unroll") for (int m = 0; m < 4; ++m) _Pragma("unroll") for (int k = 0; k < 2; ++k) dst[m][k] = *(const PG8_LAS bf16x8*)(lds + PG8_SA(b, h) + aoff + m * 2048 + k * 1024); } while (0)
; #define PG8_MMA(ai, bj, At, Bt) do { __builtin_amdgcn_s_setprio(1); _Pragma("unroll") for (int m = 0; m < 4; ++m) _Pragma("unroll") for (int n = 0; n < 2; ++n) _Pragma("unroll") for (int k = 0; k < 2; ++k) \
;         acc[ai][bj][m][n] = __builtin_amdgcn_mfma_f32_16x16x32_bf16(Bt[n][k], At[m][k], acc[ai][bj][m][n], 0, 0, 0); __builtin_amdgcn_s_setprio(0); } while (0)
; #define PG8_WAIT_V(n) asm volatile("s_waitcnt vmcnt(" #n ")" ::: "memory")
; #define PG8_WAIT_L(n) asm volatile("s_waitcnt lgkmcnt(" #n ")" ::: "memory")
; #define PG8_BAR __builtin_amdgcn_s_barrier()
; #define PG8_SCHED __builtin_amdgcn_sched_barrier(0)
; template <class Epi, class Sched, bool ALIGN_EPI = false, bool SP2 = false>
; __device__ __forceinline__ void gemm_phase(PG8_LAS unsigned char* lds, const Gemm g, const Sched& S, const Epi& E) {
;     ...
;             PG8_WAIT_V(8); PG8_WAIT_L(0); PG8_BAR; PG8_MMA(0, 0, At, B0); PG8_MMA(0, 1, At, B1); PG8_BAR; PG8_SCHED;
;             PG8_LDA(At, 1, 1); PG8_STAGE(PG8_SB(1, 0), b3, voffB); PG8_STAGE(PG8_SB(1, 1), b3 + hstep, voffB); PG8_STAGE(PG8_SA(1, 0), a3, voffA);
;             PG8_WAIT_V(8); PG8_WAIT_L(0); PG8_BAR; PG8_MMA(1, 0, At, B0); PG8_MMA(1, 1, At, B1); PG8_BAR; PG8_SCHED;
	s_setprio 0
	s_add_i32 s38, s59, s33
	v_lshl_add_u64 v[212:213], v[212:213], 0, s[80:81]
	s_mov_b32 m0, s38
	ds_read_b128 v[174:177], v187 offset:49152
	ds_read_b128 v[180:183], v187 offset:50176
	ds_read_b128 v[188:191], v187 offset:51200
	ds_read_b128 v[192:195], v187 offset:52224
	ds_read_b128 v[196:199], v187 offset:53248
	ds_read_b128 v[200:203], v187 offset:54272
	ds_read_b128 v[204:207], v187 offset:55296
	ds_read_b128 v[208:211], v187 offset:56320
	global_load_lds_dwordx4 v[212:213], off
	s_add_i32 m0, s38, 0x2000
	s_add_u32 s36, s36, 0x40080
	v_lshl_add_u64 v[212:213], v[214:215], 0, s[80:81]
	s_addc_u32 s37, s37, 0
	s_add_i32 s38, s60, s33
	global_load_lds_dwordx4 v[212:213], off
	v_lshl_add_u64 v[212:213], s[36:37], 0, v[156:157]
	s_mov_b32 m0, s38
	s_nop 0
	global_load_lds_dwordx4 v[212:213], off
	v_lshl_add_u64 v[212:213], s[36:37], 0, v[160:161]
	s_add_i32 m0, s38, 0x2000
	s_nop 0
	global_load_lds_dwordx4 v[212:213], off
	v_lshl_add_u64 v[212:213], v[216:217], 0, s[80:81]
	s_mov_b32 m0, s51
	s_nop 0
	global_load_lds_dwordx4 v[212:213], off
	v_lshl_add_u64 v[212:213], v[218:219], 0, s[80:81]
	s_mov_b32 m0, s52
	s_nop 0
	global_load_lds_dwordx4 v[212:213], off
	s_waitcnt vmcnt(8)
	s_waitcnt lgkmcnt(0)
	s_setprio 1
	s_barrier
	v_mfma_f32_16x16x32_bf16 v[62:65], v[130:133], v[174:177], v[62:65]
	v_mfma_f32_16x16x32_bf16 v[58:61], v[138:141], v[174:177], v[58:61]
	v_mfma_f32_16x16x32_bf16 v[46:49], v[130:133], v[188:191], v[46:49]
	v_mfma_f32_16x16x32_bf16 v[42:45], v[138:141], v[188:191], v[42:45]
	v_mfma_f32_16x16x32_bf16 v[30:33], v[130:133], v[196:199], v[30:33]
	v_mfma_f32_16x16x32_bf16 v[26:29], v[138:141], v[196:199], v[26:29]
	v_mfma_f32_16x16x32_bf16 v[14:17], v[130:133], v[204:207], v[14:17]
	v_mfma_f32_16x16x32_bf16 v[10:13], v[138:141], v[204:207], v[10:13]
	v_mfma_f32_16x16x32_bf16 v[62:65], v[134:137], v[180:183], v[62:65]
	v_mfma_f32_16x16x32_bf16 v[58:61], v[142:145], v[180:183], v[58:61]
	v_mfma_f32_16x16x32_bf16 v[46:49], v[134:137], v[192:195], v[46:49]
	v_mfma_f32_16x16x32_bf16 v[42:45], v[142:145], v[192:195], v[42:45]
	v_mfma_f32_16x16x32_bf16 v[30:33], v[134:137], v[200:203], v[30:33]
	v_mfma_f32_16x16x32_bf16 v[26:29], v[142:145], v[200:203], v[26:29]
	v_mfma_f32_16x16x32_bf16 v[14:17], v[134:137], v[208:211], v[14:17]
	v_mfma_f32_16x16x32_bf16 v[10:13], v[142:145], v[208:211], v[10:13]
	s_setprio 0
	s_setprio 1
	v_mfma_f32_16x16x32_bf16 v[54:57], v[146:149], v[174:177], v[54:57]
	v_mfma_f32_16x16x32_bf16 v[50:53], v[166:169], v[174:177], v[50:53]
	v_mfma_f32_16x16x32_bf16 v[38:41], v[146:149], v[188:191], v[38:41]
	v_mfma_f32_16x16x32_bf16 v[34:37], v[166:169], v[188:191], v[34:37]
	v_mfma_f32_16x16x32_bf16 v[22:25], v[146:149], v[196:199], v[22:25]
	v_mfma_f32_16x16x32_bf16 v[18:21], v[166:169], v[196:199], v[18:21]
	v_mfma_f32_16x16x32_bf16 v[6:9], v[146:149], v[204:207], v[6:9]
	v_mfma_f32_16x16x32_bf16 v[2:5], v[166:169], v[204:207], v[2:5]
	v_mfma_f32_16x16x32_bf16 v[54:57], v[150:153], v[180:183], v[54:57]
	v_mfma_f32_16x16x32_bf16 v[50:53], v[170:173], v[180:183], v[50:53]
	v_mfma_f32_16x16x32_bf16 v[38:41], v[150:153], v[192:195], v[38:41]
	v_mfma_f32_16x16x32_bf16 v[34:37], v[170:173], v[192:195], v[34:37]
	v_mfma_f32_16x16x32_bf16 v[22:25], v[150:153], v[200:203], v[22:25]
	v_mfma_f32_16x16x32_bf16 v[18:21], v[170:173], v[200:203], v[18:21]
	v_mfma_f32_16x16x32_bf16 v[6:9], v[150:153], v[208:211], v[6:9]
	v_mfma_f32_16x16x32_bf16 v[2:5], v[170:173], v[208:211], v[2:5]
	s_barrier
	s_setprio 0
	s_add_i32 s58, s58, 2
	s_add_u32 s34, s34, 0x100
	s_addc_u32 s35, s35, 0
	s_add_u32 s56, s56, 0x100
	s_addc_u32 s57, s57, 0
	s_cmp_gt_u32 s58, 13
	s_cbranch_scc0 .LBB0_1062
	s_and_b64 vcc, exec, s[18:19]
	s_cbranch_vccz .LBB0_1065
	s_barrier

; #define PG8_STAGE(bufoff, gbase, voff) do { _Pragma("unroll") for (int _i = 0; _i < 2; ++_i) \
;         __builtin_amdgcn_global_load_lds((const unsigned*)((const char*)(gbase) + (voff)[_i]), (PG8_LAS unsigned*)(lds + (bufoff) + ldsw + _i * 8192), 16, 0, 0); } while (0)
; #define PG8_LDA(dst, b, h) do { _Pragma("unroll") for (int m = 0; m < 4; ++m) _Pragma("unroll") for (int k = 0; k < 2; ++k) dst[m][k] = *(const PG8_LAS bf16x8*)(lds + PG8_SA(b, h) + aoff + m * 2048 + k * 1024); } while (0)
; #define PG8_LDB(dst, b, h) do { _Pragma("unroll") for (int n = 0; n < 2; ++n) _Pragma("unroll") for (int k = 0; k < 2; ++k) dst[n][k] = *(const PG8_LAS bf16x8*)(lds + PG8_SB(b, h) + boff + n * 2048 + k * 1024); } while (0)
; #define PG8_MMA(ai, bj, At, Bt) do { __builtin_amdgcn_s_setprio(1); _Pragma("unroll") for (int m = 0; m < 4; ++m) _Pragma("unroll") for (int n = 0; n < 2; ++n) _Pragma("unroll") for (int k = 0; k < 2; ++k) \
;         acc[ai][bj][m][n] = __builtin_amdgcn_mfma_f32_16x16x32_bf16(Bt[n][k], At[m][k], acc[ai][bj][m][n], 0, 0, 0); __builtin_amdgcn_s_setprio(0); } while (0)
; #define PG8_WAIT_V(n) asm volatile("s_waitcnt vmcnt(" #n ")" ::: "memory")
; #define PG8_WAIT_L(n) asm volatile("s_waitcnt lgkmcnt(" #n ")" ::: "memory")
; template <class Epi, class Sched, bool ALIGN_EPI = false, bool SP2 = false>
; __device__ __forceinline__ void gemm_phase(PG8_LAS unsigned char* lds, const Gemm g, const Sched& S, const Epi& E) {
;     ...
;             const bool last = (t == nt - 2);
;             const char* a1 = cA + (size_t)(t + 1) * kstep;
;             const char* a2 = last ? nA : cA + (size_t)(t + 2) * kstep; const char* b2 = last ? nB : cB + (size_t)(t + 2) * kstep;
;             const char* a3 = a2 + kstep; const char* b3 = b2 + kstep;
;             if (last && has_next) S.a_ready(nxt);
;             if constexpr (SP2) {
;             PG8_LDB(B0, 0, 0); PG8_LDB(B1, 0, 1); PG8_SCHED; PG8_LDA(At, 0, 0); PG8_STAGE(PG8_SA(1, 1), a1 + hstep, voffA);
;             PG8_WAIT_V(8); PG8_WAIT_L(0); PG8_BAR; PG8_MMA(0, 0, At, B0); PG8_MMA(0, 1, At, B1); PG8_BAR; PG8_SCHED;
;             PG8_LDA(At, 0, 1); PG8_STAGE(PG8_SB(0, 0), b2, voffB); PG8_STAGE(PG8_SB(0, 1), b2 + hstep, voffB); PG8_STAGE(PG8_SA(0, 0), a2, voffA);
;             PG8_WAIT_V(8); PG8_WAIT_L(0); PG8_BAR; PG8_MMA(1, 0, At, B0); PG8_MMA(1, 1, At, B1); PG8_BAR; PG8_SCHED;
.LBB0_1106:
	s_add_u32 s30, s28, 0xfffc0080
	s_addc_u32 s31, s29, -1
	s_add_i32 s55, 0, 0x10000
	s_cmp_eq_u32 s54, 12
	s_cselect_b32 s35, s19, s31
	s_cselect_b32 s34, s25, s30
	s_cselect_b32 s31, s17, s53
	s_cselect_b32 s30, s27, s52
	s_add_i32 s58, 0, 0x14000
	v_add_u32_e32 v142, s55, v179
	v_add_u32_e32 v158, s58, v179
	ds_read_b128 v[130:133], v142
	ds_read_b128 v[134:137], v142 offset:1024
	ds_read_b128 v[138:141], v142 offset:2048
	ds_read_b128 v[142:145], v142 offset:3072
	ds_read_b128 v[146:149], v158
	ds_read_b128 v[150:153], v158 offset:1024
	ds_read_b128 v[154:157], v158 offset:2048
	ds_read_b128 v[158:161], v158 offset:3072
	v_lshl_add_u64 v[212:213], s[28:29], 0, v[194:195]
	s_add_i32 m0, s36, 0xc000
	ds_read_b128 v[162:165], v211
	ds_read_b128 v[166:169], v211 offset:1024
	ds_read_b128 v[170:173], v211 offset:2048
	ds_read_b128 v[174:177], v211 offset:3072
	ds_read_b128 v[180:183], v211 offset:4096
	ds_read_b128 v[198:201], v211 offset:5120
	ds_read_b128 v[202:205], v211 offset:6144
	ds_read_b128 v[206:209], v211 offset:7168
	global_load_lds_dwordx4 v[212:213], off
	v_lshl_add_u64 v[212:213], s[28:29], 0, v[196:197]
	s_add_i32 m0, s36, 0xe000
	s_nop 0
	global_load_lds_dwordx4 v[212:213], off
	s_waitcnt vmcnt(8)
	s_waitcnt lgkmcnt(0)
	s_setprio 1
	s_barrier
	v_mfma_f32_16x16x32_bf16 v[126:129], v[130:133], v[162:165], v[126:129]
	v_mfma_f32_16x16x32_bf16 v[122:125], v[138:141], v[162:165], v[122:125]
	v_mfma_f32_16x16x32_bf16 v[110:113], v[130:133], v[170:173], v[110:113]
	v_mfma_f32_16x16x32_bf16 v[106:109], v[138:141], v[170:173], v[106:109]
	v_mfma_f32_16x16x32_bf16 v[94:97], v[130:133], v[180:183], v[94:97]
	v_mfma_f32_16x16x32_bf16 v[90:93], v[138:141], v[180:183], v[90:93]
	v_mfma_f32_16x16x32_bf16 v[78:81], v[130:133], v[202:205], v[78:81]
	v_mfma_f32_16x16x32_bf16 v[74:77], v[138:141], v[202:205], v[74:77]
	v_mfma_f32_16x16x32_bf16 v[126:129], v[134:137], v[166:169], v[126:129]
	v_mfma_f32_16x16x32_bf16 v[122:125], v[142:145], v[166:169], v[122:125]
	v_mfma_f32_16x16x32_bf16 v[110:113], v[134:137], v[174:177], v[110:113]
	v_mfma_f32_16x16x32_bf16 v[106:109], v[142:145], v[174:177], v[106:109]
	v_mfma_f32_16x16x32_bf16 v[94:97], v[134:137], v[198:201], v[94:97]
	v_mfma_f32_16x16x32_bf16 v[90:93], v[142:145], v[198:201], v[90:93]
	v_mfma_f32_16x16x32_bf16 v[78:81], v[134:137], v[206:209], v[78:81]
	v_mfma_f32_16x16x32_bf16 v[74:77], v[142:145], v[206:209], v[74:77]
	s_setprio 0
	s_setprio 1
	v_mfma_f32_16x16x32_bf16 v[118:121], v[146:149], v[162:165], v[118:121]
	v_mfma_f32_16x16x32_bf16 v[114:117], v[154:157], v[162:165], v[114:117]
	v_mfma_f32_16x16x32_bf16 v[102:105], v[146:149], v[170:173], v[102:105]
	v_mfma_f32_16x16x32_bf16 v[98:101], v[154:157], v[170:173], v[98:101]
	v_mfma_f32_16x16x32_bf16 v[86:89], v[146:149], v[180:183], v[86:89]
	v_mfma_f32_16x16x32_bf16 v[82:85], v[154:157], v[180:183], v[82:85]
	v_mfma_f32_16x16x32_bf16 v[70:73], v[146:149], v[202:205], v[70:73]
	v_mfma_f32_16x16x32_bf16 v[66:69], v[154:157], v[202:205], v[66:69]
	v_mfma_f32_16x16x32_bf16 v[118:121], v[150:153], v[166:169], v[118:121]
	v_mfma_f32_16x16x32_bf16 v[114:117], v[158:161], v[166:169], v[114:117]
	v_mfma_f32_16x16x32_bf16 v[102:105], v[150:153], v[174:177], v[102:105]
	v_mfma_f32_16x16x32_bf16 v[98:101], v[158:161], v[174:177], v[98:101]
	v_mfma_f32_16x16x32_bf16 v[86:89], v[150:153], v[198:201], v[86:89]
	v_mfma_f32_16x16x32_bf16 v[82:85], v[158:161], v[198:201], v[82:85]
	v_mfma_f32_16x16x32_bf16 v[70:73], v[150:153], v[206:209], v[70:73]
	v_mfma_f32_16x16x32_bf16 v[66:69], v[158:161], v[206:209], v[66:69]
	s_barrier
	s_setprio 0
	s_add_i32 s55, s55, s33
	v_lshl_add_u64 v[212:213], s[30:31], 0, v[188:189]
	s_mov_b32 m0, s55
	ds_read_b128 v[162:165], v211 offset:16384
	ds_read_b128 v[166:169], v211 offset:17408
	ds_read_b128 v[170:173], v211 offset:18432
	ds_read_b128 v[174:177], v211 offset:19456
	ds_read_b128 v[180:183], v211 offset:20480
	ds_read_b128 v[198:201], v211 offset:21504
	ds_read_b128 v[202:205], v211 offset:22528
	ds_read_b128 v[206:209], v211 offset:23552
	global_load_lds_dwordx4 v[212:213], off
	s_add_i32 m0, s55, 0x2000
	s_add_u32 s56, s30, 0x40000
	v_lshl_add_u64 v[214:215], s[30:31], 0, v[192:193]
	s_addc_u32 s57, s31, 0
	s_add_i32 s55, s58, s33
	global_load_lds_dwordx4 v[214:215], off
	v_lshl_add_u64 v[216:217], s[56:57], 0, v[188:189]
	s_mov_b32 m0, s55
	v_lshl_add_u64 v[218:219], s[34:35], 0, v[190:191]
	global_load_lds_dwordx4 v[216:217], off
	v_lshl_add_u64 v[216:217], s[56:57], 0, v[192:193]
	s_add_i32 m0, s55, 0x2000
	s_nop 0
	global_load_lds_dwordx4 v[216:217], off
	v_lshl_add_u64 v[216:217], s[34:35], 0, v[186:187]
	s_mov_b32 m0, s36
	s_nop 0
	global_load_lds_dwordx4 v[216:217], off
	s_mov_b32 m0, s37
	s_nop 0
	global_load_lds_dwordx4 v[218:219], off
	s_waitcnt vmcnt(8)
	s_waitcnt lgkmcnt(0)
	s_setprio 1
	s_barrier
; #define PG8_STAGE(bufoff, gbase, voff) do { _Pragma("unroll") for (int _i = 0; _i < 2; ++_i) \
;         __builtin_amdgcn_global_load_lds((const unsigned*)((const char*)(gbase) + (voff)[_i]), (PG8_LAS unsigned*)(lds + (bufoff) + ldsw + _i * 8192), 16, 0, 0); } while (0)
; #define PG8_LDA(dst, b, h) do { _Pragma("unroll") for (int m = 0; m < 4; ++m) _Pragma("unroll") for (int k = 0; k < 2; ++k) dst[m][k] = *(const PG8_LAS bf16x8*)(lds + PG8_SA(b, h) + aoff + m * 2048 + k * 1024); } while (0)
; #define PG8_LDB(dst, b, h) do { _Pragma("unroll") for (int n = 0; n < 2; ++n) _Pragma("unroll") for (int k = 0; k < 2; ++k) dst[n][k] = *(const PG8_LAS bf16x8*)(lds + PG8_SB(b, h) + boff + n * 2048 + k * 1024); } while (0)
; #define PG8_MMA(ai, bj, At, Bt) do { __builtin_amdgcn_s_setprio(1); _Pragma("unroll") for (int m = 0; m < 4; ++m) _Pragma("unroll") for (int n = 0; n < 2; ++n) _Pragma("unroll") for (int k = 0; k < 2; ++k) \
;         acc[ai][bj][m][n] = __builtin_amdgcn_mfma_f32_16x16x32_bf16(Bt[n][k], At[m][k], acc[ai][bj][m][n], 0, 0, 0); __builtin_amdgcn_s_setprio(0); } while (0)
; #define PG8_WAIT_V(n) asm volatile("s_waitcnt vmcnt(" #n ")" ::: "memory")
; #define PG8_WAIT_L(n) asm volatile("s_waitcnt lgkmcnt(" #n ")" ::: "memory")
; #define PG8_BAR __builtin_amdgcn_s_barrier()
; #define PG8_SCHED __builtin_amdgcn_sched_barrier(0)
; template <class Epi, class Sched, bool ALIGN_EPI = false, bool SP2 = false>
; __device__ __forceinline__ void gemm_phase(PG8_LAS unsigned char* lds, const Gemm g, const Sched& S, const Epi& E) {
;     ...
;             PG8_WAIT_V(8); PG8_WAIT_L(0); PG8_BAR; PG8_MMA(1, 0, At, B0); PG8_MMA(1, 1, At, B1); PG8_BAR; PG8_SCHED;
;             PG8_LDB(B0, 1, 0); PG8_LDB(B1, 1, 1); PG8_SCHED; PG8_LDA(At, 1, 0); PG8_STAGE(PG8_SA(0, 1), a2 + hstep, voffA);
;             PG8_WAIT_V(8); PG8_WAIT_L(0); PG8_BAR; PG8_MMA(0, 0, At, B0); PG8_MMA(0, 1, At, B1); PG8_BAR; PG8_SCHED;
;             PG8_LDA(At, 1, 1); PG8_STAGE(PG8_SB(1, 0), b3, voffB); PG8_STAGE(PG8_SB(1, 1), b3 + hstep, voffB); PG8_STAGE(PG8_SA(1, 0), a3, voffA);
;             PG8_WAIT_V(8); PG8_WAIT_L(0); PG8_BAR; PG8_MMA(1, 0, At, B0); PG8_MMA(1, 1, At, B1); PG8_BAR; PG8_SCHED;
	v_mfma_f32_16x16x32_bf16 v[62:65], v[130:133], v[162:165], v[62:65]
	v_mfma_f32_16x16x32_bf16 v[58:61], v[138:141], v[162:165], v[58:61]
	v_mfma_f32_16x16x32_bf16 v[46:49], v[130:133], v[170:173], v[46:49]
	v_mfma_f32_16x16x32_bf16 v[42:45], v[138:141], v[170:173], v[42:45]
	v_mfma_f32_16x16x32_bf16 v[30:33], v[130:133], v[180:183], v[30:33]
	v_mfma_f32_16x16x32_bf16 v[26:29], v[138:141], v[180:183], v[26:29]
	v_mfma_f32_16x16x32_bf16 v[14:17], v[130:133], v[202:205], v[14:17]
	v_mfma_f32_16x16x32_bf16 v[10:13], v[138:141], v[202:205], v[10:13]
	v_mfma_f32_16x16x32_bf16 v[62:65], v[134:137], v[166:169], v[62:65]
	v_mfma_f32_16x16x32_bf16 v[58:61], v[142:145], v[166:169], v[58:61]
	v_mfma_f32_16x16x32_bf16 v[46:49], v[134:137], v[174:177], v[46:49]
	v_mfma_f32_16x16x32_bf16 v[42:45], v[142:145], v[174:177], v[42:45]
	v_mfma_f32_16x16x32_bf16 v[30:33], v[134:137], v[198:201], v[30:33]
	v_mfma_f32_16x16x32_bf16 v[26:29], v[142:145], v[198:201], v[26:29]
	v_mfma_f32_16x16x32_bf16 v[14:17], v[134:137], v[206:209], v[14:17]
	v_mfma_f32_16x16x32_bf16 v[10:13], v[142:145], v[206:209], v[10:13]
	s_setprio 0
	s_setprio 1
	v_mfma_f32_16x16x32_bf16 v[54:57], v[146:149], v[162:165], v[54:57]
	v_mfma_f32_16x16x32_bf16 v[50:53], v[154:157], v[162:165], v[50:53]
	v_mfma_f32_16x16x32_bf16 v[38:41], v[146:149], v[170:173], v[38:41]
	v_mfma_f32_16x16x32_bf16 v[34:37], v[154:157], v[170:173], v[34:37]
	v_mfma_f32_16x16x32_bf16 v[22:25], v[146:149], v[180:183], v[22:25]
	v_mfma_f32_16x16x32_bf16 v[18:21], v[154:157], v[180:183], v[18:21]
	v_mfma_f32_16x16x32_bf16 v[6:9], v[146:149], v[202:205], v[6:9]
	v_mfma_f32_16x16x32_bf16 v[2:5], v[154:157], v[202:205], v[2:5]
	v_mfma_f32_16x16x32_bf16 v[54:57], v[150:153], v[166:169], v[54:57]
	v_mfma_f32_16x16x32_bf16 v[50:53], v[158:161], v[166:169], v[50:53]
	v_mfma_f32_16x16x32_bf16 v[38:41], v[150:153], v[174:177], v[38:41]
	v_mfma_f32_16x16x32_bf16 v[34:37], v[158:161], v[174:177], v[34:37]
	v_mfma_f32_16x16x32_bf16 v[22:25], v[150:153], v[198:201], v[22:25]
	v_mfma_f32_16x16x32_bf16 v[18:21], v[158:161], v[198:201], v[18:21]
	v_mfma_f32_16x16x32_bf16 v[6:9], v[150:153], v[206:209], v[6:9]
	v_mfma_f32_16x16x32_bf16 v[2:5], v[158:161], v[206:209], v[2:5]
	s_barrier
	s_setprio 0
	s_add_i32 s55, 0, 0x18000
	s_add_i32 s56, 0, 0x1c000
	v_add_u32_e32 v142, s55, v179
	v_add_u32_e32 v158, s56, v179
	ds_read_b128 v[130:133], v142
	ds_read_b128 v[134:137], v142 offset:1024
	ds_read_b128 v[138:141], v142 offset:2048
	ds_read_b128 v[142:145], v142 offset:3072
	ds_read_b128 v[146:149], v158
	ds_read_b128 v[150:153], v158 offset:1024
	ds_read_b128 v[154:157], v158 offset:2048
	ds_read_b128 v[158:161], v158 offset:3072
	s_add_u32 s34, s34, 0x40000
	s_addc_u32 s35, s35, 0
	s_mov_b32 m0, s38
	v_lshl_add_u64 v[220:221], s[34:35], 0, v[186:187]
	ds_read_b128 v[162:165], v211 offset:32768
	ds_read_b128 v[166:169], v211 offset:33792
	ds_read_b128 v[170:173], v211 offset:34816
	ds_read_b128 v[174:177], v211 offset:35840
	ds_read_b128 v[180:183], v211 offset:36864
	ds_read_b128 v[198:201], v211 offset:37888
	ds_read_b128 v[202:205], v211 offset:38912
	ds_read_b128 v[206:209], v211 offset:39936
	global_load_lds_dwordx4 v[220:221], off
	v_lshl_add_u64 v[220:221], s[34:35], 0, v[190:191]
	s_mov_b32 m0, s39
	s_nop 0
	global_load_lds_dwordx4 v[220:221], off
	s_waitcnt vmcnt(8)
	s_waitcnt lgkmcnt(0)
	s_setprio 1
	s_barrier
	v_mfma_f32_16x16x32_bf16 v[126:129], v[130:133], v[162:165], v[126:129]
	v_mfma_f32_16x16x32_bf16 v[122:125], v[138:141], v[162:165], v[122:125]
	v_mfma_f32_16x16x32_bf16 v[110:113], v[130:133], v[170:173], v[110:113]
	v_mfma_f32_16x16x32_bf16 v[106:109], v[138:141], v[170:173], v[106:109]
	v_mfma_f32_16x16x32_bf16 v[94:97], v[130:133], v[180:183], v[94:97]
	v_mfma_f32_16x16x32_bf16 v[90:93], v[138:141], v[180:183], v[90:93]
	v_mfma_f32_16x16x32_bf16 v[78:81], v[130:133], v[202:205], v[78:81]
	v_mfma_f32_16x16x32_bf16 v[74:77], v[138:141], v[202:205], v[74:77]
	v_mfma_f32_16x16x32_bf16 v[126:129], v[134:137], v[166:169], v[126:129]
	v_mfma_f32_16x16x32_bf16 v[122:125], v[142:145], v[166:169], v[122:125]
	v_mfma_f32_16x16x32_bf16 v[110:113], v[134:137], v[174:177], v[110:113]
	v_mfma_f32_16x16x32_bf16 v[106:109], v[142:145], v[174:177], v[106:109]
	v_mfma_f32_16x16x32_bf16 v[94:97], v[134:137], v[198:201], v[94:97]
	v_mfma_f32_16x16x32_bf16 v[90:93], v[142:145], v[198:201], v[90:93]
	v_mfma_f32_16x16x32_bf16 v[78:81], v[134:137], v[206:209], v[78:81]
	v_mfma_f32_16x16x32_bf16 v[74:77], v[142:145], v[206:209], v[74:77]
	s_setprio 0
	s_setprio 1
	v_mfma_f32_16x16x32_bf16 v[118:121], v[146:149], v[162:165], v[118:121]
	v_mfma_f32_16x16x32_bf16 v[114:117], v[154:157], v[162:165], v[114:117]
	v_mfma_f32_16x16x32_bf16 v[102:105], v[146:149], v[170:173], v[102:105]
	v_mfma_f32_16x16x32_bf16 v[98:101], v[154:157], v[170:173], v[98:101]
	v_mfma_f32_16x16x32_bf16 v[86:89], v[146:149], v[180:183], v[86:89]
	v_mfma_f32_16x16x32_bf16 v[82:85], v[154:157], v[180:183], v[82:85]
	v_mfma_f32_16x16x32_bf16 v[70:73], v[146:149], v[202:205], v[70:73]
	v_mfma_f32_16x16x32_bf16 v[66:69], v[154:157], v[202:205], v[66:69]
	v_mfma_f32_16x16x32_bf16 v[118:121], v[150:153], v[166:169], v[118:121]
	v_mfma_f32_16x16x32_bf16 v[114:117], v[158:161], v[166:169], v[114:117]
	v_mfma_f32_16x16x32_bf16 v[102:105], v[150:153], v[174:177], v[102:105]
	v_mfma_f32_16x16x32_bf16 v[98:101], v[158:161], v[174:177], v[98:101]
	v_mfma_f32_16x16x32_bf16 v[86:89], v[150:153], v[198:201], v[86:89]
	v_mfma_f32_16x16x32_bf16 v[82:85], v[158:161], v[198:201], v[82:85]
	v_mfma_f32_16x16x32_bf16 v[70:73], v[150:153], v[206:209], v[70:73]
	v_mfma_f32_16x16x32_bf16 v[66:69], v[158:161], v[206:209], v[66:69]
	s_barrier
; #define PG8_STAGE(bufoff, gbase, voff) do { _Pragma("unroll") for (int _i = 0; _i < 2; ++_i) \
;         __builtin_amdgcn_global_load_lds((const unsigned*)((const char*)(gbase) + (voff)[_i]), (PG8_LAS unsigned*)(lds + (bufoff) + ldsw + _i * 8192), 16, 0, 0); } while (0)
; #define PG8_LDA(dst, b, h) do { _Pragma("unroll") for (int m = 0; m < 4; ++m) _Pragma("unroll") for (int k = 0; k < 2; ++k) dst[m][k] = *(const PG8_LAS bf16x8*)(lds + PG8_SA(b, h) + aoff + m * 2048 + k * 1024); } while (0)
; #define PG8_MMA(ai, bj, At, Bt) do { __builtin_amdgcn_s_setprio(1); _Pragma("unroll") for (int m = 0; m < 4; ++m) _Pragma("unroll") for (int n = 0; n < 2; ++n) _Pragma("unroll") for (int k = 0; k < 2; ++k) \
;         acc[ai][bj][m][n] = __builtin_amdgcn_mfma_f32_16x16x32_bf16(Bt[n][k], At[m][k], acc[ai][bj][m][n], 0, 0, 0); __builtin_amdgcn_s_setprio(0); } while (0)
; #define PG8_WAIT_V(n) asm volatile("s_waitcnt vmcnt(" #n ")" ::: "memory")
; #define PG8_WAIT_L(n) asm volatile("s_waitcnt lgkmcnt(" #n ")" ::: "memory")
; #define PG8_BAR __builtin_amdgcn_s_barrier()
; #define PG8_SCHED __builtin_amdgcn_sched_barrier(0)
; template <class Epi, class Sched, bool ALIGN_EPI = false, bool SP2 = false>
; __device__ __forceinline__ void gemm_phase(PG8_LAS unsigned char* lds, const Gemm g, const Sched& S, const Epi& E) {
;     ...
;             PG8_WAIT_V(8); PG8_WAIT_L(0); PG8_BAR; PG8_MMA(0, 0, At, B0); PG8_MMA(0, 1, At, B1); PG8_BAR; PG8_SCHED;
;             PG8_LDA(At, 1, 1); PG8_STAGE(PG8_SB(1, 0), b3, voffB); PG8_STAGE(PG8_SB(1, 1), b3 + hstep, voffB); PG8_STAGE(PG8_SA(1, 0), a3, voffA);
;             PG8_WAIT_V(8); PG8_WAIT_L(0); PG8_BAR; PG8_MMA(1, 0, At, B0); PG8_MMA(1, 1, At, B1); PG8_BAR; PG8_SCHED;
	s_setprio 0
	s_add_i32 s34, s55, s33
	v_lshl_add_u64 v[212:213], v[212:213], 0, s[80:81]
	s_mov_b32 m0, s34
	ds_read_b128 v[162:165], v211 offset:49152
	ds_read_b128 v[166:169], v211 offset:50176
	ds_read_b128 v[170:173], v211 offset:51200
	ds_read_b128 v[174:177], v211 offset:52224
	ds_read_b128 v[180:183], v211 offset:53248
	ds_read_b128 v[198:201], v211 offset:54272
	ds_read_b128 v[202:205], v211 offset:55296
	ds_read_b128 v[206:209], v211 offset:56320
	global_load_lds_dwordx4 v[212:213], off
	s_add_i32 m0, s34, 0x2000
	s_add_u32 s30, s30, 0x40080
	v_lshl_add_u64 v[212:213], v[214:215], 0, s[80:81]
	s_addc_u32 s31, s31, 0
	s_add_i32 s34, s56, s33
	global_load_lds_dwordx4 v[212:213], off
	v_lshl_add_u64 v[212:213], s[30:31], 0, v[188:189]
	s_mov_b32 m0, s34
	s_nop 0
	global_load_lds_dwordx4 v[212:213], off
	v_lshl_add_u64 v[212:213], s[30:31], 0, v[192:193]
	s_add_i32 m0, s34, 0x2000
	s_nop 0
	global_load_lds_dwordx4 v[212:213], off
	v_lshl_add_u64 v[212:213], v[216:217], 0, s[80:81]
	s_mov_b32 m0, s47
	s_nop 0
	global_load_lds_dwordx4 v[212:213], off
	v_lshl_add_u64 v[212:213], v[218:219], 0, s[80:81]
	s_mov_b32 m0, s48
	s_nop 0
	global_load_lds_dwordx4 v[212:213], off
	s_waitcnt vmcnt(8)
	s_waitcnt lgkmcnt(0)
	s_setprio 1
	s_barrier
	v_mfma_f32_16x16x32_bf16 v[62:65], v[130:133], v[162:165], v[62:65]
	v_mfma_f32_16x16x32_bf16 v[58:61], v[138:141], v[162:165], v[58:61]
	v_mfma_f32_16x16x32_bf16 v[46:49], v[130:133], v[170:173], v[46:49]
	v_mfma_f32_16x16x32_bf16 v[42:45], v[138:141], v[170:173], v[42:45]
	v_mfma_f32_16x16x32_bf16 v[30:33], v[130:133], v[180:183], v[30:33]
	v_mfma_f32_16x16x32_bf16 v[26:29], v[138:141], v[180:183], v[26:29]
	v_mfma_f32_16x16x32_bf16 v[14:17], v[130:133], v[202:205], v[14:17]
	v_mfma_f32_16x16x32_bf16 v[10:13], v[138:141], v[202:205], v[10:13]
	v_mfma_f32_16x16x32_bf16 v[62:65], v[134:137], v[166:169], v[62:65]
	v_mfma_f32_16x16x32_bf16 v[58:61], v[142:145], v[166:169], v[58:61]
	v_mfma_f32_16x16x32_bf16 v[46:49], v[134:137], v[174:177], v[46:49]
	v_mfma_f32_16x16x32_bf16 v[42:45], v[142:145], v[174:177], v[42:45]
	v_mfma_f32_16x16x32_bf16 v[30:33], v[134:137], v[198:201], v[30:33]
	v_mfma_f32_16x16x32_bf16 v[26:29], v[142:145], v[198:201], v[26:29]
	v_mfma_f32_16x16x32_bf16 v[14:17], v[134:137], v[206:209], v[14:17]
	v_mfma_f32_16x16x32_bf16 v[10:13], v[142:145], v[206:209], v[10:13]
	s_setprio 0
	s_setprio 1
	v_mfma_f32_16x16x32_bf16 v[54:57], v[146:149], v[162:165], v[54:57]
	v_mfma_f32_16x16x32_bf16 v[50:53], v[154:157], v[162:165], v[50:53]
	v_mfma_f32_16x16x32_bf16 v[38:41], v[146:149], v[170:173], v[38:41]
	v_mfma_f32_16x16x32_bf16 v[34:37], v[154:157], v[170:173], v[34:37]
	v_mfma_f32_16x16x32_bf16 v[22:25], v[146:149], v[180:183], v[22:25]
	v_mfma_f32_16x16x32_bf16 v[18:21], v[154:157], v[180:183], v[18:21]
	v_mfma_f32_16x16x32_bf16 v[6:9], v[146:149], v[202:205], v[6:9]
	v_mfma_f32_16x16x32_bf16 v[2:5], v[154:157], v[202:205], v[2:5]
	v_mfma_f32_16x16x32_bf16 v[54:57], v[150:153], v[166:169], v[54:57]
	v_mfma_f32_16x16x32_bf16 v[50:53], v[158:161], v[166:169], v[50:53]
	v_mfma_f32_16x16x32_bf16 v[38:41], v[150:153], v[174:177], v[38:41]
	v_mfma_f32_16x16x32_bf16 v[34:37], v[158:161], v[174:177], v[34:37]
	v_mfma_f32_16x16x32_bf16 v[22:25], v[150:153], v[198:201], v[22:25]
	v_mfma_f32_16x16x32_bf16 v[18:21], v[158:161], v[198:201], v[18:21]
	v_mfma_f32_16x16x32_bf16 v[6:9], v[150:153], v[206:209], v[6:9]
	v_mfma_f32_16x16x32_bf16 v[2:5], v[158:161], v[206:209], v[2:5]
	s_barrier
	s_setprio 0
	s_add_i32 s54, s54, 2
	s_add_u32 s28, s28, 0x100
	s_addc_u32 s29, s29, 0
	s_add_u32 s52, s52, 0x100
	s_addc_u32 s53, s53, 0
	s_cmp_gt_u32 s54, 13
	s_cbranch_scc0 .LBB0_1106
	s_and_b64 vcc, exec, s[14:15]
	s_cbranch_vccz .LBB0_1109
	s_barrier

; #define PG8_STAGE(bufoff, gbase, voff) do { _Pragma("unroll") for (int _i = 0; _i < 2; ++_i) \
;         __builtin_amdgcn_global_load_lds((const unsigned*)((const char*)(gbase) + (voff)[_i]), (PG8_LAS unsigned*)(lds + (bufoff) + ldsw + _i * 8192), 16, 0, 0); } while (0)
; #define PG8_LDA(dst, b, h) do { _Pragma("unroll") for (int m = 0; m < 4; ++m) _Pragma("unroll") for (int k = 0; k < 2; ++k) dst[m][k] = *(const PG8_LAS bf16x8*)(lds + PG8_SA(b, h) + aoff + m * 2048 + k * 1024); } while (0)
; #define PG8_LDB(dst, b, h) do { _Pragma("unroll") for (int n = 0; n < 2; ++n) _Pragma("unroll") for (int k = 0; k < 2; ++k) dst[n][k] = *(const PG8_LAS bf16x8*)(lds + PG8_SB(b, h) + boff + n * 2048 + k * 1024); } while (0)
; #define PG8_MMA(ai, bj, At, Bt) do { __builtin_amdgcn_s_setprio(1); _Pragma("unroll") for (int m = 0; m < 4; ++m) _Pragma("unroll") for (int n = 0; n < 2; ++n) _Pragma("unroll") for (int k = 0; k < 2; ++k) \
;         acc[ai][bj][m][n] = __builtin_amdgcn_mfma_f32_16x16x32_bf16(Bt[n][k], At[m][k], acc[ai][bj][m][n], 0, 0, 0); __builtin_amdgcn_s_setprio(0); } while (0)
; #define PG8_WAIT_V(n) asm volatile("s_waitcnt vmcnt(" #n ")" ::: "memory")
; #define PG8_WAIT_L(n) asm volatile("s_waitcnt lgkmcnt(" #n ")" ::: "memory")
; template <class Epi, class Sched, bool ALIGN_EPI = false, bool SP2 = false>
; __device__ __forceinline__ void gemm_phase(PG8_LAS unsigned char* lds, const Gemm g, const Sched& S, const Epi& E) {
;     ...
;             const bool last = (t == nt - 2);
;             const char* a1 = cA + (size_t)(t + 1) * kstep;
;             const char* a2 = last ? nA : cA + (size_t)(t + 2) * kstep; const char* b2 = last ? nB : cB + (size_t)(t + 2) * kstep;
;             const char* a3 = a2 + kstep; const char* b3 = b2 + kstep;
;             if (last && has_next) S.a_ready(nxt);
;             if constexpr (SP2) {
;             PG8_LDB(B0, 0, 0); PG8_LDB(B1, 0, 1); PG8_SCHED; PG8_LDA(At, 0, 0); PG8_STAGE(PG8_SA(1, 1), a1 + hstep, voffA);
;             PG8_WAIT_V(8); PG8_WAIT_L(0); PG8_BAR; PG8_MMA(0, 0, At, B0); PG8_MMA(0, 1, At, B1); PG8_BAR; PG8_SCHED;
;             PG8_LDA(At, 0, 1); PG8_STAGE(PG8_SB(0, 0), b2, voffB); PG8_STAGE(PG8_SB(0, 1), b2 + hstep, voffB); PG8_STAGE(PG8_SA(0, 0), a2, voffA);
;             PG8_WAIT_V(8); PG8_WAIT_L(0); PG8_BAR; PG8_MMA(1, 0, At, B0); PG8_MMA(1, 1, At, B1); PG8_BAR; PG8_SCHED;
.LBB0_1249:
	s_add_u32 s26, s24, 0xfffc0080
	s_addc_u32 s27, s25, -1
	s_add_i32 s50, 0, 0x10000
	s_cmp_eq_u32 s49, 12
	s_cselect_b32 s29, s17, s27
	s_cselect_b32 s28, s45, s26
	v_add_u32_e32 v156, s50, v158
	s_cselect_b32 s27, s15, s48
	s_cselect_b32 s26, s46, s47
	s_add_i32 s52, 0, 0x14000
	ds_read_b128 v[66:69], v156
	ds_read_b128 v[118:121], v156 offset:1024
	ds_read_b128 v[152:155], v156 offset:2048
	ds_read_b128 v[162:165], v156 offset:3072
	v_add_u32_e32 v156, s52, v158
	ds_read_b128 v[166:169], v156
	ds_read_b128 v[170:173], v156 offset:1024
	ds_read_b128 v[174:177], v156 offset:2048
	ds_read_b128 v[180:183], v156 offset:3072
	v_lshl_add_u64 v[156:157], s[24:25], 0, v[148:149]
	s_add_i32 m0, s33, 0xc000
	ds_read_b128 v[186:189], v160
	ds_read_b128 v[190:193], v160 offset:1024
	ds_read_b128 v[194:197], v160 offset:2048
	ds_read_b128 v[198:201], v160 offset:3072
	ds_read_b128 v[202:205], v160 offset:4096
	ds_read_b128 v[206:209], v160 offset:5120
	ds_read_b128 v[210:213], v160 offset:6144
	ds_read_b128 v[214:217], v160 offset:7168
	global_load_lds_dwordx4 v[156:157], off
	v_lshl_add_u64 v[156:157], s[24:25], 0, v[150:151]
	s_add_i32 m0, s33, 0xe000
	s_nop 0
	global_load_lds_dwordx4 v[156:157], off
	s_waitcnt vmcnt(8)
	s_waitcnt lgkmcnt(0)
	s_setprio 1
	s_barrier
	v_mfma_f32_16x16x32_bf16 v[134:137], v[66:69], v[186:189], v[134:137]
	v_mfma_f32_16x16x32_bf16 v[126:129], v[152:155], v[186:189], v[126:129]
	v_mfma_f32_16x16x32_bf16 v[114:117], v[66:69], v[194:197], v[114:117]
	v_mfma_f32_16x16x32_bf16 v[110:113], v[152:155], v[194:197], v[110:113]
	v_mfma_f32_16x16x32_bf16 v[98:101], v[66:69], v[202:205], v[98:101]
	v_mfma_f32_16x16x32_bf16 v[94:97], v[152:155], v[202:205], v[94:97]
	v_mfma_f32_16x16x32_bf16 v[82:85], v[66:69], v[210:213], v[82:85]
	v_mfma_f32_16x16x32_bf16 v[78:81], v[152:155], v[210:213], v[78:81]
	v_mfma_f32_16x16x32_bf16 v[134:137], v[118:121], v[190:193], v[134:137]
	v_mfma_f32_16x16x32_bf16 v[126:129], v[162:165], v[190:193], v[126:129]
	v_mfma_f32_16x16x32_bf16 v[114:117], v[118:121], v[198:201], v[114:117]
	v_mfma_f32_16x16x32_bf16 v[110:113], v[162:165], v[198:201], v[110:113]
	v_mfma_f32_16x16x32_bf16 v[98:101], v[118:121], v[206:209], v[98:101]
	v_mfma_f32_16x16x32_bf16 v[94:97], v[162:165], v[206:209], v[94:97]
	v_mfma_f32_16x16x32_bf16 v[82:85], v[118:121], v[214:217], v[82:85]
	v_mfma_f32_16x16x32_bf16 v[78:81], v[162:165], v[214:217], v[78:81]
	s_setprio 0
	s_setprio 1
	v_mfma_f32_16x16x32_bf16 v[130:133], v[166:169], v[186:189], v[130:133]
	v_mfma_f32_16x16x32_bf16 v[122:125], v[174:177], v[186:189], v[122:125]
	v_mfma_f32_16x16x32_bf16 v[106:109], v[166:169], v[194:197], v[106:109]
	v_mfma_f32_16x16x32_bf16 v[102:105], v[174:177], v[194:197], v[102:105]
	v_mfma_f32_16x16x32_bf16 v[90:93], v[166:169], v[202:205], v[90:93]
	v_mfma_f32_16x16x32_bf16 v[86:89], v[174:177], v[202:205], v[86:89]
	v_mfma_f32_16x16x32_bf16 v[74:77], v[166:169], v[210:213], v[74:77]
	v_mfma_f32_16x16x32_bf16 v[70:73], v[174:177], v[210:213], v[70:73]
	v_mfma_f32_16x16x32_bf16 v[130:133], v[170:173], v[190:193], v[130:133]
	v_mfma_f32_16x16x32_bf16 v[122:125], v[180:183], v[190:193], v[122:125]
	v_mfma_f32_16x16x32_bf16 v[106:109], v[170:173], v[198:201], v[106:109]
	v_mfma_f32_16x16x32_bf16 v[102:105], v[180:183], v[198:201], v[102:105]
	v_mfma_f32_16x16x32_bf16 v[90:93], v[170:173], v[206:209], v[90:93]
	v_mfma_f32_16x16x32_bf16 v[86:89], v[180:183], v[206:209], v[86:89]
	v_mfma_f32_16x16x32_bf16 v[74:77], v[170:173], v[214:217], v[74:77]
	v_mfma_f32_16x16x32_bf16 v[70:73], v[180:183], v[214:217], v[70:73]
	s_barrier
	s_setprio 0
	s_add_i32 s50, s50, s36
	v_lshl_add_u64 v[156:157], s[26:27], 0, v[142:143]
	s_mov_b32 m0, s50
	ds_read_b128 v[186:189], v160 offset:16384
	ds_read_b128 v[190:193], v160 offset:17408
	ds_read_b128 v[194:197], v160 offset:18432
	ds_read_b128 v[198:201], v160 offset:19456
	ds_read_b128 v[202:205], v160 offset:20480
	ds_read_b128 v[206:209], v160 offset:21504
	ds_read_b128 v[210:213], v160 offset:22528
	ds_read_b128 v[214:217], v160 offset:23552
	global_load_lds_dwordx4 v[156:157], off
	s_add_i32 m0, s50, 0x2000
	s_add_u32 s50, s26, 0x40000
	v_lshl_add_u64 v[218:219], s[26:27], 0, v[138:139]
	s_addc_u32 s51, s27, 0
	s_add_i32 s52, s52, s36
	global_load_lds_dwordx4 v[218:219], off
	v_lshl_add_u64 v[220:221], s[50:51], 0, v[142:143]
	s_mov_b32 m0, s52
	v_lshl_add_u64 v[222:223], s[28:29], 0, v[140:141]
	global_load_lds_dwordx4 v[220:221], off
	v_lshl_add_u64 v[220:221], s[50:51], 0, v[138:139]
	s_add_i32 m0, s52, 0x2000
	s_nop 0
	global_load_lds_dwordx4 v[220:221], off
	v_lshl_add_u64 v[220:221], s[28:29], 0, v[144:145]
	s_mov_b32 m0, s33
	s_nop 0
	global_load_lds_dwordx4 v[220:221], off
	s_mov_b32 m0, s38
	s_nop 0
	global_load_lds_dwordx4 v[222:223], off
	s_waitcnt vmcnt(8)
	s_waitcnt lgkmcnt(0)
	s_setprio 1
	s_barrier
; #define PG8_STAGE(bufoff, gbase, voff) do { _Pragma("unroll") for (int _i = 0; _i < 2; ++_i) \
;         __builtin_amdgcn_global_load_lds((const unsigned*)((const char*)(gbase) + (voff)[_i]), (PG8_LAS unsigned*)(lds + (bufoff) + ldsw + _i * 8192), 16, 0, 0); } while (0)
; #define PG8_LDA(dst, b, h) do { _Pragma("unroll") for (int m = 0; m < 4; ++m) _Pragma("unroll") for (int k = 0; k < 2; ++k) dst[m][k] = *(const PG8_LAS bf16x8*)(lds + PG8_SA(b, h) + aoff + m * 2048 + k * 1024); } while (0)
; #define PG8_LDB(dst, b, h) do { _Pragma("unroll") for (int n = 0; n < 2; ++n) _Pragma("unroll") for (int k = 0; k < 2; ++k) dst[n][k] = *(const PG8_LAS bf16x8*)(lds + PG8_SB(b, h) + boff + n * 2048 + k * 1024); } while (0)
; #define PG8_MMA(ai, bj, At, Bt) do { __builtin_amdgcn_s_setprio(1); _Pragma("unroll") for (int m = 0; m < 4; ++m) _Pragma("unroll") for (int n = 0; n < 2; ++n) _Pragma("unroll") for (int k = 0; k < 2; ++k) \
;         acc[ai][bj][m][n] = __builtin_amdgcn_mfma_f32_16x16x32_bf16(Bt[n][k], At[m][k], acc[ai][bj][m][n], 0, 0, 0); __builtin_amdgcn_s_setprio(0); } while (0)
; #define PG8_WAIT_V(n) asm volatile("s_waitcnt vmcnt(" #n ")" ::: "memory")
; #define PG8_WAIT_L(n) asm volatile("s_waitcnt lgkmcnt(" #n ")" ::: "memory")
; #define PG8_BAR __builtin_amdgcn_s_barrier()
; #define PG8_SCHED __builtin_amdgcn_sched_barrier(0)
; template <class Epi, class Sched, bool ALIGN_EPI = false, bool SP2 = false>
; __device__ __forceinline__ void gemm_phase(PG8_LAS unsigned char* lds, const Gemm g, const Sched& S, const Epi& E) {
;     ...
;             PG8_WAIT_V(8); PG8_WAIT_L(0); PG8_BAR; PG8_MMA(1, 0, At, B0); PG8_MMA(1, 1, At, B1); PG8_BAR; PG8_SCHED;
;             PG8_LDB(B0, 1, 0); PG8_LDB(B1, 1, 1); PG8_SCHED; PG8_LDA(At, 1, 0); PG8_STAGE(PG8_SA(0, 1), a2 + hstep, voffA);
;             PG8_WAIT_V(8); PG8_WAIT_L(0); PG8_BAR; PG8_MMA(0, 0, At, B0); PG8_MMA(0, 1, At, B1); PG8_BAR; PG8_SCHED;
;             PG8_LDA(At, 1, 1); PG8_STAGE(PG8_SB(1, 0), b3, voffB); PG8_STAGE(PG8_SB(1, 1), b3 + hstep, voffB); PG8_STAGE(PG8_SA(1, 0), a3, voffA);
;             PG8_WAIT_V(8); PG8_WAIT_L(0); PG8_BAR; PG8_MMA(1, 0, At, B0); PG8_MMA(1, 1, At, B1); PG8_BAR; PG8_SCHED;
	v_mfma_f32_16x16x32_bf16 v[62:65], v[66:69], v[186:189], v[62:65]
	v_mfma_f32_16x16x32_bf16 v[58:61], v[152:155], v[186:189], v[58:61]
	v_mfma_f32_16x16x32_bf16 v[46:49], v[66:69], v[194:197], v[46:49]
	v_mfma_f32_16x16x32_bf16 v[42:45], v[152:155], v[194:197], v[42:45]
	v_mfma_f32_16x16x32_bf16 v[30:33], v[66:69], v[202:205], v[30:33]
	v_mfma_f32_16x16x32_bf16 v[26:29], v[152:155], v[202:205], v[26:29]
	v_mfma_f32_16x16x32_bf16 v[14:17], v[66:69], v[210:213], v[14:17]
	v_mfma_f32_16x16x32_bf16 v[10:13], v[152:155], v[210:213], v[10:13]
	v_mfma_f32_16x16x32_bf16 v[62:65], v[118:121], v[190:193], v[62:65]
	v_mfma_f32_16x16x32_bf16 v[58:61], v[162:165], v[190:193], v[58:61]
	v_mfma_f32_16x16x32_bf16 v[46:49], v[118:121], v[198:201], v[46:49]
	v_mfma_f32_16x16x32_bf16 v[42:45], v[162:165], v[198:201], v[42:45]
	v_mfma_f32_16x16x32_bf16 v[30:33], v[118:121], v[206:209], v[30:33]
	v_mfma_f32_16x16x32_bf16 v[26:29], v[162:165], v[206:209], v[26:29]
	v_mfma_f32_16x16x32_bf16 v[14:17], v[118:121], v[214:217], v[14:17]
	v_mfma_f32_16x16x32_bf16 v[10:13], v[162:165], v[214:217], v[10:13]
	s_setprio 0
	s_setprio 1
	v_mfma_f32_16x16x32_bf16 v[54:57], v[166:169], v[186:189], v[54:57]
	v_mfma_f32_16x16x32_bf16 v[50:53], v[174:177], v[186:189], v[50:53]
	v_mfma_f32_16x16x32_bf16 v[38:41], v[166:169], v[194:197], v[38:41]
	v_mfma_f32_16x16x32_bf16 v[34:37], v[174:177], v[194:197], v[34:37]
	v_mfma_f32_16x16x32_bf16 v[22:25], v[166:169], v[202:205], v[22:25]
	v_mfma_f32_16x16x32_bf16 v[18:21], v[174:177], v[202:205], v[18:21]
	v_mfma_f32_16x16x32_bf16 v[6:9], v[166:169], v[210:213], v[6:9]
	v_mfma_f32_16x16x32_bf16 v[2:5], v[174:177], v[210:213], v[2:5]
	v_mfma_f32_16x16x32_bf16 v[54:57], v[170:173], v[190:193], v[54:57]
	v_mfma_f32_16x16x32_bf16 v[50:53], v[180:183], v[190:193], v[50:53]
	v_mfma_f32_16x16x32_bf16 v[38:41], v[170:173], v[198:201], v[38:41]
	v_mfma_f32_16x16x32_bf16 v[34:37], v[180:183], v[198:201], v[34:37]
	v_mfma_f32_16x16x32_bf16 v[22:25], v[170:173], v[206:209], v[22:25]
	v_mfma_f32_16x16x32_bf16 v[18:21], v[180:183], v[206:209], v[18:21]
	v_mfma_f32_16x16x32_bf16 v[6:9], v[170:173], v[214:217], v[6:9]
	v_mfma_f32_16x16x32_bf16 v[2:5], v[180:183], v[214:217], v[2:5]
	s_barrier
	s_setprio 0
	s_add_i32 s50, 0, 0x18000
	v_add_u32_e32 v161, s50, v158
	s_add_i32 s51, 0, 0x1c000
	ds_read_b128 v[66:69], v161
	ds_read_b128 v[118:121], v161 offset:1024
	ds_read_b128 v[152:155], v161 offset:2048
	ds_read_b128 v[162:165], v161 offset:3072
	v_add_u32_e32 v161, s51, v158
	ds_read_b128 v[166:169], v161
	ds_read_b128 v[170:173], v161 offset:1024
	ds_read_b128 v[174:177], v161 offset:2048
	ds_read_b128 v[180:183], v161 offset:3072
	s_add_u32 s28, s28, 0x40000
	s_addc_u32 s29, s29, 0
	s_mov_b32 m0, s39
	v_lshl_add_u64 v[240:241], s[28:29], 0, v[144:145]
	ds_read_b128 v[186:189], v160 offset:32768
	ds_read_b128 v[190:193], v160 offset:33792
	ds_read_b128 v[194:197], v160 offset:34816
	ds_read_b128 v[198:201], v160 offset:35840
	ds_read_b128 v[202:205], v160 offset:36864
	ds_read_b128 v[206:209], v160 offset:37888
	ds_read_b128 v[210:213], v160 offset:38912
	ds_read_b128 v[214:217], v160 offset:39936
	global_load_lds_dwordx4 v[240:241], off
	v_lshl_add_u64 v[240:241], s[28:29], 0, v[140:141]
	s_mov_b32 m0, s40
	s_nop 0
	global_load_lds_dwordx4 v[240:241], off
	s_waitcnt vmcnt(8)
	s_waitcnt lgkmcnt(0)
	s_setprio 1
	s_barrier
	v_mfma_f32_16x16x32_bf16 v[134:137], v[66:69], v[186:189], v[134:137]
	v_mfma_f32_16x16x32_bf16 v[126:129], v[152:155], v[186:189], v[126:129]
	v_mfma_f32_16x16x32_bf16 v[114:117], v[66:69], v[194:197], v[114:117]
	v_mfma_f32_16x16x32_bf16 v[110:113], v[152:155], v[194:197], v[110:113]
	v_mfma_f32_16x16x32_bf16 v[98:101], v[66:69], v[202:205], v[98:101]
	v_mfma_f32_16x16x32_bf16 v[94:97], v[152:155], v[202:205], v[94:97]
	v_mfma_f32_16x16x32_bf16 v[82:85], v[66:69], v[210:213], v[82:85]
	v_mfma_f32_16x16x32_bf16 v[78:81], v[152:155], v[210:213], v[78:81]
	v_mfma_f32_16x16x32_bf16 v[134:137], v[118:121], v[190:193], v[134:137]
	v_mfma_f32_16x16x32_bf16 v[126:129], v[162:165], v[190:193], v[126:129]
	v_mfma_f32_16x16x32_bf16 v[114:117], v[118:121], v[198:201], v[114:117]
	v_mfma_f32_16x16x32_bf16 v[110:113], v[162:165], v[198:201], v[110:113]
	v_mfma_f32_16x16x32_bf16 v[98:101], v[118:121], v[206:209], v[98:101]
	v_mfma_f32_16x16x32_bf16 v[94:97], v[162:165], v[206:209], v[94:97]
	v_mfma_f32_16x16x32_bf16 v[82:85], v[118:121], v[214:217], v[82:85]
	v_mfma_f32_16x16x32_bf16 v[78:81], v[162:165], v[214:217], v[78:81]
	s_setprio 0
	s_setprio 1
	v_mfma_f32_16x16x32_bf16 v[130:133], v[166:169], v[186:189], v[130:133]
	v_mfma_f32_16x16x32_bf16 v[122:125], v[174:177], v[186:189], v[122:125]
	v_mfma_f32_16x16x32_bf16 v[106:109], v[166:169], v[194:197], v[106:109]
	v_mfma_f32_16x16x32_bf16 v[102:105], v[174:177], v[194:197], v[102:105]
	v_mfma_f32_16x16x32_bf16 v[90:93], v[166:169], v[202:205], v[90:93]
	v_mfma_f32_16x16x32_bf16 v[86:89], v[174:177], v[202:205], v[86:89]
	v_mfma_f32_16x16x32_bf16 v[74:77], v[166:169], v[210:213], v[74:77]
	v_mfma_f32_16x16x32_bf16 v[70:73], v[174:177], v[210:213], v[70:73]
	v_mfma_f32_16x16x32_bf16 v[130:133], v[170:173], v[190:193], v[130:133]
	v_mfma_f32_16x16x32_bf16 v[122:125], v[180:183], v[190:193], v[122:125]
	v_mfma_f32_16x16x32_bf16 v[106:109], v[170:173], v[198:201], v[106:109]
	v_mfma_f32_16x16x32_bf16 v[102:105], v[180:183], v[198:201], v[102:105]
	v_mfma_f32_16x16x32_bf16 v[90:93], v[170:173], v[206:209], v[90:93]
	v_mfma_f32_16x16x32_bf16 v[86:89], v[180:183], v[206:209], v[86:89]
	v_mfma_f32_16x16x32_bf16 v[74:77], v[170:173], v[214:217], v[74:77]
	v_mfma_f32_16x16x32_bf16 v[70:73], v[180:183], v[214:217], v[70:73]
	s_barrier
; #define PG8_STAGE(bufoff, gbase, voff) do { _Pragma("unroll") for (int _i = 0; _i < 2; ++_i) \
;         __builtin_amdgcn_global_load_lds((const unsigned*)((const char*)(gbase) + (voff)[_i]), (PG8_LAS unsigned*)(lds + (bufoff) + ldsw + _i * 8192), 16, 0, 0); } while (0)
; #define PG8_LDA(dst, b, h) do { _Pragma("unroll") for (int m = 0; m < 4; ++m) _Pragma("unroll") for (int k = 0; k < 2; ++k) dst[m][k] = *(const PG8_LAS bf16x8*)(lds + PG8_SA(b, h) + aoff + m * 2048 + k * 1024); } while (0)
; #define PG8_MMA(ai, bj, At, Bt) do { __builtin_amdgcn_s_setprio(1); _Pragma("unroll") for (int m = 0; m < 4; ++m) _Pragma("unroll") for (int n = 0; n < 2; ++n) _Pragma("unroll") for (int k = 0; k < 2; ++k) \
;         acc[ai][bj][m][n] = __builtin_amdgcn_mfma_f32_16x16x32_bf16(Bt[n][k], At[m][k], acc[ai][bj][m][n], 0, 0, 0); __builtin_amdgcn_s_setprio(0); } while (0)
; #define PG8_WAIT_V(n) asm volatile("s_waitcnt vmcnt(" #n ")" ::: "memory")
; #define PG8_WAIT_L(n) asm volatile("s_waitcnt lgkmcnt(" #n ")" ::: "memory")
; #define PG8_BAR __builtin_amdgcn_s_barrier()
; #define PG8_SCHED __builtin_amdgcn_sched_barrier(0)
; template <class Epi, class Sched, bool ALIGN_EPI = false, bool SP2 = false>
; __device__ __forceinline__ void gemm_phase(PG8_LAS unsigned char* lds, const Gemm g, const Sched& S, const Epi& E) {
;     ...
;             PG8_WAIT_V(8); PG8_WAIT_L(0); PG8_BAR; PG8_MMA(0, 0, At, B0); PG8_MMA(0, 1, At, B1); PG8_BAR; PG8_SCHED;
;             PG8_LDA(At, 1, 1); PG8_STAGE(PG8_SB(1, 0), b3, voffB); PG8_STAGE(PG8_SB(1, 1), b3 + hstep, voffB); PG8_STAGE(PG8_SA(1, 0), a3, voffA);
;             PG8_WAIT_V(8); PG8_WAIT_L(0); PG8_BAR; PG8_MMA(1, 0, At, B0); PG8_MMA(1, 1, At, B1); PG8_BAR; PG8_SCHED;
	s_setprio 0
	s_add_i32 s28, s50, s36
	v_lshl_add_u64 v[156:157], v[156:157], 0, s[80:81]
	s_mov_b32 m0, s28
	ds_read_b128 v[186:189], v160 offset:49152
	ds_read_b128 v[190:193], v160 offset:50176
	ds_read_b128 v[194:197], v160 offset:51200
	ds_read_b128 v[198:201], v160 offset:52224
	ds_read_b128 v[202:205], v160 offset:53248
	ds_read_b128 v[206:209], v160 offset:54272
	ds_read_b128 v[210:213], v160 offset:55296
	ds_read_b128 v[214:217], v160 offset:56320
	global_load_lds_dwordx4 v[156:157], off
	s_add_i32 m0, s28, 0x2000
	s_add_u32 s26, s26, 0x40080
	v_lshl_add_u64 v[156:157], v[218:219], 0, s[80:81]
	s_addc_u32 s27, s27, 0
	s_add_i32 s28, s51, s36
	global_load_lds_dwordx4 v[156:157], off
	v_lshl_add_u64 v[156:157], s[26:27], 0, v[142:143]
	s_mov_b32 m0, s28
	s_nop 0
	global_load_lds_dwordx4 v[156:157], off
	v_lshl_add_u64 v[156:157], s[26:27], 0, v[138:139]
	s_add_i32 m0, s28, 0x2000
	s_nop 0
	global_load_lds_dwordx4 v[156:157], off
	v_lshl_add_u64 v[156:157], v[220:221], 0, s[80:81]
	s_mov_b32 m0, s41
	s_nop 0
	global_load_lds_dwordx4 v[156:157], off
	v_lshl_add_u64 v[156:157], v[222:223], 0, s[80:81]
	s_mov_b32 m0, s42
	s_nop 0
	global_load_lds_dwordx4 v[156:157], off
	s_waitcnt vmcnt(8)
	s_waitcnt lgkmcnt(0)
	s_setprio 1
	s_barrier
	v_mfma_f32_16x16x32_bf16 v[62:65], v[66:69], v[186:189], v[62:65]
	v_mfma_f32_16x16x32_bf16 v[58:61], v[152:155], v[186:189], v[58:61]
	v_mfma_f32_16x16x32_bf16 v[46:49], v[66:69], v[194:197], v[46:49]
	v_mfma_f32_16x16x32_bf16 v[42:45], v[152:155], v[194:197], v[42:45]
	v_mfma_f32_16x16x32_bf16 v[30:33], v[66:69], v[202:205], v[30:33]
	v_mfma_f32_16x16x32_bf16 v[26:29], v[152:155], v[202:205], v[26:29]
	v_mfma_f32_16x16x32_bf16 v[14:17], v[66:69], v[210:213], v[14:17]
	v_mfma_f32_16x16x32_bf16 v[10:13], v[152:155], v[210:213], v[10:13]
	v_mfma_f32_16x16x32_bf16 v[62:65], v[118:121], v[190:193], v[62:65]
	v_mfma_f32_16x16x32_bf16 v[58:61], v[162:165], v[190:193], v[58:61]
	v_mfma_f32_16x16x32_bf16 v[46:49], v[118:121], v[198:201], v[46:49]
	v_mfma_f32_16x16x32_bf16 v[42:45], v[162:165], v[198:201], v[42:45]
	v_mfma_f32_16x16x32_bf16 v[30:33], v[118:121], v[206:209], v[30:33]
	v_mfma_f32_16x16x32_bf16 v[26:29], v[162:165], v[206:209], v[26:29]
	v_mfma_f32_16x16x32_bf16 v[14:17], v[118:121], v[214:217], v[14:17]
	v_mfma_f32_16x16x32_bf16 v[10:13], v[162:165], v[214:217], v[10:13]
	s_setprio 0
	s_setprio 1
	v_mfma_f32_16x16x32_bf16 v[54:57], v[166:169], v[186:189], v[54:57]
	v_mfma_f32_16x16x32_bf16 v[50:53], v[174:177], v[186:189], v[50:53]
	v_mfma_f32_16x16x32_bf16 v[38:41], v[166:169], v[194:197], v[38:41]
	v_mfma_f32_16x16x32_bf16 v[34:37], v[174:177], v[194:197], v[34:37]
	v_mfma_f32_16x16x32_bf16 v[22:25], v[166:169], v[202:205], v[22:25]
	v_mfma_f32_16x16x32_bf16 v[18:21], v[174:177], v[202:205], v[18:21]
	v_mfma_f32_16x16x32_bf16 v[6:9], v[166:169], v[210:213], v[6:9]
	v_mfma_f32_16x16x32_bf16 v[2:5], v[174:177], v[210:213], v[2:5]
	v_mfma_f32_16x16x32_bf16 v[54:57], v[170:173], v[190:193], v[54:57]
	v_mfma_f32_16x16x32_bf16 v[50:53], v[180:183], v[190:193], v[50:53]
	v_mfma_f32_16x16x32_bf16 v[38:41], v[170:173], v[198:201], v[38:41]
	v_mfma_f32_16x16x32_bf16 v[34:37], v[180:183], v[198:201], v[34:37]
	v_mfma_f32_16x16x32_bf16 v[22:25], v[170:173], v[206:209], v[22:25]
	v_mfma_f32_16x16x32_bf16 v[18:21], v[180:183], v[206:209], v[18:21]
	v_mfma_f32_16x16x32_bf16 v[6:9], v[170:173], v[214:217], v[6:9]
	v_mfma_f32_16x16x32_bf16 v[2:5], v[180:183], v[214:217], v[2:5]
	s_barrier
	s_setprio 0
	s_add_i32 s49, s49, 2
	s_add_u32 s24, s24, 0x100
	s_addc_u32 s25, s25, 0
	s_add_u32 s47, s47, 0x100
	s_addc_u32 s48, s48, 0
	s_cmp_gt_u32 s49, 13
	s_cbranch_scc0 .LBB0_1249
	s_and_b64 vcc, exec, s[12:13]
	s_cbranch_vccz .LBB0_1252
	s_barrier

; #define PG8_STAGE(bufoff, gbase, voff) do { _Pragma("unroll") for (int _i = 0; _i < 2; ++_i) \
;         __builtin_amdgcn_global_load_lds((const unsigned*)((const char*)(gbase) + (voff)[_i]), (PG8_LAS unsigned*)(lds + (bufoff) + ldsw + _i * 8192), 16, 0, 0); } while (0)
; #define PG8_LDA(dst, b, h) do { _Pragma("unroll") for (int m = 0; m < 4; ++m) _Pragma("unroll") for (int k = 0; k < 2; ++k) dst[m][k] = *(const PG8_LAS bf16x8*)(lds + PG8_SA(b, h) + aoff + m * 2048 + k * 1024); } while (0)
; #define PG8_LDB(dst, b, h) do { _Pragma("unroll") for (int n = 0; n < 2; ++n) _Pragma("unroll") for (int k = 0; k < 2; ++k) dst[n][k] = *(const PG8_LAS bf16x8*)(lds + PG8_SB(b, h) + boff + n * 2048 + k * 1024); } while (0)
; #define PG8_MMA(ai, bj, At, Bt) do { __builtin_amdgcn_s_setprio(1); _Pragma("unroll") for (int m = 0; m < 4; ++m) _Pragma("unroll") for (int n = 0; n < 2; ++n) _Pragma("unroll") for (int k = 0; k < 2; ++k) \
;         acc[ai][bj][m][n] = __builtin_amdgcn_mfma_f32_16x16x32_bf16(Bt[n][k], At[m][k], acc[ai][bj][m][n], 0, 0, 0); __builtin_amdgcn_s_setprio(0); } while (0)
; #define PG8_WAIT_V(n) asm volatile("s_waitcnt vmcnt(" #n ")" ::: "memory")
; #define PG8_WAIT_L(n) asm volatile("s_waitcnt lgkmcnt(" #n ")" ::: "memory")
; template <class Epi, class Sched, bool ALIGN_EPI = false, bool SP2 = false>
; __device__ __forceinline__ void gemm_phase(PG8_LAS unsigned char* lds, const Gemm g, const Sched& S, const Epi& E) {
;     ...
;             const bool last = (t == nt - 2);
;             const char* a1 = cA + (size_t)(t + 1) * kstep;
;             const char* a2 = last ? nA : cA + (size_t)(t + 2) * kstep; const char* b2 = last ? nB : cB + (size_t)(t + 2) * kstep;
;             const char* a3 = a2 + kstep; const char* b3 = b2 + kstep;
;             if (last && has_next) S.a_ready(nxt);
;             if constexpr (SP2) {
;             PG8_LDB(B0, 0, 0); PG8_LDB(B1, 0, 1); PG8_SCHED; PG8_LDA(At, 0, 0); PG8_STAGE(PG8_SA(1, 1), a1 + hstep, voffA);
;             PG8_WAIT_V(8); PG8_WAIT_L(0); PG8_BAR; PG8_MMA(0, 0, At, B0); PG8_MMA(0, 1, At, B1); PG8_BAR; PG8_SCHED;
;             PG8_LDA(At, 0, 1); PG8_STAGE(PG8_SB(0, 0), b2, voffB); PG8_STAGE(PG8_SB(0, 1), b2 + hstep, voffB); PG8_STAGE(PG8_SA(0, 0), a2, voffA);
;             PG8_WAIT_V(8); PG8_WAIT_L(0); PG8_BAR; PG8_MMA(1, 0, At, B0); PG8_MMA(1, 1, At, B1); PG8_BAR; PG8_SCHED;
.LBB0_1330:
	s_add_u32 s22, s20, 0x100
	s_addc_u32 s23, s21, 0
	s_add_i32 s52, 0, 0x10000
	s_cmp_eq_u32 s51, 40
	s_cselect_b32 s27, s7, s23
	s_cselect_b32 s26, s6, s22
	v_add_u32_e32 v157, s52, v154
	s_cselect_b32 s25, s19, s50
	s_cselect_b32 s24, s18, s49
	s_add_i32 s53, 0, 0x14000
	ds_read_b128 v[142:145], v157
	ds_read_b128 v[146:149], v157 offset:1024
	ds_read_b128 v[150:153], v157 offset:2048
	ds_read_b128 v[158:161], v157 offset:3072
	v_add_u32_e32 v157, s53, v154
	ds_read_b128 v[162:165], v157
	ds_read_b128 v[166:169], v157 offset:1024
	ds_read_b128 v[170:173], v157 offset:2048
	ds_read_b128 v[174:177], v157 offset:3072
	v_lshl_add_u64 v[214:215], s[20:21], 0, v[138:139]
	s_add_i32 m0, s37, 0xc000
	ds_read_b128 v[180:183], v156
	ds_read_b128 v[186:189], v156 offset:1024
	ds_read_b128 v[190:193], v156 offset:2048
	ds_read_b128 v[194:197], v156 offset:3072
	ds_read_b128 v[198:201], v156 offset:4096
	ds_read_b128 v[202:205], v156 offset:5120
	ds_read_b128 v[206:209], v156 offset:6144
	ds_read_b128 v[210:213], v156 offset:7168
	global_load_lds_dwordx4 v[214:215], off
	v_lshl_add_u64 v[214:215], s[20:21], 0, v[140:141]
	s_add_i32 m0, s37, 0xe000
	s_nop 0
	global_load_lds_dwordx4 v[214:215], off
	s_waitcnt vmcnt(8)
	s_waitcnt lgkmcnt(0)
	s_setprio 1
	s_barrier
	v_mfma_f32_16x16x32_bf16 v[126:129], v[142:145], v[180:183], v[126:129]
	v_mfma_f32_16x16x32_bf16 v[122:125], v[150:153], v[180:183], v[122:125]
	v_mfma_f32_16x16x32_bf16 v[114:117], v[142:145], v[190:193], v[114:117]
	v_mfma_f32_16x16x32_bf16 v[106:109], v[150:153], v[190:193], v[106:109]
	v_mfma_f32_16x16x32_bf16 v[98:101], v[142:145], v[198:201], v[98:101]
	v_mfma_f32_16x16x32_bf16 v[90:93], v[150:153], v[198:201], v[90:93]
	v_mfma_f32_16x16x32_bf16 v[82:85], v[142:145], v[206:209], v[82:85]
	v_mfma_f32_16x16x32_bf16 v[74:77], v[150:153], v[206:209], v[74:77]
	v_mfma_f32_16x16x32_bf16 v[126:129], v[146:149], v[186:189], v[126:129]
	v_mfma_f32_16x16x32_bf16 v[122:125], v[158:161], v[186:189], v[122:125]
	v_mfma_f32_16x16x32_bf16 v[114:117], v[146:149], v[194:197], v[114:117]
	v_mfma_f32_16x16x32_bf16 v[106:109], v[158:161], v[194:197], v[106:109]
	v_mfma_f32_16x16x32_bf16 v[98:101], v[146:149], v[202:205], v[98:101]
	v_mfma_f32_16x16x32_bf16 v[90:93], v[158:161], v[202:205], v[90:93]
	v_mfma_f32_16x16x32_bf16 v[82:85], v[146:149], v[210:213], v[82:85]
	v_mfma_f32_16x16x32_bf16 v[74:77], v[158:161], v[210:213], v[74:77]
	s_setprio 0
	s_setprio 1
	v_mfma_f32_16x16x32_bf16 v[118:121], v[162:165], v[180:183], v[118:121]
	v_mfma_f32_16x16x32_bf16 v[110:113], v[170:173], v[180:183], v[110:113]
	v_mfma_f32_16x16x32_bf16 v[102:105], v[162:165], v[190:193], v[102:105]
	v_mfma_f32_16x16x32_bf16 v[94:97], v[170:173], v[190:193], v[94:97]
	v_mfma_f32_16x16x32_bf16 v[86:89], v[162:165], v[198:201], v[86:89]
	v_mfma_f32_16x16x32_bf16 v[78:81], v[170:173], v[198:201], v[78:81]
	v_mfma_f32_16x16x32_bf16 v[70:73], v[162:165], v[206:209], v[70:73]
	v_mfma_f32_16x16x32_bf16 v[66:69], v[170:173], v[206:209], v[66:69]
	v_mfma_f32_16x16x32_bf16 v[118:121], v[166:169], v[186:189], v[118:121]
	v_mfma_f32_16x16x32_bf16 v[110:113], v[174:177], v[186:189], v[110:113]
	v_mfma_f32_16x16x32_bf16 v[102:105], v[166:169], v[194:197], v[102:105]
	v_mfma_f32_16x16x32_bf16 v[94:97], v[174:177], v[194:197], v[94:97]
	v_mfma_f32_16x16x32_bf16 v[86:89], v[166:169], v[202:205], v[86:89]
	v_mfma_f32_16x16x32_bf16 v[78:81], v[174:177], v[202:205], v[78:81]
	v_mfma_f32_16x16x32_bf16 v[70:73], v[166:169], v[210:213], v[70:73]
	v_mfma_f32_16x16x32_bf16 v[66:69], v[174:177], v[210:213], v[66:69]
	s_barrier
	s_setprio 0
	s_add_i32 s20, s52, s36
	v_lshl_add_u64 v[214:215], s[24:25], 0, v[132:133]
	s_mov_b32 m0, s20
	ds_read_b128 v[180:183], v156 offset:16384
	ds_read_b128 v[186:189], v156 offset:17408
	ds_read_b128 v[190:193], v156 offset:18432
	ds_read_b128 v[194:197], v156 offset:19456
	ds_read_b128 v[198:201], v156 offset:20480
	ds_read_b128 v[202:205], v156 offset:21504
	ds_read_b128 v[206:209], v156 offset:22528
	ds_read_b128 v[210:213], v156 offset:23552
	global_load_lds_dwordx4 v[214:215], off
	s_add_i32 m0, s20, 0x2000
	s_add_u32 s20, s24, 0xb0000
	v_lshl_add_u64 v[216:217], s[24:25], 0, v[136:137]
	s_addc_u32 s21, s25, 0
	s_add_i32 s52, s53, s36
	global_load_lds_dwordx4 v[216:217], off
	v_lshl_add_u64 v[218:219], s[20:21], 0, v[132:133]
	s_mov_b32 m0, s52
	v_lshl_add_u64 v[220:221], s[26:27], 0, v[134:135]
	global_load_lds_dwordx4 v[218:219], off
	v_lshl_add_u64 v[218:219], s[20:21], 0, v[136:137]
	s_add_i32 m0, s52, 0x2000
	s_nop 0
	global_load_lds_dwordx4 v[218:219], off
	v_lshl_add_u64 v[218:219], s[26:27], 0, v[130:131]
	s_mov_b32 m0, s37
	s_nop 0
	global_load_lds_dwordx4 v[218:219], off
	s_mov_b32 m0, s38
	s_nop 0
	global_load_lds_dwordx4 v[220:221], off
	s_waitcnt vmcnt(8)
	s_waitcnt lgkmcnt(0)
	s_setprio 1
	s_barrier
; #define PG8_STAGE(bufoff, gbase, voff) do { _Pragma("unroll") for (int _i = 0; _i < 2; ++_i) \
;         __builtin_amdgcn_global_load_lds((const unsigned*)((const char*)(gbase) + (voff)[_i]), (PG8_LAS unsigned*)(lds + (bufoff) + ldsw + _i * 8192), 16, 0, 0); } while (0)
; #define PG8_LDA(dst, b, h) do { _Pragma("unroll") for (int m = 0; m < 4; ++m) _Pragma("unroll") for (int k = 0; k < 2; ++k) dst[m][k] = *(const PG8_LAS bf16x8*)(lds + PG8_SA(b, h) + aoff + m * 2048 + k * 1024); } while (0)
; #define PG8_LDB(dst, b, h) do { _Pragma("unroll") for (int n = 0; n < 2; ++n) _Pragma("unroll") for (int k = 0; k < 2; ++k) dst[n][k] = *(const PG8_LAS bf16x8*)(lds + PG8_SB(b, h) + boff + n * 2048 + k * 1024); } while (0)
; #define PG8_MMA(ai, bj, At, Bt) do { __builtin_amdgcn_s_setprio(1); _Pragma("unroll") for (int m = 0; m < 4; ++m) _Pragma("unroll") for (int n = 0; n < 2; ++n) _Pragma("unroll") for (int k = 0; k < 2; ++k) \
;         acc[ai][bj][m][n] = __builtin_amdgcn_mfma_f32_16x16x32_bf16(Bt[n][k], At[m][k], acc[ai][bj][m][n], 0, 0, 0); __builtin_amdgcn_s_setprio(0); } while (0)
; #define PG8_WAIT_V(n) asm volatile("s_waitcnt vmcnt(" #n ")" ::: "memory")
; #define PG8_WAIT_L(n) asm volatile("s_waitcnt lgkmcnt(" #n ")" ::: "memory")
; #define PG8_BAR __builtin_amdgcn_s_barrier()
; #define PG8_SCHED __builtin_amdgcn_sched_barrier(0)
; template <class Epi, class Sched, bool ALIGN_EPI = false, bool SP2 = false>
; __device__ __forceinline__ void gemm_phase(PG8_LAS unsigned char* lds, const Gemm g, const Sched& S, const Epi& E) {
;     ...
;             PG8_WAIT_V(8); PG8_WAIT_L(0); PG8_BAR; PG8_MMA(1, 0, At, B0); PG8_MMA(1, 1, At, B1); PG8_BAR; PG8_SCHED;
;             PG8_LDB(B0, 1, 0); PG8_LDB(B1, 1, 1); PG8_SCHED; PG8_LDA(At, 1, 0); PG8_STAGE(PG8_SA(0, 1), a2 + hstep, voffA);
;             PG8_WAIT_V(8); PG8_WAIT_L(0); PG8_BAR; PG8_MMA(0, 0, At, B0); PG8_MMA(0, 1, At, B1); PG8_BAR; PG8_SCHED;
;             PG8_LDA(At, 1, 1); PG8_STAGE(PG8_SB(1, 0), b3, voffB); PG8_STAGE(PG8_SB(1, 1), b3 + hstep, voffB); PG8_STAGE(PG8_SA(1, 0), a3, voffA);
;             PG8_WAIT_V(8); PG8_WAIT_L(0); PG8_BAR; PG8_MMA(1, 0, At, B0); PG8_MMA(1, 1, At, B1); PG8_BAR; PG8_SCHED;
	v_mfma_f32_16x16x32_bf16 v[62:65], v[142:145], v[180:183], v[62:65]
	v_mfma_f32_16x16x32_bf16 v[58:61], v[150:153], v[180:183], v[58:61]
	v_mfma_f32_16x16x32_bf16 v[50:53], v[142:145], v[190:193], v[50:53]
	v_mfma_f32_16x16x32_bf16 v[42:45], v[150:153], v[190:193], v[42:45]
	v_mfma_f32_16x16x32_bf16 v[34:37], v[142:145], v[198:201], v[34:37]
	v_mfma_f32_16x16x32_bf16 v[26:29], v[150:153], v[198:201], v[26:29]
	v_mfma_f32_16x16x32_bf16 v[18:21], v[142:145], v[206:209], v[18:21]
	v_mfma_f32_16x16x32_bf16 v[10:13], v[150:153], v[206:209], v[10:13]
	v_mfma_f32_16x16x32_bf16 v[62:65], v[146:149], v[186:189], v[62:65]
	v_mfma_f32_16x16x32_bf16 v[58:61], v[158:161], v[186:189], v[58:61]
	v_mfma_f32_16x16x32_bf16 v[50:53], v[146:149], v[194:197], v[50:53]
	v_mfma_f32_16x16x32_bf16 v[42:45], v[158:161], v[194:197], v[42:45]
	v_mfma_f32_16x16x32_bf16 v[34:37], v[146:149], v[202:205], v[34:37]
	v_mfma_f32_16x16x32_bf16 v[26:29], v[158:161], v[202:205], v[26:29]
	v_mfma_f32_16x16x32_bf16 v[18:21], v[146:149], v[210:213], v[18:21]
	v_mfma_f32_16x16x32_bf16 v[10:13], v[158:161], v[210:213], v[10:13]
	s_setprio 0
	s_setprio 1
	v_mfma_f32_16x16x32_bf16 v[54:57], v[162:165], v[180:183], v[54:57]
	v_mfma_f32_16x16x32_bf16 v[46:49], v[170:173], v[180:183], v[46:49]
	v_mfma_f32_16x16x32_bf16 v[38:41], v[162:165], v[190:193], v[38:41]
	v_mfma_f32_16x16x32_bf16 v[30:33], v[170:173], v[190:193], v[30:33]
	v_mfma_f32_16x16x32_bf16 v[22:25], v[162:165], v[198:201], v[22:25]
	v_mfma_f32_16x16x32_bf16 v[14:17], v[170:173], v[198:201], v[14:17]
	v_mfma_f32_16x16x32_bf16 v[6:9], v[162:165], v[206:209], v[6:9]
	v_mfma_f32_16x16x32_bf16 v[2:5], v[170:173], v[206:209], v[2:5]
	v_mfma_f32_16x16x32_bf16 v[54:57], v[166:169], v[186:189], v[54:57]
	v_mfma_f32_16x16x32_bf16 v[46:49], v[174:177], v[186:189], v[46:49]
	v_mfma_f32_16x16x32_bf16 v[38:41], v[166:169], v[194:197], v[38:41]
	v_mfma_f32_16x16x32_bf16 v[30:33], v[174:177], v[194:197], v[30:33]
	v_mfma_f32_16x16x32_bf16 v[22:25], v[166:169], v[202:205], v[22:25]
	v_mfma_f32_16x16x32_bf16 v[14:17], v[174:177], v[202:205], v[14:17]
	v_mfma_f32_16x16x32_bf16 v[6:9], v[166:169], v[210:213], v[6:9]
	v_mfma_f32_16x16x32_bf16 v[2:5], v[174:177], v[210:213], v[2:5]
	s_barrier
	s_setprio 0
	s_add_i32 s52, 0, 0x18000
	v_add_u32_e32 v157, s52, v154
	s_add_i32 s53, 0, 0x1c000
	ds_read_b128 v[142:145], v157
	ds_read_b128 v[146:149], v157 offset:1024
	ds_read_b128 v[150:153], v157 offset:2048
	ds_read_b128 v[158:161], v157 offset:3072
	v_add_u32_e32 v157, s53, v154
	ds_read_b128 v[162:165], v157
	ds_read_b128 v[166:169], v157 offset:1024
	ds_read_b128 v[170:173], v157 offset:2048
	ds_read_b128 v[174:177], v157 offset:3072
	s_add_u32 s20, s26, 0xb0000
	s_addc_u32 s21, s27, 0
	s_mov_b32 m0, s39
	v_lshl_add_u64 v[222:223], s[20:21], 0, v[130:131]
	ds_read_b128 v[180:183], v156 offset:32768
	ds_read_b128 v[186:189], v156 offset:33792
	ds_read_b128 v[190:193], v156 offset:34816
	ds_read_b128 v[194:197], v156 offset:35840
	ds_read_b128 v[198:201], v156 offset:36864
	ds_read_b128 v[202:205], v156 offset:37888
	ds_read_b128 v[206:209], v156 offset:38912
	ds_read_b128 v[210:213], v156 offset:39936
	global_load_lds_dwordx4 v[222:223], off
	v_lshl_add_u64 v[222:223], s[20:21], 0, v[134:135]
	s_mov_b32 m0, s40
	s_nop 0
	global_load_lds_dwordx4 v[222:223], off
	s_waitcnt vmcnt(8)
	s_waitcnt lgkmcnt(0)
	s_setprio 1
	s_barrier
	v_mfma_f32_16x16x32_bf16 v[126:129], v[142:145], v[180:183], v[126:129]
	v_mfma_f32_16x16x32_bf16 v[122:125], v[150:153], v[180:183], v[122:125]
	v_mfma_f32_16x16x32_bf16 v[114:117], v[142:145], v[190:193], v[114:117]
	v_mfma_f32_16x16x32_bf16 v[106:109], v[150:153], v[190:193], v[106:109]
	v_mfma_f32_16x16x32_bf16 v[98:101], v[142:145], v[198:201], v[98:101]
	v_mfma_f32_16x16x32_bf16 v[90:93], v[150:153], v[198:201], v[90:93]
	v_mfma_f32_16x16x32_bf16 v[82:85], v[142:145], v[206:209], v[82:85]
	v_mfma_f32_16x16x32_bf16 v[74:77], v[150:153], v[206:209], v[74:77]
	v_mfma_f32_16x16x32_bf16 v[126:129], v[146:149], v[186:189], v[126:129]
	v_mfma_f32_16x16x32_bf16 v[122:125], v[158:161], v[186:189], v[122:125]
	v_mfma_f32_16x16x32_bf16 v[114:117], v[146:149], v[194:197], v[114:117]
	v_mfma_f32_16x16x32_bf16 v[106:109], v[158:161], v[194:197], v[106:109]
	v_mfma_f32_16x16x32_bf16 v[98:101], v[146:149], v[202:205], v[98:101]
	v_mfma_f32_16x16x32_bf16 v[90:93], v[158:161], v[202:205], v[90:93]
	v_mfma_f32_16x16x32_bf16 v[82:85], v[146:149], v[210:213], v[82:85]
	v_mfma_f32_16x16x32_bf16 v[74:77], v[158:161], v[210:213], v[74:77]
	s_setprio 0
	s_setprio 1
	v_mfma_f32_16x16x32_bf16 v[118:121], v[162:165], v[180:183], v[118:121]
	v_mfma_f32_16x16x32_bf16 v[110:113], v[170:173], v[180:183], v[110:113]
	v_mfma_f32_16x16x32_bf16 v[102:105], v[162:165], v[190:193], v[102:105]
	v_mfma_f32_16x16x32_bf16 v[94:97], v[170:173], v[190:193], v[94:97]
	v_mfma_f32_16x16x32_bf16 v[86:89], v[162:165], v[198:201], v[86:89]
	v_mfma_f32_16x16x32_bf16 v[78:81], v[170:173], v[198:201], v[78:81]
	v_mfma_f32_16x16x32_bf16 v[70:73], v[162:165], v[206:209], v[70:73]
	v_mfma_f32_16x16x32_bf16 v[66:69], v[170:173], v[206:209], v[66:69]
	v_mfma_f32_16x16x32_bf16 v[118:121], v[166:169], v[186:189], v[118:121]
	v_mfma_f32_16x16x32_bf16 v[110:113], v[174:177], v[186:189], v[110:113]
	v_mfma_f32_16x16x32_bf16 v[102:105], v[166:169], v[194:197], v[102:105]
	v_mfma_f32_16x16x32_bf16 v[94:97], v[174:177], v[194:197], v[94:97]
	v_mfma_f32_16x16x32_bf16 v[86:89], v[166:169], v[202:205], v[86:89]
	v_mfma_f32_16x16x32_bf16 v[78:81], v[174:177], v[202:205], v[78:81]
	v_mfma_f32_16x16x32_bf16 v[70:73], v[166:169], v[210:213], v[70:73]
	v_mfma_f32_16x16x32_bf16 v[66:69], v[174:177], v[210:213], v[66:69]
	s_barrier
; #define PG8_STAGE(bufoff, gbase, voff) do { _Pragma("unroll") for (int _i = 0; _i < 2; ++_i) \
;         __builtin_amdgcn_global_load_lds((const unsigned*)((const char*)(gbase) + (voff)[_i]), (PG8_LAS unsigned*)(lds + (bufoff) + ldsw + _i * 8192), 16, 0, 0); } while (0)
; #define PG8_LDA(dst, b, h) do { _Pragma("unroll") for (int m = 0; m < 4; ++m) _Pragma("unroll") for (int k = 0; k < 2; ++k) dst[m][k] = *(const PG8_LAS bf16x8*)(lds + PG8_SA(b, h) + aoff + m * 2048 + k * 1024); } while (0)
; #define PG8_MMA(ai, bj, At, Bt) do { __builtin_amdgcn_s_setprio(1); _Pragma("unroll") for (int m = 0; m < 4; ++m) _Pragma("unroll") for (int n = 0; n < 2; ++n) _Pragma("unroll") for (int k = 0; k < 2; ++k) \
;         acc[ai][bj][m][n] = __builtin_amdgcn_mfma_f32_16x16x32_bf16(Bt[n][k], At[m][k], acc[ai][bj][m][n], 0, 0, 0); __builtin_amdgcn_s_setprio(0); } while (0)
; #define PG8_WAIT_V(n) asm volatile("s_waitcnt vmcnt(" #n ")" ::: "memory")
; #define PG8_WAIT_L(n) asm volatile("s_waitcnt lgkmcnt(" #n ")" ::: "memory")
; #define PG8_BAR __builtin_amdgcn_s_barrier()
; #define PG8_SCHED __builtin_amdgcn_sched_barrier(0)
; template <class Epi, class Sched, bool ALIGN_EPI = false, bool SP2 = false>
; __device__ __forceinline__ void gemm_phase(PG8_LAS unsigned char* lds, const Gemm g, const Sched& S, const Epi& E) {
;     ...
;             PG8_WAIT_V(8); PG8_WAIT_L(0); PG8_BAR; PG8_MMA(0, 0, At, B0); PG8_MMA(0, 1, At, B1); PG8_BAR; PG8_SCHED;
;             PG8_LDA(At, 1, 1); PG8_STAGE(PG8_SB(1, 0), b3, voffB); PG8_STAGE(PG8_SB(1, 1), b3 + hstep, voffB); PG8_STAGE(PG8_SA(1, 0), a3, voffA);
;             PG8_WAIT_V(8); PG8_WAIT_L(0); PG8_BAR; PG8_MMA(1, 0, At, B0); PG8_MMA(1, 1, At, B1); PG8_BAR; PG8_SCHED;
	s_setprio 0
	s_add_i32 s20, s52, s36
	v_lshl_add_u64 v[214:215], v[214:215], 0, s[80:81]
	s_mov_b32 m0, s20
	ds_read_b128 v[180:183], v156 offset:49152
	ds_read_b128 v[186:189], v156 offset:50176
	ds_read_b128 v[190:193], v156 offset:51200
	ds_read_b128 v[194:197], v156 offset:52224
	ds_read_b128 v[198:201], v156 offset:53248
	ds_read_b128 v[202:205], v156 offset:54272
	ds_read_b128 v[206:209], v156 offset:55296
	ds_read_b128 v[210:213], v156 offset:56320
	global_load_lds_dwordx4 v[214:215], off
	s_add_i32 m0, s20, 0x2000
	s_add_u32 s20, s24, 0xb0080
	v_lshl_add_u64 v[214:215], v[216:217], 0, s[80:81]
	s_addc_u32 s21, s25, 0
	s_add_i32 s24, s53, s36
	global_load_lds_dwordx4 v[214:215], off
	v_lshl_add_u64 v[214:215], s[20:21], 0, v[132:133]
	s_mov_b32 m0, s24
	s_nop 0
	global_load_lds_dwordx4 v[214:215], off
	v_lshl_add_u64 v[214:215], s[20:21], 0, v[136:137]
	s_add_i32 m0, s24, 0x2000
	s_nop 0
	global_load_lds_dwordx4 v[214:215], off
	v_lshl_add_u64 v[214:215], v[218:219], 0, s[80:81]
	s_mov_b32 m0, s41
	s_nop 0
	global_load_lds_dwordx4 v[214:215], off
	v_lshl_add_u64 v[214:215], v[220:221], 0, s[80:81]
	s_mov_b32 m0, s42
	s_nop 0
	global_load_lds_dwordx4 v[214:215], off
	s_waitcnt vmcnt(8)
	s_waitcnt lgkmcnt(0)
	s_setprio 1
	s_barrier
	v_mfma_f32_16x16x32_bf16 v[62:65], v[142:145], v[180:183], v[62:65]
	v_mfma_f32_16x16x32_bf16 v[58:61], v[150:153], v[180:183], v[58:61]
	v_mfma_f32_16x16x32_bf16 v[50:53], v[142:145], v[190:193], v[50:53]
	v_mfma_f32_16x16x32_bf16 v[42:45], v[150:153], v[190:193], v[42:45]
	v_mfma_f32_16x16x32_bf16 v[34:37], v[142:145], v[198:201], v[34:37]
	v_mfma_f32_16x16x32_bf16 v[26:29], v[150:153], v[198:201], v[26:29]
	v_mfma_f32_16x16x32_bf16 v[18:21], v[142:145], v[206:209], v[18:21]
	v_mfma_f32_16x16x32_bf16 v[10:13], v[150:153], v[206:209], v[10:13]
	v_mfma_f32_16x16x32_bf16 v[62:65], v[146:149], v[186:189], v[62:65]
	v_mfma_f32_16x16x32_bf16 v[58:61], v[158:161], v[186:189], v[58:61]
	v_mfma_f32_16x16x32_bf16 v[50:53], v[146:149], v[194:197], v[50:53]
	v_mfma_f32_16x16x32_bf16 v[42:45], v[158:161], v[194:197], v[42:45]
	v_mfma_f32_16x16x32_bf16 v[34:37], v[146:149], v[202:205], v[34:37]
	v_mfma_f32_16x16x32_bf16 v[26:29], v[158:161], v[202:205], v[26:29]
	v_mfma_f32_16x16x32_bf16 v[18:21], v[146:149], v[210:213], v[18:21]
	v_mfma_f32_16x16x32_bf16 v[10:13], v[158:161], v[210:213], v[10:13]
	s_setprio 0
	s_setprio 1
	v_mfma_f32_16x16x32_bf16 v[54:57], v[162:165], v[180:183], v[54:57]
	v_mfma_f32_16x16x32_bf16 v[46:49], v[170:173], v[180:183], v[46:49]
	v_mfma_f32_16x16x32_bf16 v[38:41], v[162:165], v[190:193], v[38:41]
	v_mfma_f32_16x16x32_bf16 v[30:33], v[170:173], v[190:193], v[30:33]
	v_mfma_f32_16x16x32_bf16 v[22:25], v[162:165], v[198:201], v[22:25]
	v_mfma_f32_16x16x32_bf16 v[14:17], v[170:173], v[198:201], v[14:17]
	v_mfma_f32_16x16x32_bf16 v[6:9], v[162:165], v[206:209], v[6:9]
	v_mfma_f32_16x16x32_bf16 v[2:5], v[170:173], v[206:209], v[2:5]
	v_mfma_f32_16x16x32_bf16 v[54:57], v[166:169], v[186:189], v[54:57]
	v_mfma_f32_16x16x32_bf16 v[46:49], v[174:177], v[186:189], v[46:49]
	v_mfma_f32_16x16x32_bf16 v[38:41], v[166:169], v[194:197], v[38:41]
	v_mfma_f32_16x16x32_bf16 v[30:33], v[174:177], v[194:197], v[30:33]
	v_mfma_f32_16x16x32_bf16 v[22:25], v[166:169], v[202:205], v[22:25]
	v_mfma_f32_16x16x32_bf16 v[14:17], v[174:177], v[202:205], v[14:17]
	v_mfma_f32_16x16x32_bf16 v[6:9], v[166:169], v[210:213], v[6:9]
	v_mfma_f32_16x16x32_bf16 v[2:5], v[174:177], v[210:213], v[2:5]
	s_barrier
	s_setprio 0
	s_add_i32 s51, s51, 2
	s_add_u32 s49, s49, 0x100
	s_addc_u32 s50, s50, 0
	s_cmp_gt_u32 s51, 41
	s_mov_b64 s[20:21], s[22:23]
	s_cbranch_scc0 .LBB0_1330
	s_and_b64 vcc, exec, s[16:17]
	s_cbranch_vccz .LBB0_1333
	s_barrier

; #define PG8_STAGE(bufoff, gbase, voff) do { _Pragma("unroll") for (int _i = 0; _i < 2; ++_i) \
;         __builtin_amdgcn_global_load_lds((const unsigned*)((const char*)(gbase) + (voff)[_i]), (PG8_LAS unsigned*)(lds + (bufoff) + ldsw + _i * 8192), 16, 0, 0); } while (0)
; #define PG8_LDA(dst, b, h) do { _Pragma("unroll") for (int m = 0; m < 4; ++m) _Pragma("unroll") for (int k = 0; k < 2; ++k) dst[m][k] = *(const PG8_LAS bf16x8*)(lds + PG8_SA(b, h) + aoff + m * 2048 + k * 1024); } while (0)
; #define PG8_LDB(dst, b, h) do { _Pragma("unroll") for (int n = 0; n < 2; ++n) _Pragma("unroll") for (int k = 0; k < 2; ++k) dst[n][k] = *(const PG8_LAS bf16x8*)(lds + PG8_SB(b, h) + boff + n * 2048 + k * 1024); } while (0)
; #define PG8_MMA(ai, bj, At, Bt) do { __builtin_amdgcn_s_setprio(1); _Pragma("unroll") for (int m = 0; m < 4; ++m) _Pragma("unroll") for (int n = 0; n < 2; ++n) _Pragma("unroll") for (int k = 0; k < 2; ++k) \
;         acc[ai][bj][m][n] = __builtin_amdgcn_mfma_f32_16x16x32_bf16(Bt[n][k], At[m][k], acc[ai][bj][m][n], 0, 0, 0); __builtin_amdgcn_s_setprio(0); } while (0)
; #define PG8_WAIT_V(n) asm volatile("s_waitcnt vmcnt(" #n ")" ::: "memory")
; #define PG8_WAIT_L(n) asm volatile("s_waitcnt lgkmcnt(" #n ")" ::: "memory")
; template <class Epi, class Sched, bool ALIGN_EPI = false, bool SP2 = false>
; __device__ __forceinline__ void gemm_phase(PG8_LAS unsigned char* lds, const Gemm g, const Sched& S, const Epi& E) {
;     ...
;             const bool last = (t == nt - 2);
;             const char* a1 = cA + (size_t)(t + 1) * kstep;
;             const char* a2 = last ? nA : cA + (size_t)(t + 2) * kstep; const char* b2 = last ? nB : cB + (size_t)(t + 2) * kstep;
;             const char* a3 = a2 + kstep; const char* b3 = b2 + kstep;
;             if (last && has_next) S.a_ready(nxt);
;             if constexpr (SP2) {
;             PG8_LDB(B0, 0, 0); PG8_LDB(B1, 0, 1); PG8_SCHED; PG8_LDA(At, 0, 0); PG8_STAGE(PG8_SA(1, 1), a1 + hstep, voffA);
;             PG8_WAIT_V(8); PG8_WAIT_L(0); PG8_BAR; PG8_MMA(0, 0, At, B0); PG8_MMA(0, 1, At, B1); PG8_BAR; PG8_SCHED;
;             PG8_LDA(At, 0, 1); PG8_STAGE(PG8_SB(0, 0), b2, voffB); PG8_STAGE(PG8_SB(0, 1), b2 + hstep, voffB); PG8_STAGE(PG8_SA(0, 0), a2, voffA);
;             PG8_WAIT_V(8); PG8_WAIT_L(0); PG8_BAR; PG8_MMA(1, 0, At, B0); PG8_MMA(1, 1, At, B1); PG8_BAR; PG8_SCHED;
.LBB0_1360:
	s_add_u32 s20, s18, 0x100
	s_addc_u32 s21, s19, 0
	s_add_i32 s50, 0, 0x10000
	s_cmp_eq_u32 s49, 40
	s_cselect_b32 s25, s7, s21
	s_cselect_b32 s24, s6, s20
	v_add_u32_e32 v146, s50, v148
	s_cselect_b32 s23, s17, s48
	s_cselect_b32 s22, s16, s47
	s_add_i32 s51, 0, 0x14000
	ds_read_b128 v[142:145], v146
	ds_read_b128 v[152:155], v146 offset:1024
	ds_read_b128 v[156:159], v146 offset:2048
	ds_read_b128 v[160:163], v146 offset:3072
	v_add_u32_e32 v146, s51, v148
	ds_read_b128 v[164:167], v146
	ds_read_b128 v[168:171], v146 offset:1024
	ds_read_b128 v[172:175], v146 offset:2048
	ds_read_b128 v[180:183], v146 offset:3072
	v_lshl_add_u64 v[146:147], s[18:19], 0, v[138:139]
	s_add_i32 m0, s33, 0xc000
	ds_read_b128 v[186:189], v150
	ds_read_b128 v[190:193], v150 offset:1024
	ds_read_b128 v[194:197], v150 offset:2048
	ds_read_b128 v[198:201], v150 offset:3072
	ds_read_b128 v[202:205], v150 offset:4096
	ds_read_b128 v[206:209], v150 offset:5120
	ds_read_b128 v[210:213], v150 offset:6144
	ds_read_b128 v[214:217], v150 offset:7168
	global_load_lds_dwordx4 v[146:147], off
	v_lshl_add_u64 v[146:147], s[18:19], 0, v[140:141]
	s_add_i32 m0, s33, 0xe000
	s_nop 0
	global_load_lds_dwordx4 v[146:147], off
	s_waitcnt vmcnt(8)
	s_waitcnt lgkmcnt(0)
	s_setprio 1
	s_barrier
	v_mfma_f32_16x16x32_bf16 v[126:129], v[142:145], v[186:189], v[126:129]
	v_mfma_f32_16x16x32_bf16 v[122:125], v[156:159], v[186:189], v[122:125]
	v_mfma_f32_16x16x32_bf16 v[114:117], v[142:145], v[194:197], v[114:117]
	v_mfma_f32_16x16x32_bf16 v[106:109], v[156:159], v[194:197], v[106:109]
	v_mfma_f32_16x16x32_bf16 v[98:101], v[142:145], v[202:205], v[98:101]
	v_mfma_f32_16x16x32_bf16 v[90:93], v[156:159], v[202:205], v[90:93]
	v_mfma_f32_16x16x32_bf16 v[82:85], v[142:145], v[210:213], v[82:85]
	v_mfma_f32_16x16x32_bf16 v[74:77], v[156:159], v[210:213], v[74:77]
	v_mfma_f32_16x16x32_bf16 v[126:129], v[152:155], v[190:193], v[126:129]
	v_mfma_f32_16x16x32_bf16 v[122:125], v[160:163], v[190:193], v[122:125]
	v_mfma_f32_16x16x32_bf16 v[114:117], v[152:155], v[198:201], v[114:117]
	v_mfma_f32_16x16x32_bf16 v[106:109], v[160:163], v[198:201], v[106:109]
	v_mfma_f32_16x16x32_bf16 v[98:101], v[152:155], v[206:209], v[98:101]
	v_mfma_f32_16x16x32_bf16 v[90:93], v[160:163], v[206:209], v[90:93]
	v_mfma_f32_16x16x32_bf16 v[82:85], v[152:155], v[214:217], v[82:85]
	v_mfma_f32_16x16x32_bf16 v[74:77], v[160:163], v[214:217], v[74:77]
	s_setprio 0
	s_setprio 1
	v_mfma_f32_16x16x32_bf16 v[118:121], v[164:167], v[186:189], v[118:121]
	v_mfma_f32_16x16x32_bf16 v[110:113], v[172:175], v[186:189], v[110:113]
	v_mfma_f32_16x16x32_bf16 v[102:105], v[164:167], v[194:197], v[102:105]
	v_mfma_f32_16x16x32_bf16 v[94:97], v[172:175], v[194:197], v[94:97]
	v_mfma_f32_16x16x32_bf16 v[86:89], v[164:167], v[202:205], v[86:89]
	v_mfma_f32_16x16x32_bf16 v[78:81], v[172:175], v[202:205], v[78:81]
	v_mfma_f32_16x16x32_bf16 v[70:73], v[164:167], v[210:213], v[70:73]
	v_mfma_f32_16x16x32_bf16 v[66:69], v[172:175], v[210:213], v[66:69]
	v_mfma_f32_16x16x32_bf16 v[118:121], v[168:171], v[190:193], v[118:121]
	v_mfma_f32_16x16x32_bf16 v[110:113], v[180:183], v[190:193], v[110:113]
	v_mfma_f32_16x16x32_bf16 v[102:105], v[168:171], v[198:201], v[102:105]
	v_mfma_f32_16x16x32_bf16 v[94:97], v[180:183], v[198:201], v[94:97]
	v_mfma_f32_16x16x32_bf16 v[86:89], v[168:171], v[206:209], v[86:89]
	v_mfma_f32_16x16x32_bf16 v[78:81], v[180:183], v[206:209], v[78:81]
	v_mfma_f32_16x16x32_bf16 v[70:73], v[168:171], v[214:217], v[70:73]
	v_mfma_f32_16x16x32_bf16 v[66:69], v[180:183], v[214:217], v[66:69]
	s_barrier
	s_setprio 0
	s_add_i32 s18, s50, s27
	v_lshl_add_u64 v[146:147], s[22:23], 0, v[132:133]
	s_mov_b32 m0, s18
	ds_read_b128 v[186:189], v150 offset:16384
	ds_read_b128 v[190:193], v150 offset:17408
	ds_read_b128 v[194:197], v150 offset:18432
	ds_read_b128 v[198:201], v150 offset:19456
	ds_read_b128 v[202:205], v150 offset:20480
	ds_read_b128 v[206:209], v150 offset:21504
	ds_read_b128 v[210:213], v150 offset:22528
	ds_read_b128 v[214:217], v150 offset:23552
	global_load_lds_dwordx4 v[146:147], off
	s_add_i32 m0, s18, 0x2000
	s_add_u32 s18, s22, 0xb0000
	v_lshl_add_u64 v[176:177], s[22:23], 0, v[136:137]
	s_addc_u32 s19, s23, 0
	s_add_i32 s50, s51, s27
	global_load_lds_dwordx4 v[176:177], off
	v_lshl_add_u64 v[218:219], s[18:19], 0, v[132:133]
	s_mov_b32 m0, s50
	v_lshl_add_u64 v[220:221], s[24:25], 0, v[134:135]
	global_load_lds_dwordx4 v[218:219], off
	v_lshl_add_u64 v[218:219], s[18:19], 0, v[136:137]
	s_add_i32 m0, s50, 0x2000
	s_nop 0
	global_load_lds_dwordx4 v[218:219], off
	v_lshl_add_u64 v[218:219], s[24:25], 0, v[130:131]
	s_mov_b32 m0, s33
	s_nop 0
	global_load_lds_dwordx4 v[218:219], off
	s_mov_b32 m0, s36
	s_nop 0
	global_load_lds_dwordx4 v[220:221], off
	s_waitcnt vmcnt(8)
	s_waitcnt lgkmcnt(0)
	s_setprio 1
	s_barrier
; #define PG8_STAGE(bufoff, gbase, voff) do { _Pragma("unroll") for (int _i = 0; _i < 2; ++_i) \
;         __builtin_amdgcn_global_load_lds((const unsigned*)((const char*)(gbase) + (voff)[_i]), (PG8_LAS unsigned*)(lds + (bufoff) + ldsw + _i * 8192), 16, 0, 0); } while (0)
; #define PG8_LDA(dst, b, h) do { _Pragma("unroll") for (int m = 0; m < 4; ++m) _Pragma("unroll") for (int k = 0; k < 2; ++k) dst[m][k] = *(const PG8_LAS bf16x8*)(lds + PG8_SA(b, h) + aoff + m * 2048 + k * 1024); } while (0)
; #define PG8_LDB(dst, b, h) do { _Pragma("unroll") for (int n = 0; n < 2; ++n) _Pragma("unroll") for (int k = 0; k < 2; ++k) dst[n][k] = *(const PG8_LAS bf16x8*)(lds + PG8_SB(b, h) + boff + n * 2048 + k * 1024); } while (0)
; #define PG8_MMA(ai, bj, At, Bt) do { __builtin_amdgcn_s_setprio(1); _Pragma("unroll") for (int m = 0; m < 4; ++m) _Pragma("unroll") for (int n = 0; n < 2; ++n) _Pragma("unroll") for (int k = 0; k < 2; ++k) \
;         acc[ai][bj][m][n] = __builtin_amdgcn_mfma_f32_16x16x32_bf16(Bt[n][k], At[m][k], acc[ai][bj][m][n], 0, 0, 0); __builtin_amdgcn_s_setprio(0); } while (0)
; #define PG8_WAIT_V(n) asm volatile("s_waitcnt vmcnt(" #n ")" ::: "memory")
; #define PG8_WAIT_L(n) asm volatile("s_waitcnt lgkmcnt(" #n ")" ::: "memory")
; #define PG8_BAR __builtin_amdgcn_s_barrier()
; #define PG8_SCHED __builtin_amdgcn_sched_barrier(0)
; template <class Epi, class Sched, bool ALIGN_EPI = false, bool SP2 = false>
; __device__ __forceinline__ void gemm_phase(PG8_LAS unsigned char* lds, const Gemm g, const Sched& S, const Epi& E) {
;     ...
;             PG8_WAIT_V(8); PG8_WAIT_L(0); PG8_BAR; PG8_MMA(1, 0, At, B0); PG8_MMA(1, 1, At, B1); PG8_BAR; PG8_SCHED;
;             PG8_LDB(B0, 1, 0); PG8_LDB(B1, 1, 1); PG8_SCHED; PG8_LDA(At, 1, 0); PG8_STAGE(PG8_SA(0, 1), a2 + hstep, voffA);
;             PG8_WAIT_V(8); PG8_WAIT_L(0); PG8_BAR; PG8_MMA(0, 0, At, B0); PG8_MMA(0, 1, At, B1); PG8_BAR; PG8_SCHED;
;             PG8_LDA(At, 1, 1); PG8_STAGE(PG8_SB(1, 0), b3, voffB); PG8_STAGE(PG8_SB(1, 1), b3 + hstep, voffB); PG8_STAGE(PG8_SA(1, 0), a3, voffA);
;             PG8_WAIT_V(8); PG8_WAIT_L(0); PG8_BAR; PG8_MMA(1, 0, At, B0); PG8_MMA(1, 1, At, B1); PG8_BAR; PG8_SCHED;
	v_mfma_f32_16x16x32_bf16 v[62:65], v[142:145], v[186:189], v[62:65]
	v_mfma_f32_16x16x32_bf16 v[58:61], v[156:159], v[186:189], v[58:61]
	v_mfma_f32_16x16x32_bf16 v[50:53], v[142:145], v[194:197], v[50:53]
	v_mfma_f32_16x16x32_bf16 v[42:45], v[156:159], v[194:197], v[42:45]
	v_mfma_f32_16x16x32_bf16 v[34:37], v[142:145], v[202:205], v[34:37]
	v_mfma_f32_16x16x32_bf16 v[26:29], v[156:159], v[202:205], v[26:29]
	v_mfma_f32_16x16x32_bf16 v[18:21], v[142:145], v[210:213], v[18:21]
	v_mfma_f32_16x16x32_bf16 v[10:13], v[156:159], v[210:213], v[10:13]
	v_mfma_f32_16x16x32_bf16 v[62:65], v[152:155], v[190:193], v[62:65]
	v_mfma_f32_16x16x32_bf16 v[58:61], v[160:163], v[190:193], v[58:61]
	v_mfma_f32_16x16x32_bf16 v[50:53], v[152:155], v[198:201], v[50:53]
	v_mfma_f32_16x16x32_bf16 v[42:45], v[160:163], v[198:201], v[42:45]
	v_mfma_f32_16x16x32_bf16 v[34:37], v[152:155], v[206:209], v[34:37]
	v_mfma_f32_16x16x32_bf16 v[26:29], v[160:163], v[206:209], v[26:29]
	v_mfma_f32_16x16x32_bf16 v[18:21], v[152:155], v[214:217], v[18:21]
	v_mfma_f32_16x16x32_bf16 v[10:13], v[160:163], v[214:217], v[10:13]
	s_setprio 0
	s_setprio 1
	v_mfma_f32_16x16x32_bf16 v[54:57], v[164:167], v[186:189], v[54:57]
	v_mfma_f32_16x16x32_bf16 v[46:49], v[172:175], v[186:189], v[46:49]
	v_mfma_f32_16x16x32_bf16 v[38:41], v[164:167], v[194:197], v[38:41]
	v_mfma_f32_16x16x32_bf16 v[30:33], v[172:175], v[194:197], v[30:33]
	v_mfma_f32_16x16x32_bf16 v[22:25], v[164:167], v[202:205], v[22:25]
	v_mfma_f32_16x16x32_bf16 v[14:17], v[172:175], v[202:205], v[14:17]
	v_mfma_f32_16x16x32_bf16 v[6:9], v[164:167], v[210:213], v[6:9]
	v_mfma_f32_16x16x32_bf16 v[2:5], v[172:175], v[210:213], v[2:5]
	v_mfma_f32_16x16x32_bf16 v[54:57], v[168:171], v[190:193], v[54:57]
	v_mfma_f32_16x16x32_bf16 v[46:49], v[180:183], v[190:193], v[46:49]
	v_mfma_f32_16x16x32_bf16 v[38:41], v[168:171], v[198:201], v[38:41]
	v_mfma_f32_16x16x32_bf16 v[30:33], v[180:183], v[198:201], v[30:33]
	v_mfma_f32_16x16x32_bf16 v[22:25], v[168:171], v[206:209], v[22:25]
	v_mfma_f32_16x16x32_bf16 v[14:17], v[180:183], v[206:209], v[14:17]
	v_mfma_f32_16x16x32_bf16 v[6:9], v[168:171], v[214:217], v[6:9]
	v_mfma_f32_16x16x32_bf16 v[2:5], v[180:183], v[214:217], v[2:5]
	s_barrier
	s_setprio 0
	s_add_i32 s50, 0, 0x18000
	v_add_u32_e32 v151, s50, v148
	s_add_i32 s51, 0, 0x1c000
	ds_read_b128 v[142:145], v151
	ds_read_b128 v[152:155], v151 offset:1024
	ds_read_b128 v[156:159], v151 offset:2048
	ds_read_b128 v[160:163], v151 offset:3072
	v_add_u32_e32 v151, s51, v148
	ds_read_b128 v[164:167], v151
	ds_read_b128 v[168:171], v151 offset:1024
	ds_read_b128 v[172:175], v151 offset:2048
	ds_read_b128 v[180:183], v151 offset:3072
	s_add_u32 s18, s24, 0xb0000
	s_addc_u32 s19, s25, 0
	s_mov_b32 m0, s37
	v_lshl_add_u64 v[222:223], s[18:19], 0, v[130:131]
	ds_read_b128 v[186:189], v150 offset:32768
	ds_read_b128 v[190:193], v150 offset:33792
	ds_read_b128 v[194:197], v150 offset:34816
	ds_read_b128 v[198:201], v150 offset:35840
	ds_read_b128 v[202:205], v150 offset:36864
	ds_read_b128 v[206:209], v150 offset:37888
	ds_read_b128 v[210:213], v150 offset:38912
	ds_read_b128 v[214:217], v150 offset:39936
	global_load_lds_dwordx4 v[222:223], off
	v_lshl_add_u64 v[222:223], s[18:19], 0, v[134:135]
	s_mov_b32 m0, s38
	s_nop 0
	global_load_lds_dwordx4 v[222:223], off
	s_waitcnt vmcnt(8)
	s_waitcnt lgkmcnt(0)
	s_setprio 1
	s_barrier
	v_mfma_f32_16x16x32_bf16 v[126:129], v[142:145], v[186:189], v[126:129]
	v_mfma_f32_16x16x32_bf16 v[122:125], v[156:159], v[186:189], v[122:125]
	v_mfma_f32_16x16x32_bf16 v[114:117], v[142:145], v[194:197], v[114:117]
	v_mfma_f32_16x16x32_bf16 v[106:109], v[156:159], v[194:197], v[106:109]
	v_mfma_f32_16x16x32_bf16 v[98:101], v[142:145], v[202:205], v[98:101]
	v_mfma_f32_16x16x32_bf16 v[90:93], v[156:159], v[202:205], v[90:93]
	v_mfma_f32_16x16x32_bf16 v[82:85], v[142:145], v[210:213], v[82:85]
	v_mfma_f32_16x16x32_bf16 v[74:77], v[156:159], v[210:213], v[74:77]
	v_mfma_f32_16x16x32_bf16 v[126:129], v[152:155], v[190:193], v[126:129]
	v_mfma_f32_16x16x32_bf16 v[122:125], v[160:163], v[190:193], v[122:125]
	v_mfma_f32_16x16x32_bf16 v[114:117], v[152:155], v[198:201], v[114:117]
	v_mfma_f32_16x16x32_bf16 v[106:109], v[160:163], v[198:201], v[106:109]
	v_mfma_f32_16x16x32_bf16 v[98:101], v[152:155], v[206:209], v[98:101]
	v_mfma_f32_16x16x32_bf16 v[90:93], v[160:163], v[206:209], v[90:93]
	v_mfma_f32_16x16x32_bf16 v[82:85], v[152:155], v[214:217], v[82:85]
	v_mfma_f32_16x16x32_bf16 v[74:77], v[160:163], v[214:217], v[74:77]
	s_setprio 0
	s_setprio 1
	v_mfma_f32_16x16x32_bf16 v[118:121], v[164:167], v[186:189], v[118:121]
	v_mfma_f32_16x16x32_bf16 v[110:113], v[172:175], v[186:189], v[110:113]
	v_mfma_f32_16x16x32_bf16 v[102:105], v[164:167], v[194:197], v[102:105]
	v_mfma_f32_16x16x32_bf16 v[94:97], v[172:175], v[194:197], v[94:97]
	v_mfma_f32_16x16x32_bf16 v[86:89], v[164:167], v[202:205], v[86:89]
	v_mfma_f32_16x16x32_bf16 v[78:81], v[172:175], v[202:205], v[78:81]
	v_mfma_f32_16x16x32_bf16 v[70:73], v[164:167], v[210:213], v[70:73]
	v_mfma_f32_16x16x32_bf16 v[66:69], v[172:175], v[210:213], v[66:69]
	v_mfma_f32_16x16x32_bf16 v[118:121], v[168:171], v[190:193], v[118:121]
	v_mfma_f32_16x16x32_bf16 v[110:113], v[180:183], v[190:193], v[110:113]
	v_mfma_f32_16x16x32_bf16 v[102:105], v[168:171], v[198:201], v[102:105]
	v_mfma_f32_16x16x32_bf16 v[94:97], v[180:183], v[198:201], v[94:97]
	v_mfma_f32_16x16x32_bf16 v[86:89], v[168:171], v[206:209], v[86:89]
	v_mfma_f32_16x16x32_bf16 v[78:81], v[180:183], v[206:209], v[78:81]
	v_mfma_f32_16x16x32_bf16 v[70:73], v[168:171], v[214:217], v[70:73]
	v_mfma_f32_16x16x32_bf16 v[66:69], v[180:183], v[214:217], v[66:69]
	s_barrier
; #define PG8_STAGE(bufoff, gbase, voff) do { _Pragma("unroll") for (int _i = 0; _i < 2; ++_i) \
;         __builtin_amdgcn_global_load_lds((const unsigned*)((const char*)(gbase) + (voff)[_i]), (PG8_LAS unsigned*)(lds + (bufoff) + ldsw + _i * 8192), 16, 0, 0); } while (0)
; #define PG8_LDA(dst, b, h) do { _Pragma("unroll") for (int m = 0; m < 4; ++m) _Pragma("unroll") for (int k = 0; k < 2; ++k) dst[m][k] = *(const PG8_LAS bf16x8*)(lds + PG8_SA(b, h) + aoff + m * 2048 + k * 1024); } while (0)
; #define PG8_MMA(ai, bj, At, Bt) do { __builtin_amdgcn_s_setprio(1); _Pragma("unroll") for (int m = 0; m < 4; ++m) _Pragma("unroll") for (int n = 0; n < 2; ++n) _Pragma("unroll") for (int k = 0; k < 2; ++k) \
;         acc[ai][bj][m][n] = __builtin_amdgcn_mfma_f32_16x16x32_bf16(Bt[n][k], At[m][k], acc[ai][bj][m][n], 0, 0, 0); __builtin_amdgcn_s_setprio(0); } while (0)
; #define PG8_WAIT_V(n) asm volatile("s_waitcnt vmcnt(" #n ")" ::: "memory")
; #define PG8_WAIT_L(n) asm volatile("s_waitcnt lgkmcnt(" #n ")" ::: "memory")
; #define PG8_BAR __builtin_amdgcn_s_barrier()
; #define PG8_SCHED __builtin_amdgcn_sched_barrier(0)
; template <class Epi, class Sched, bool ALIGN_EPI = false, bool SP2 = false>
; __device__ __forceinline__ void gemm_phase(PG8_LAS unsigned char* lds, const Gemm g, const Sched& S, const Epi& E) {
;     ...
;             PG8_WAIT_V(8); PG8_WAIT_L(0); PG8_BAR; PG8_MMA(0, 0, At, B0); PG8_MMA(0, 1, At, B1); PG8_BAR; PG8_SCHED;
;             PG8_LDA(At, 1, 1); PG8_STAGE(PG8_SB(1, 0), b3, voffB); PG8_STAGE(PG8_SB(1, 1), b3 + hstep, voffB); PG8_STAGE(PG8_SA(1, 0), a3, voffA);
;             PG8_WAIT_V(8); PG8_WAIT_L(0); PG8_BAR; PG8_MMA(1, 0, At, B0); PG8_MMA(1, 1, At, B1); PG8_BAR; PG8_SCHED;
	s_setprio 0
	s_add_i32 s18, s50, s27
	v_lshl_add_u64 v[146:147], v[146:147], 0, s[80:81]
	s_mov_b32 m0, s18
	ds_read_b128 v[186:189], v150 offset:49152
	ds_read_b128 v[190:193], v150 offset:50176
	ds_read_b128 v[194:197], v150 offset:51200
	ds_read_b128 v[198:201], v150 offset:52224
	ds_read_b128 v[202:205], v150 offset:53248
	ds_read_b128 v[206:209], v150 offset:54272
	ds_read_b128 v[210:213], v150 offset:55296
	ds_read_b128 v[214:217], v150 offset:56320
	global_load_lds_dwordx4 v[146:147], off
	s_add_i32 m0, s18, 0x2000
	s_add_u32 s18, s22, 0xb0080
	v_lshl_add_u64 v[146:147], v[176:177], 0, s[80:81]
	s_addc_u32 s19, s23, 0
	s_add_i32 s22, s51, s27
	global_load_lds_dwordx4 v[146:147], off
	v_lshl_add_u64 v[146:147], s[18:19], 0, v[132:133]
	s_mov_b32 m0, s22
	s_nop 0
	global_load_lds_dwordx4 v[146:147], off
	v_lshl_add_u64 v[146:147], s[18:19], 0, v[136:137]
	s_add_i32 m0, s22, 0x2000
	s_nop 0
	global_load_lds_dwordx4 v[146:147], off
	v_lshl_add_u64 v[146:147], v[218:219], 0, s[80:81]
	s_mov_b32 m0, s39
	s_nop 0
	global_load_lds_dwordx4 v[146:147], off
	v_lshl_add_u64 v[146:147], v[220:221], 0, s[80:81]
	s_mov_b32 m0, s40
	s_nop 0
	global_load_lds_dwordx4 v[146:147], off
	s_waitcnt vmcnt(8)
	s_waitcnt lgkmcnt(0)
	s_setprio 1
	s_barrier
	v_mfma_f32_16x16x32_bf16 v[62:65], v[142:145], v[186:189], v[62:65]
	v_mfma_f32_16x16x32_bf16 v[58:61], v[156:159], v[186:189], v[58:61]
	v_mfma_f32_16x16x32_bf16 v[50:53], v[142:145], v[194:197], v[50:53]
	v_mfma_f32_16x16x32_bf16 v[42:45], v[156:159], v[194:197], v[42:45]
	v_mfma_f32_16x16x32_bf16 v[34:37], v[142:145], v[202:205], v[34:37]
	v_mfma_f32_16x16x32_bf16 v[26:29], v[156:159], v[202:205], v[26:29]
	v_mfma_f32_16x16x32_bf16 v[18:21], v[142:145], v[210:213], v[18:21]
	v_mfma_f32_16x16x32_bf16 v[10:13], v[156:159], v[210:213], v[10:13]
	v_mfma_f32_16x16x32_bf16 v[62:65], v[152:155], v[190:193], v[62:65]
	v_mfma_f32_16x16x32_bf16 v[58:61], v[160:163], v[190:193], v[58:61]
	v_mfma_f32_16x16x32_bf16 v[50:53], v[152:155], v[198:201], v[50:53]
	v_mfma_f32_16x16x32_bf16 v[42:45], v[160:163], v[198:201], v[42:45]
	v_mfma_f32_16x16x32_bf16 v[34:37], v[152:155], v[206:209], v[34:37]
	v_mfma_f32_16x16x32_bf16 v[26:29], v[160:163], v[206:209], v[26:29]
	v_mfma_f32_16x16x32_bf16 v[18:21], v[152:155], v[214:217], v[18:21]
	v_mfma_f32_16x16x32_bf16 v[10:13], v[160:163], v[214:217], v[10:13]
	s_setprio 0
	s_setprio 1
	v_mfma_f32_16x16x32_bf16 v[54:57], v[164:167], v[186:189], v[54:57]
	v_mfma_f32_16x16x32_bf16 v[46:49], v[172:175], v[186:189], v[46:49]
	v_mfma_f32_16x16x32_bf16 v[38:41], v[164:167], v[194:197], v[38:41]
	v_mfma_f32_16x16x32_bf16 v[30:33], v[172:175], v[194:197], v[30:33]
	v_mfma_f32_16x16x32_bf16 v[22:25], v[164:167], v[202:205], v[22:25]
	v_mfma_f32_16x16x32_bf16 v[14:17], v[172:175], v[202:205], v[14:17]
	v_mfma_f32_16x16x32_bf16 v[6:9], v[164:167], v[210:213], v[6:9]
	v_mfma_f32_16x16x32_bf16 v[2:5], v[172:175], v[210:213], v[2:5]
	v_mfma_f32_16x16x32_bf16 v[54:57], v[168:171], v[190:193], v[54:57]
	v_mfma_f32_16x16x32_bf16 v[46:49], v[180:183], v[190:193], v[46:49]
	v_mfma_f32_16x16x32_bf16 v[38:41], v[168:171], v[198:201], v[38:41]
	v_mfma_f32_16x16x32_bf16 v[30:33], v[180:183], v[198:201], v[30:33]
	v_mfma_f32_16x16x32_bf16 v[22:25], v[168:171], v[206:209], v[22:25]
	v_mfma_f32_16x16x32_bf16 v[14:17], v[180:183], v[206:209], v[14:17]
	v_mfma_f32_16x16x32_bf16 v[6:9], v[168:171], v[214:217], v[6:9]
	v_mfma_f32_16x16x32_bf16 v[2:5], v[180:183], v[214:217], v[2:5]
	s_barrier
	s_setprio 0
	s_add_i32 s49, s49, 2
	s_add_u32 s47, s47, 0x100
	s_addc_u32 s48, s48, 0
	s_cmp_gt_u32 s49, 41
	s_mov_b64 s[18:19], s[20:21]
	s_cbranch_scc0 .LBB0_1360
	s_and_b64 vcc, exec, s[14:15]
	s_cbranch_vccz .LBB0_1363
	s_barrier
